# v39 + the L1 invalidate at the end of every GEMM phase body is issued before that body's own store drain (overlapped), flag keeps the barrier entry from repeating it
# speedup vs baseline: 1.0151x; 1.0151x over previous
; #define LAS __attribute__((address_space(3)))
; __global__ __launch_bounds__(512) void fwd_megakernel(P p_arg) {
;     P p = p_arg;
;     extern __shared__ __attribute__((aligned(16))) unsigned char shm[];
;     LAS unsigned char* lds = (LAS unsigned char*)shm;
;     Ctx c; c.tid = threadIdx.x; c.wv = threadIdx.x >> 6; c.lane = threadIdx.x & 63; c.G = gridDim.x; c.bid = blockIdx.x; c.lds = lds; c.seg = p.ws + OFF_SEG;
;     volatile LAS unsigned* st = (volatile LAS unsigned*)(lds + LDS_BYTES - 16);
;     if (c.tid == 0) { st[0] = 0u; st[1] = 0u; }
;     __syncthreads();
;     const XcdBarrier xb = xcd_barrier_post((unsigned*)(p.ws + OFF_BAR), st);
_Z14fwd_megakernel1P:
	s_mov_b32 s100, 0
	s_mov_b64 s[92:93], s[0:1]
	s_load_dwordx2 s[94:95], s[0:1], 0x100
	s_load_dword s8, s[0:1], 0x108
	s_add_u32 s0, s92, 0x108
	s_addc_u32 s1, s93, 0
	v_mov_b32_e32 v217, v0
	v_writelane_b32 v255, s0, 0
	s_mov_b32 s90, s2
	v_cmp_eq_u32_e32 vcc, 0, v217
	v_writelane_b32 v255, s1, 1
	s_and_saveexec_b64 s[2:3], vcc
	s_cbranch_execz .LBB0_2
	s_add_i32 s0, 0, 0x257f0
	v_mov_b32_e32 v0, 0
	v_mov_b32_e32 v1, s0
	s_add_i32 s0, 0, 0x257f4
	ds_write_b32 v1, v0
	v_mov_b32_e32 v1, s0
	ds_write_b32 v1, v0

; __device__ __forceinline__ void xcd_barrier(const XcdBarrier& b) {
;     asm volatile("s_waitcnt vmcnt(0)" ::: "memory");
;     __syncthreads();
;     int tid0 = threadIdx.x; asm volatile("" : "+v"(tid0));
;     if (tid0 == 0) {
;         unsigned* bar = b.bar;
;         __builtin_amdgcn_s_waitcnt(0);
;         unsigned nloc = b.st[0], nx = b.st[1];
;         if (nloc == 0u) { xcd_barrier_complete(bar, b.x, nloc, nx); b.st[0] = nloc; b.st[1] = nx; }
.LBB0_103:
	s_getreg_b32 s0, hwreg(HW_REG_XCC_ID, 0, 4)
	s_cselect_b32 s99, 1, 0
	s_cmp_eq_u32 s100, 1
	s_cbranch_scc1 .Lxb_noinv_1
	v_readfirstlane_b32 s98, v217
	s_cmp_lt_u32 s98, 0x1c0
	s_cbranch_scc1 .Lxb_noinv_1
	buffer_inv sc1
.Lxb_noinv_1:
	s_mov_b32 s100, 0
	s_cmp_lg_u32 s99, 0
	s_waitcnt vmcnt(0)
	v_mov_b32_e32 v0, v217
	s_barrier
	s_nop 0
	v_cmp_eq_u32_e32 vcc, 0, v0
	s_and_saveexec_b64 s[2:3], vcc
	s_xor_b64 s[2:3], exec, s[2:3]
	s_cbranch_execz .LBB0_156
	s_lshl_b64 s[4:5], s[4:5], 2
	s_add_u32 s4, s96, s4
	s_addc_u32 s5, s97, s5
	s_add_i32 s1, 0, 0x257f0
	v_mov_b32_e32 v0, s1
	s_waitcnt vmcnt(0) expcnt(0) lgkmcnt(0)
	ds_read_b32 v3, v0
	s_add_i32 s1, 0, 0x257f4
	v_mov_b32_e32 v0, s1
	ds_read_b32 v1, v0
	s_and_b32 s0, s0, 15
	s_waitcnt lgkmcnt(1)
	v_cmp_ne_u32_e32 vcc, 0, v3
	s_cbranch_vccnz .LBB0_119
	v_readlane_b32 s6, v255, 0
	v_readlane_b32 s7, v255, 1
	s_load_dwordx2 s[10:11], s[6:7], 0x4
	s_add_u32 s6, s4, 0x1000
	s_addc_u32 s7, s5, 0
	s_add_u32 s8, s4, 0x1100
	s_addc_u32 s9, s5, 0
	s_waitcnt lgkmcnt(0)
	s_mul_i32 s1, s10, s34
	s_add_u32 s10, s4, 0x1200
	s_mul_i32 s1, s1, s11
	s_addc_u32 s11, s5, 0
	s_add_u32 s12, s4, 0x1300
	s_addc_u32 s13, s5, 0
	s_mov_b32 s18, 1
	v_mov_b32_e32 v18, 0
	s_branch .LBB0_107

; #define PG8_STAGE(bufoff, gbase, voff) do { _Pragma("unroll") for (int _i = 0; _i < 2; ++_i) \
;         __builtin_amdgcn_global_load_lds((const unsigned*)((const char*)(gbase) + (voff)[_i]), (LAS unsigned*)(lds + (bufoff) + ldsw + _i * 8192), 16, 0, 0); } while (0)
; #define PG8_LDA(dst, b, h) do { _Pragma("unroll") for (int m = 0; m < 4; ++m) _Pragma("unroll") for (int k = 0; k < 2; ++k) dst[m][k] = *(const LAS bf16x8*)(lds + PG8_SA(b, h) + aoff + m * 2048 + k * 1024); } while (0)
; #define PG8_LDB(dst, b, h) do { _Pragma("unroll") for (int n = 0; n < 2; ++n) _Pragma("unroll") for (int k = 0; k < 2; ++k) dst[n][k] = *(const LAS bf16x8*)(lds + PG8_SB(b, h) + boff + n * 2048 + k * 1024); } while (0)
; #define PG8_MMA(ai, bj, At, Bt) do { __builtin_amdgcn_s_setprio(1); _Pragma("unroll") for (int m = 0; m < 4; ++m) _Pragma("unroll") for (int n = 0; n < 2; ++n) _Pragma("unroll") for (int k = 0; k < 2; ++k) \
;         acc[ai][bj][m][n] = __builtin_amdgcn_mfma_f32_16x16x32_bf16(Bt[n][k], At[m][k], acc[ai][bj][m][n], 0, 0, 0); __builtin_amdgcn_s_setprio(0); } while (0)
; #define PG8_WAIT_L(n) asm volatile("s_waitcnt lgkmcnt(" #n ")" ::: "memory")
; #define PG8_BAR __builtin_amdgcn_s_barrier()
; #define PG8_SCHED __builtin_amdgcn_sched_barrier(0)
; template <class Epi, class Sched>
; __device__ __forceinline__ void gemm_phase(LAS unsigned char* lds, const int tid, const int ldk, const int Kloop, const Sched& S, const Epi& E) {
;     ...
;         for (int t = 0; t < nt; t += 2) {
;             const bool last = (t == nt - 2);
;             const char* a1 = cA + (size_t)(t + 1) * kstep;
;             const char* a2 = last ? nA : cA + (size_t)(t + 2) * kstep; const char* b2 = last ? nB : cB + (size_t)(t + 2) * kstep;
;             const char* a3 = a2 + kstep; const char* b3 = b2 + kstep;
;             PG8_LDB(B0, 0, 0); PG8_SCHED; PG8_LDA(At, 0, 0); PG8_STAGE(PG8_SA(1, 1), a1 + hstep, voffA);
;             PG8_WAIT_L(8); PG8_BAR; PG8_WAIT_L(0); PG8_MMA(0, 0, At, B0); PG8_BAR; PG8_SCHED;
;             PG8_LDB(B1, 0, 1); PG8_STAGE(PG8_SB(0, 0), b2, voffB);
;             PG8_BAR; PG8_WAIT_L(0); PG8_MMA(0, 1, At, B1); PG8_BAR;
;             PG8_LDA(At, 0, 1); PG8_STAGE(PG8_SA(0, 0), a2, voffA);
;             PG8_BAR; PG8_WAIT_L(0); PG8_MMA(1, 0, At, B0); PG8_BAR; PG8_SCHED;
.LBB0_181:
	s_add_u32 s14, s12, 0xfffc0080
	s_addc_u32 s15, s13, -1
	s_add_i32 s75, 0, 0x10000
	v_add_u32_e32 v158, s75, v144
	ds_read_b128 v[146:149], v158
	ds_read_b128 v[150:153], v158 offset:1024
	ds_read_b128 v[154:157], v158 offset:2048
	ds_read_b128 v[158:161], v158 offset:3072
	s_cmp_eq_u32 s74, 12
	s_cselect_b32 s17, s7, s15
	s_cselect_b32 s16, s6, s14
	s_cselect_b32 s15, s9, s73
	s_cselect_b32 s14, s8, s72
	v_lshl_add_u64 v[172:173], s[12:13], 0, v[138:139]
	s_add_i32 m0, s31, 0xc000
	ds_read_b128 v[162:165], v145
	ds_read_b128 v[166:169], v145 offset:1024
	ds_read_b128 v[176:179], v145 offset:2048
	ds_read_b128 v[180:183], v145 offset:3072
	ds_read_b128 v[184:187], v145 offset:4096
	ds_read_b128 v[188:191], v145 offset:5120
	ds_read_b128 v[192:195], v145 offset:6144
	ds_read_b128 v[196:199], v145 offset:7168
	global_load_lds_dwordx4 v[172:173], off
	v_lshl_add_u64 v[172:173], s[12:13], 0, v[140:141]
	s_add_i32 m0, s31, 0xe000
	s_nop 0
	global_load_lds_dwordx4 v[172:173], off
	s_waitcnt lgkmcnt(8)
	s_barrier
	s_waitcnt lgkmcnt(0)
	s_setprio 1
	s_waitcnt lgkmcnt(0)
	v_mfma_f32_16x16x32_bf16 v[130:133], v[146:149], v[162:165], v[130:133]
	v_mfma_f32_16x16x32_bf16 v[126:129], v[154:157], v[162:165], v[126:129]
	v_mfma_f32_16x16x32_bf16 v[122:125], v[146:149], v[176:179], v[122:125]
	v_mfma_f32_16x16x32_bf16 v[118:121], v[154:157], v[176:179], v[118:121]
	v_mfma_f32_16x16x32_bf16 v[106:109], v[146:149], v[184:187], v[106:109]
	v_mfma_f32_16x16x32_bf16 v[102:105], v[154:157], v[184:187], v[102:105]
	v_mfma_f32_16x16x32_bf16 v[90:93], v[146:149], v[192:195], v[90:93]
	v_mfma_f32_16x16x32_bf16 v[86:89], v[154:157], v[192:195], v[86:89]
	v_mfma_f32_16x16x32_bf16 v[130:133], v[150:153], v[166:169], v[130:133]
	v_mfma_f32_16x16x32_bf16 v[126:129], v[158:161], v[166:169], v[126:129]
	v_mfma_f32_16x16x32_bf16 v[122:125], v[150:153], v[180:183], v[122:125]
	v_mfma_f32_16x16x32_bf16 v[118:121], v[158:161], v[180:183], v[118:121]
	v_mfma_f32_16x16x32_bf16 v[106:109], v[150:153], v[188:191], v[106:109]
	v_mfma_f32_16x16x32_bf16 v[102:105], v[158:161], v[188:191], v[102:105]
	v_mfma_f32_16x16x32_bf16 v[90:93], v[150:153], v[196:199], v[90:93]
	v_mfma_f32_16x16x32_bf16 v[86:89], v[158:161], v[196:199], v[86:89]
	s_setprio 0
	s_barrier
	s_add_i32 s78, 0, 0x14000
	s_add_i32 s75, s75, s30
	v_add_u32_e32 v170, s78, v144
	v_lshl_add_u64 v[172:173], s[14:15], 0, v[4:5]
	s_mov_b32 m0, s75
	ds_read_b128 v[200:203], v170
	ds_read_b128 v[204:207], v170 offset:1024
	ds_read_b128 v[222:225], v170 offset:2048
	ds_read_b128 v[226:229], v170 offset:3072
	global_load_lds_dwordx4 v[172:173], off
	v_lshl_add_u64 v[208:209], s[14:15], 0, v[136:137]
	s_add_i32 m0, s75, 0x2000
	s_nop 0
	global_load_lds_dwordx4 v[208:209], off
	s_barrier
	s_waitcnt lgkmcnt(0)
	s_setprio 1
	s_waitcnt lgkmcnt(0)
	v_mfma_f32_16x16x32_bf16 v[114:117], v[200:203], v[162:165], v[114:117]
	v_mfma_f32_16x16x32_bf16 v[110:113], v[222:225], v[162:165], v[110:113]
	v_mfma_f32_16x16x32_bf16 v[98:101], v[200:203], v[176:179], v[98:101]
	v_mfma_f32_16x16x32_bf16 v[94:97], v[222:225], v[176:179], v[94:97]
	v_mfma_f32_16x16x32_bf16 v[82:85], v[200:203], v[184:187], v[82:85]
	v_mfma_f32_16x16x32_bf16 v[78:81], v[222:225], v[184:187], v[78:81]
	v_mfma_f32_16x16x32_bf16 v[74:77], v[200:203], v[192:195], v[74:77]
	v_mfma_f32_16x16x32_bf16 v[70:73], v[222:225], v[192:195], v[70:73]
	v_mfma_f32_16x16x32_bf16 v[114:117], v[204:207], v[166:169], v[114:117]
	v_mfma_f32_16x16x32_bf16 v[110:113], v[226:229], v[166:169], v[110:113]
	v_mfma_f32_16x16x32_bf16 v[98:101], v[204:207], v[180:183], v[98:101]
	v_mfma_f32_16x16x32_bf16 v[94:97], v[226:229], v[180:183], v[94:97]
	v_mfma_f32_16x16x32_bf16 v[82:85], v[204:207], v[188:191], v[82:85]
	v_mfma_f32_16x16x32_bf16 v[78:81], v[226:229], v[188:191], v[78:81]
	v_mfma_f32_16x16x32_bf16 v[74:77], v[204:207], v[196:199], v[74:77]
	v_mfma_f32_16x16x32_bf16 v[70:73], v[226:229], v[196:199], v[70:73]
	s_setprio 0
	s_mov_b32 m0, s31
	v_lshl_add_u64 v[210:211], s[16:17], 0, v[2:3]
	s_barrier
	ds_read_b128 v[162:165], v145 offset:16384
	ds_read_b128 v[166:169], v145 offset:17408
	ds_read_b128 v[176:179], v145 offset:18432
	ds_read_b128 v[180:183], v145 offset:19456
	ds_read_b128 v[184:187], v145 offset:20480
	ds_read_b128 v[188:191], v145 offset:21504
	ds_read_b128 v[192:195], v145 offset:22528
	ds_read_b128 v[196:199], v145 offset:23552
	global_load_lds_dwordx4 v[210:211], off
	v_lshl_add_u64 v[218:219], s[16:17], 0, v[134:135]
	s_mov_b32 m0, s34
	s_nop 0
	global_load_lds_dwordx4 v[218:219], off
	s_barrier
	s_waitcnt lgkmcnt(0)
	s_setprio 1
	s_waitcnt lgkmcnt(0)
	v_mfma_f32_16x16x32_bf16 v[66:69], v[146:149], v[162:165], v[66:69]
	v_mfma_f32_16x16x32_bf16 v[62:65], v[154:157], v[162:165], v[62:65]
	v_mfma_f32_16x16x32_bf16 v[58:61], v[146:149], v[176:179], v[58:61]
	v_mfma_f32_16x16x32_bf16 v[54:57], v[154:157], v[176:179], v[54:57]
	v_mfma_f32_16x16x32_bf16 v[42:45], v[146:149], v[184:187], v[42:45]
	v_mfma_f32_16x16x32_bf16 v[38:41], v[154:157], v[184:187], v[38:41]
	v_mfma_f32_16x16x32_bf16 v[26:29], v[146:149], v[192:195], v[26:29]
	v_mfma_f32_16x16x32_bf16 v[22:25], v[154:157], v[192:195], v[22:25]
	v_mfma_f32_16x16x32_bf16 v[66:69], v[150:153], v[166:169], v[66:69]
	v_mfma_f32_16x16x32_bf16 v[62:65], v[158:161], v[166:169], v[62:65]
	v_mfma_f32_16x16x32_bf16 v[58:61], v[150:153], v[180:183], v[58:61]
	v_mfma_f32_16x16x32_bf16 v[54:57], v[158:161], v[180:183], v[54:57]
	v_mfma_f32_16x16x32_bf16 v[42:45], v[150:153], v[188:191], v[42:45]
	v_mfma_f32_16x16x32_bf16 v[38:41], v[158:161], v[188:191], v[38:41]
	v_mfma_f32_16x16x32_bf16 v[26:29], v[150:153], v[196:199], v[26:29]
	v_mfma_f32_16x16x32_bf16 v[22:25], v[158:161], v[196:199], v[22:25]
	s_setprio 0
	s_barrier
; #define PG8_STAGE(bufoff, gbase, voff) do { _Pragma("unroll") for (int _i = 0; _i < 2; ++_i) \
;         __builtin_amdgcn_global_load_lds((const unsigned*)((const char*)(gbase) + (voff)[_i]), (LAS unsigned*)(lds + (bufoff) + ldsw + _i * 8192), 16, 0, 0); } while (0)
; #define PG8_LDA(dst, b, h) do { _Pragma("unroll") for (int m = 0; m < 4; ++m) _Pragma("unroll") for (int k = 0; k < 2; ++k) dst[m][k] = *(const LAS bf16x8*)(lds + PG8_SA(b, h) + aoff + m * 2048 + k * 1024); } while (0)
; #define PG8_LDB(dst, b, h) do { _Pragma("unroll") for (int n = 0; n < 2; ++n) _Pragma("unroll") for (int k = 0; k < 2; ++k) dst[n][k] = *(const LAS bf16x8*)(lds + PG8_SB(b, h) + boff + n * 2048 + k * 1024); } while (0)
; #define PG8_MMA(ai, bj, At, Bt) do { __builtin_amdgcn_s_setprio(1); _Pragma("unroll") for (int m = 0; m < 4; ++m) _Pragma("unroll") for (int n = 0; n < 2; ++n) _Pragma("unroll") for (int k = 0; k < 2; ++k) \
;         acc[ai][bj][m][n] = __builtin_amdgcn_mfma_f32_16x16x32_bf16(Bt[n][k], At[m][k], acc[ai][bj][m][n], 0, 0, 0); __builtin_amdgcn_s_setprio(0); } while (0)
; #define PG8_WAIT_V(n) asm volatile("s_waitcnt vmcnt(" #n ")" ::: "memory")
; #define PG8_WAIT_L(n) asm volatile("s_waitcnt lgkmcnt(" #n ")" ::: "memory")
; #define PG8_BAR __builtin_amdgcn_s_barrier()
; #define PG8_SCHED __builtin_amdgcn_sched_barrier(0)
; template <class Epi, class Sched>
; __device__ __forceinline__ void gemm_phase(LAS unsigned char* lds, const int tid, const int ldk, const int Kloop, const Sched& S, const Epi& E) {
;     ...
;             PG8_STAGE(PG8_SB(0, 1), b2 + hstep, voffB);
;             PG8_WAIT_V(6); PG8_BAR; PG8_MMA(1, 1, At, B1); PG8_BAR;
;             PG8_LDB(B0, 1, 0); PG8_SCHED; PG8_LDA(At, 1, 0); PG8_STAGE(PG8_SA(0, 1), a2 + hstep, voffA);
;             PG8_WAIT_L(8); PG8_BAR; PG8_WAIT_L(0); PG8_MMA(0, 0, At, B0); PG8_BAR; PG8_SCHED;
;             PG8_LDB(B1, 1, 1); PG8_STAGE(PG8_SB(1, 0), b3, voffB);
;             PG8_BAR; PG8_WAIT_L(0); PG8_MMA(0, 1, At, B1); PG8_BAR;
;             PG8_LDA(At, 1, 1); PG8_STAGE(PG8_SA(1, 0), a3, voffA);
;             PG8_BAR; PG8_WAIT_L(0); PG8_MMA(1, 0, At, B0); PG8_BAR; PG8_SCHED;
	s_add_u32 s76, s14, 0x40000
	s_addc_u32 s77, s15, 0
	s_add_i32 s75, s78, s30
	v_lshl_add_u64 v[146:147], s[76:77], 0, v[4:5]
	s_mov_b32 m0, s75
	s_nop 0
	global_load_lds_dwordx4 v[146:147], off
	v_lshl_add_u64 v[146:147], s[76:77], 0, v[136:137]
	s_add_i32 m0, s75, 0x2000
	s_nop 0
	global_load_lds_dwordx4 v[146:147], off
	s_waitcnt vmcnt(6)
	s_barrier
	s_setprio 1
	v_mfma_f32_16x16x32_bf16 v[50:53], v[200:203], v[162:165], v[50:53]
	v_mfma_f32_16x16x32_bf16 v[46:49], v[222:225], v[162:165], v[46:49]
	v_mfma_f32_16x16x32_bf16 v[34:37], v[200:203], v[176:179], v[34:37]
	v_mfma_f32_16x16x32_bf16 v[30:33], v[222:225], v[176:179], v[30:33]
	v_mfma_f32_16x16x32_bf16 v[18:21], v[200:203], v[184:187], v[18:21]
	v_mfma_f32_16x16x32_bf16 v[14:17], v[222:225], v[184:187], v[14:17]
	v_mfma_f32_16x16x32_bf16 v[10:13], v[200:203], v[192:195], v[10:13]
	v_mfma_f32_16x16x32_bf16 v[6:9], v[222:225], v[192:195], v[6:9]
	v_mfma_f32_16x16x32_bf16 v[50:53], v[204:207], v[166:169], v[50:53]
	v_mfma_f32_16x16x32_bf16 v[46:49], v[226:229], v[166:169], v[46:49]
	v_mfma_f32_16x16x32_bf16 v[34:37], v[204:207], v[180:183], v[34:37]
	v_mfma_f32_16x16x32_bf16 v[30:33], v[226:229], v[180:183], v[30:33]
	v_mfma_f32_16x16x32_bf16 v[18:21], v[204:207], v[188:191], v[18:21]
	v_mfma_f32_16x16x32_bf16 v[14:17], v[226:229], v[188:191], v[14:17]
	v_mfma_f32_16x16x32_bf16 v[10:13], v[204:207], v[196:199], v[10:13]
	v_mfma_f32_16x16x32_bf16 v[6:9], v[226:229], v[196:199], v[6:9]
	s_setprio 0
	s_add_i32 s75, 0, 0x18000
	v_add_u32_e32 v158, s75, v144
	s_barrier
	ds_read_b128 v[146:149], v158
	ds_read_b128 v[150:153], v158 offset:1024
	ds_read_b128 v[154:157], v158 offset:2048
	ds_read_b128 v[158:161], v158 offset:3072
	s_add_u32 s16, s16, 0x40000
	s_addc_u32 s17, s17, 0
	s_mov_b32 m0, s35
	v_lshl_add_u64 v[200:201], s[16:17], 0, v[2:3]
	ds_read_b128 v[162:165], v145 offset:32768
	ds_read_b128 v[166:169], v145 offset:33792
	ds_read_b128 v[176:179], v145 offset:34816
	ds_read_b128 v[180:183], v145 offset:35840
	ds_read_b128 v[184:187], v145 offset:36864
	ds_read_b128 v[188:191], v145 offset:37888
	ds_read_b128 v[192:195], v145 offset:38912
	ds_read_b128 v[196:199], v145 offset:39936
	global_load_lds_dwordx4 v[200:201], off
	v_lshl_add_u64 v[200:201], s[16:17], 0, v[134:135]
	s_mov_b32 m0, s39
	s_nop 0
	global_load_lds_dwordx4 v[200:201], off
	s_waitcnt lgkmcnt(8)
	s_barrier
	s_waitcnt lgkmcnt(0)
	s_setprio 1
	s_waitcnt lgkmcnt(0)
	v_mfma_f32_16x16x32_bf16 v[130:133], v[146:149], v[162:165], v[130:133]
	v_mfma_f32_16x16x32_bf16 v[126:129], v[154:157], v[162:165], v[126:129]
	v_mfma_f32_16x16x32_bf16 v[122:125], v[146:149], v[176:179], v[122:125]
	v_mfma_f32_16x16x32_bf16 v[118:121], v[154:157], v[176:179], v[118:121]
	v_mfma_f32_16x16x32_bf16 v[106:109], v[146:149], v[184:187], v[106:109]
	v_mfma_f32_16x16x32_bf16 v[102:105], v[154:157], v[184:187], v[102:105]
	v_mfma_f32_16x16x32_bf16 v[90:93], v[146:149], v[192:195], v[90:93]
	v_mfma_f32_16x16x32_bf16 v[86:89], v[154:157], v[192:195], v[86:89]
	v_mfma_f32_16x16x32_bf16 v[130:133], v[150:153], v[166:169], v[130:133]
	v_mfma_f32_16x16x32_bf16 v[126:129], v[158:161], v[166:169], v[126:129]
	v_mfma_f32_16x16x32_bf16 v[122:125], v[150:153], v[180:183], v[122:125]
	v_mfma_f32_16x16x32_bf16 v[118:121], v[158:161], v[180:183], v[118:121]
	v_mfma_f32_16x16x32_bf16 v[106:109], v[150:153], v[188:191], v[106:109]
	v_mfma_f32_16x16x32_bf16 v[102:105], v[158:161], v[188:191], v[102:105]
	v_mfma_f32_16x16x32_bf16 v[90:93], v[150:153], v[196:199], v[90:93]
	v_mfma_f32_16x16x32_bf16 v[86:89], v[158:161], v[196:199], v[86:89]
	s_setprio 0
	s_barrier
	s_add_i32 s16, 0, 0x1c000
	s_add_i32 s17, s75, s30
	v_add_u32_e32 v170, s16, v144
	v_lshl_add_u64 v[172:173], v[172:173], 0, s[42:43]
	s_mov_b32 m0, s17
	ds_read_b128 v[200:203], v170
	ds_read_b128 v[204:207], v170 offset:1024
	ds_read_b128 v[222:225], v170 offset:2048
	ds_read_b128 v[226:229], v170 offset:3072
	global_load_lds_dwordx4 v[172:173], off
	v_lshl_add_u64 v[172:173], v[208:209], 0, s[42:43]
	s_add_i32 m0, s17, 0x2000
	s_nop 0
	global_load_lds_dwordx4 v[172:173], off
	s_barrier
	s_waitcnt lgkmcnt(0)
	s_setprio 1
	s_waitcnt lgkmcnt(0)
	v_mfma_f32_16x16x32_bf16 v[114:117], v[200:203], v[162:165], v[114:117]
	v_mfma_f32_16x16x32_bf16 v[110:113], v[222:225], v[162:165], v[110:113]
	v_mfma_f32_16x16x32_bf16 v[98:101], v[200:203], v[176:179], v[98:101]
	v_mfma_f32_16x16x32_bf16 v[94:97], v[222:225], v[176:179], v[94:97]
	v_mfma_f32_16x16x32_bf16 v[82:85], v[200:203], v[184:187], v[82:85]
	v_mfma_f32_16x16x32_bf16 v[78:81], v[222:225], v[184:187], v[78:81]
	v_mfma_f32_16x16x32_bf16 v[74:77], v[200:203], v[192:195], v[74:77]
	v_mfma_f32_16x16x32_bf16 v[70:73], v[222:225], v[192:195], v[70:73]
	v_mfma_f32_16x16x32_bf16 v[114:117], v[204:207], v[166:169], v[114:117]
	v_mfma_f32_16x16x32_bf16 v[110:113], v[226:229], v[166:169], v[110:113]
	v_mfma_f32_16x16x32_bf16 v[98:101], v[204:207], v[180:183], v[98:101]
	v_mfma_f32_16x16x32_bf16 v[94:97], v[226:229], v[180:183], v[94:97]
	v_mfma_f32_16x16x32_bf16 v[82:85], v[204:207], v[188:191], v[82:85]
	v_mfma_f32_16x16x32_bf16 v[78:81], v[226:229], v[188:191], v[78:81]
	v_mfma_f32_16x16x32_bf16 v[74:77], v[204:207], v[196:199], v[74:77]
	v_mfma_f32_16x16x32_bf16 v[70:73], v[226:229], v[196:199], v[70:73]
	s_setprio 0
	s_mov_b32 m0, s45
	v_lshl_add_u64 v[172:173], v[210:211], 0, s[42:43]
	s_barrier
	ds_read_b128 v[162:165], v145 offset:49152
	ds_read_b128 v[166:169], v145 offset:50176
	ds_read_b128 v[176:179], v145 offset:51200
	ds_read_b128 v[180:183], v145 offset:52224
	ds_read_b128 v[184:187], v145 offset:53248
	ds_read_b128 v[188:191], v145 offset:54272
	ds_read_b128 v[192:195], v145 offset:55296
	ds_read_b128 v[196:199], v145 offset:56320
	global_load_lds_dwordx4 v[172:173], off
	v_lshl_add_u64 v[172:173], v[218:219], 0, s[42:43]
	s_mov_b32 m0, s46
	s_nop 0
	global_load_lds_dwordx4 v[172:173], off
	s_barrier
; #define PG8_STAGE(bufoff, gbase, voff) do { _Pragma("unroll") for (int _i = 0; _i < 2; ++_i) \
;         __builtin_amdgcn_global_load_lds((const unsigned*)((const char*)(gbase) + (voff)[_i]), (LAS unsigned*)(lds + (bufoff) + ldsw + _i * 8192), 16, 0, 0); } while (0)
; #define PG8_MMA(ai, bj, At, Bt) do { __builtin_amdgcn_s_setprio(1); _Pragma("unroll") for (int m = 0; m < 4; ++m) _Pragma("unroll") for (int n = 0; n < 2; ++n) _Pragma("unroll") for (int k = 0; k < 2; ++k) \
;         acc[ai][bj][m][n] = __builtin_amdgcn_mfma_f32_16x16x32_bf16(Bt[n][k], At[m][k], acc[ai][bj][m][n], 0, 0, 0); __builtin_amdgcn_s_setprio(0); } while (0)
; #define PG8_WAIT_V(n) asm volatile("s_waitcnt vmcnt(" #n ")" ::: "memory")
; #define PG8_WAIT_L(n) asm volatile("s_waitcnt lgkmcnt(" #n ")" ::: "memory")
; #define PG8_BAR __builtin_amdgcn_s_barrier()
; #define PG8_SCHED __builtin_amdgcn_sched_barrier(0)
; template <class Epi, class Sched>
; __device__ __forceinline__ void gemm_phase(LAS unsigned char* lds, const int tid, const int ldk, const int Kloop, const Sched& S, const Epi& E) {
;     ...
;             PG8_BAR; PG8_WAIT_L(0); PG8_MMA(1, 0, At, B0); PG8_BAR; PG8_SCHED;
;             PG8_STAGE(PG8_SB(1, 1), b3 + hstep, voffB);
;             PG8_WAIT_V(6); PG8_BAR; PG8_MMA(1, 1, At, B1); PG8_BAR;
;         }
	s_waitcnt lgkmcnt(0)
	s_setprio 1
	s_waitcnt lgkmcnt(0)
	v_mfma_f32_16x16x32_bf16 v[66:69], v[146:149], v[162:165], v[66:69]
	v_mfma_f32_16x16x32_bf16 v[62:65], v[154:157], v[162:165], v[62:65]
	v_mfma_f32_16x16x32_bf16 v[58:61], v[146:149], v[176:179], v[58:61]
	v_mfma_f32_16x16x32_bf16 v[54:57], v[154:157], v[176:179], v[54:57]
	v_mfma_f32_16x16x32_bf16 v[42:45], v[146:149], v[184:187], v[42:45]
	v_mfma_f32_16x16x32_bf16 v[38:41], v[154:157], v[184:187], v[38:41]
	v_mfma_f32_16x16x32_bf16 v[26:29], v[146:149], v[192:195], v[26:29]
	v_mfma_f32_16x16x32_bf16 v[22:25], v[154:157], v[192:195], v[22:25]
	v_mfma_f32_16x16x32_bf16 v[66:69], v[150:153], v[166:169], v[66:69]
	v_mfma_f32_16x16x32_bf16 v[62:65], v[158:161], v[166:169], v[62:65]
	v_mfma_f32_16x16x32_bf16 v[58:61], v[150:153], v[180:183], v[58:61]
	v_mfma_f32_16x16x32_bf16 v[54:57], v[158:161], v[180:183], v[54:57]
	v_mfma_f32_16x16x32_bf16 v[42:45], v[150:153], v[188:191], v[42:45]
	v_mfma_f32_16x16x32_bf16 v[38:41], v[158:161], v[188:191], v[38:41]
	v_mfma_f32_16x16x32_bf16 v[26:29], v[150:153], v[196:199], v[26:29]
	v_mfma_f32_16x16x32_bf16 v[22:25], v[158:161], v[196:199], v[22:25]
	s_setprio 0
	s_barrier
	s_add_u32 s14, s14, 0x40080
	s_addc_u32 s15, s15, 0
	s_add_i32 s16, s16, s30
	v_lshl_add_u64 v[146:147], s[14:15], 0, v[4:5]
	s_mov_b32 m0, s16
	s_nop 0
	global_load_lds_dwordx4 v[146:147], off
	v_lshl_add_u64 v[146:147], s[14:15], 0, v[136:137]
	s_add_i32 m0, s16, 0x2000
	s_nop 0
	global_load_lds_dwordx4 v[146:147], off
	s_waitcnt vmcnt(6)
	s_barrier
	s_setprio 1
	v_mfma_f32_16x16x32_bf16 v[50:53], v[200:203], v[162:165], v[50:53]
	v_mfma_f32_16x16x32_bf16 v[46:49], v[222:225], v[162:165], v[46:49]
	v_mfma_f32_16x16x32_bf16 v[34:37], v[200:203], v[176:179], v[34:37]
	v_mfma_f32_16x16x32_bf16 v[30:33], v[222:225], v[176:179], v[30:33]
	v_mfma_f32_16x16x32_bf16 v[18:21], v[200:203], v[184:187], v[18:21]
	v_mfma_f32_16x16x32_bf16 v[14:17], v[222:225], v[184:187], v[14:17]
	v_mfma_f32_16x16x32_bf16 v[10:13], v[200:203], v[192:195], v[10:13]
	v_mfma_f32_16x16x32_bf16 v[6:9], v[222:225], v[192:195], v[6:9]
	v_mfma_f32_16x16x32_bf16 v[50:53], v[204:207], v[166:169], v[50:53]
	v_mfma_f32_16x16x32_bf16 v[46:49], v[226:229], v[166:169], v[46:49]
	v_mfma_f32_16x16x32_bf16 v[34:37], v[204:207], v[180:183], v[34:37]
	v_mfma_f32_16x16x32_bf16 v[30:33], v[226:229], v[180:183], v[30:33]
	v_mfma_f32_16x16x32_bf16 v[18:21], v[204:207], v[188:191], v[18:21]
	v_mfma_f32_16x16x32_bf16 v[14:17], v[226:229], v[188:191], v[14:17]
	v_mfma_f32_16x16x32_bf16 v[10:13], v[204:207], v[196:199], v[10:13]
	v_mfma_f32_16x16x32_bf16 v[6:9], v[226:229], v[196:199], v[6:9]
	s_setprio 0
	s_add_i32 s74, s74, 2
	s_add_u32 s12, s12, 0x100
	s_addc_u32 s13, s13, 0
	s_add_u32 s72, s72, 0x100
	s_addc_u32 s73, s73, 0
	s_cmp_gt_u32 s74, 13
	s_barrier
	s_cbranch_scc0 .LBB0_181
; __device__ __forceinline__ unsigned pk2(float lo, float hi) { const bf2_t r = __builtin_convertvector((f32x2){lo, hi}, bf2_t); unsigned u; __builtin_memcpy(&u, &r, 4); return u; }
; #define PG8_WAIT_V(n) asm volatile("s_waitcnt vmcnt(" #n ")" ::: "memory")
; #define PG8_BAR __builtin_amdgcn_s_barrier()
;     __device__ __forceinline__ void operator()(const f32x4 (&acc)[2][2][4][2], const Unit& u, int wr, int wc, int fr, int fq) const {
;     ...
;         for (int ai = 0; ai < 2; ++ai)
; #pragma unroll
;             for (int m = 0; m < 4; ++m) { bf16_t* rowp = base + (size_t)(ai * HALF + wr * 64 + m * 16 + fr) * u.ldc + wc * 32 + 8 * fq;
; #pragma unroll
;                 for (int bj = 0; bj < 2; ++bj) { const f32x4 v0 = acc[ai][bj][m][0], v1 = acc[ai][bj][m][1];
;                     u32x4 w; w.x = pk2(v0[0], v0[1]); w.y = pk2(v0[2], v0[3]); w.z = pk2(v1[0], v1[1]); w.w = pk2(v1[2], v1[3]);
;                     *(u32x4*)(rowp + bj * HALF) = w; } }
; template <class Epi, class Sched>
; __device__ __forceinline__ void gemm_phase(LAS unsigned char* lds, const int tid, const int ldk, const int Kloop, const Sched& S, const Epi& E) {
;     ...
;         if (!has_next) break;
; #pragma unroll
;         for (int a = 0; a < 2; ++a)
; #pragma unroll
;             for (int b = 0; b < 2; ++b)
; #pragma unroll
;                 for (int m = 0; m < 4; ++m)
; #pragma unroll
;                     for (int n = 0; n < 2; ++n) acc[a][b][m][n] = (f32x4){0.f, 0.f, 0.f, 0.f};
;         cur = nxt; cA = nA; cB = nB; ++ui;
;     }
;     PG8_WAIT_V(0);
;     if (wr == 0) PG8_BAR;
	v_mov_b32_e32 v146, v143
	v_mov_b32_e32 v147, v142
	s_add_u32 s2, s2, s70
	v_lshlrev_b32_e32 v146, 3, v146
	v_add_u32_e32 v150, s40, v147
	s_addc_u32 s3, s3, 0
	v_ashrrev_i32_e32 v147, 31, v146
	v_lshl_add_u64 v[146:147], v[146:147], 1, s[2:3]
	v_mad_i64_i32 v[148:149], s[2:3], v150, s27, 0
	v_cvt_pk_bf16_f32 v114, v114, v115
	v_cvt_pk_bf16_f32 v115, v116, v117
	v_cvt_pk_bf16_f32 v116, v110, v111
	v_add_u32_e32 v110, 16, v150
	v_lshl_add_u64 v[148:149], v[148:149], 1, v[146:147]
	v_cvt_pk_bf16_f32 v117, v112, v113
	v_mad_i64_i32 v[110:111], s[2:3], v110, s27, 0
	v_cvt_pk_bf16_f32 v98, v98, v99
	v_cvt_pk_bf16_f32 v99, v100, v101
	v_cvt_pk_bf16_f32 v100, v94, v95
	v_add_u32_e32 v94, 32, v150
	v_cvt_pk_bf16_f32 v130, v130, v131
	v_cvt_pk_bf16_f32 v131, v132, v133
	v_cvt_pk_bf16_f32 v132, v126, v127
	v_cvt_pk_bf16_f32 v133, v128, v129
	global_store_dwordx4 v[148:149], v[114:117], off offset:256
	v_cvt_pk_bf16_f32 v101, v96, v97
	v_mad_i64_i32 v[94:95], s[2:3], v94, s27, 0
	v_lshl_add_u64 v[114:115], v[110:111], 1, v[146:147]
	v_cvt_pk_bf16_f32 v82, v82, v83
	v_cvt_pk_bf16_f32 v83, v84, v85
	v_cvt_pk_bf16_f32 v84, v78, v79
	v_add_u32_e32 v78, 48, v150
	v_cvt_pk_bf16_f32 v74, v74, v75
	v_cvt_pk_bf16_f32 v75, v76, v77
	v_cvt_pk_bf16_f32 v76, v70, v71
	v_add_u32_e32 v70, 0x80, v150
	global_store_dwordx4 v[148:149], v[130:133], off
	v_cvt_pk_bf16_f32 v110, v122, v123
	v_cvt_pk_bf16_f32 v111, v124, v125
	v_cvt_pk_bf16_f32 v112, v118, v119
	v_cvt_pk_bf16_f32 v113, v120, v121
	global_store_dwordx4 v[114:115], v[98:101], off offset:256
	v_cvt_pk_bf16_f32 v85, v80, v81
	v_mad_i64_i32 v[78:79], s[2:3], v78, s27, 0
	v_lshl_add_u64 v[98:99], v[94:95], 1, v[146:147]
	v_mad_i64_i32 v[70:71], s[2:3], v70, s27, 0
	v_cvt_pk_bf16_f32 v50, v50, v51
	v_cvt_pk_bf16_f32 v51, v52, v53
	v_cvt_pk_bf16_f32 v52, v46, v47
	v_add_u32_e32 v46, 0x90, v150
	global_store_dwordx4 v[114:115], v[110:113], off
	v_cvt_pk_bf16_f32 v94, v106, v107
	v_cvt_pk_bf16_f32 v95, v108, v109
	v_cvt_pk_bf16_f32 v96, v102, v103
	v_cvt_pk_bf16_f32 v97, v104, v105
	global_store_dwordx4 v[98:99], v[82:85], off offset:256
	v_cvt_pk_bf16_f32 v80, v86, v87
	v_cvt_pk_bf16_f32 v81, v88, v89
	v_lshl_add_u64 v[82:83], v[78:79], 1, v[146:147]
	v_cvt_pk_bf16_f32 v78, v90, v91
	v_cvt_pk_bf16_f32 v79, v92, v93
	v_cvt_pk_bf16_f32 v77, v72, v73
	v_lshl_add_u64 v[70:71], v[70:71], 1, v[146:147]
	v_cvt_pk_bf16_f32 v53, v48, v49
	v_mad_i64_i32 v[46:47], s[2:3], v46, s27, 0
	v_cvt_pk_bf16_f32 v34, v34, v35
	v_cvt_pk_bf16_f32 v35, v36, v37
	v_cvt_pk_bf16_f32 v36, v30, v31
	v_add_u32_e32 v30, 0xa0, v150
	global_store_dwordx4 v[98:99], v[94:97], off
	global_store_dwordx4 v[82:83], v[78:81], off
	global_store_dwordx4 v[82:83], v[74:77], off offset:256
	v_cvt_pk_bf16_f32 v66, v66, v67
	v_cvt_pk_bf16_f32 v67, v68, v69
	v_cvt_pk_bf16_f32 v68, v62, v63
	v_cvt_pk_bf16_f32 v69, v64, v65
	global_store_dwordx4 v[70:71], v[50:53], off offset:256
	v_cvt_pk_bf16_f32 v37, v32, v33
	v_mad_i64_i32 v[30:31], s[2:3], v30, s27, 0
	v_lshl_add_u64 v[50:51], v[46:47], 1, v[146:147]
	v_cvt_pk_bf16_f32 v18, v18, v19
	v_cvt_pk_bf16_f32 v19, v20, v21
	v_cvt_pk_bf16_f32 v20, v14, v15
	v_add_u32_e32 v14, 0xb0, v150
	global_store_dwordx4 v[70:71], v[66:69], off
	v_cvt_pk_bf16_f32 v46, v58, v59
	v_cvt_pk_bf16_f32 v47, v60, v61
	v_cvt_pk_bf16_f32 v48, v54, v55
	v_cvt_pk_bf16_f32 v49, v56, v57
	global_store_dwordx4 v[50:51], v[34:37], off offset:256
	v_cvt_pk_bf16_f32 v21, v16, v17
	v_mad_i64_i32 v[14:15], s[2:3], v14, s27, 0
	v_lshl_add_u64 v[34:35], v[30:31], 1, v[146:147]
	global_store_dwordx4 v[50:51], v[46:49], off
	v_cvt_pk_bf16_f32 v30, v42, v43
	v_cvt_pk_bf16_f32 v31, v44, v45
	v_cvt_pk_bf16_f32 v32, v38, v39
	v_cvt_pk_bf16_f32 v33, v40, v41
	global_store_dwordx4 v[34:35], v[18:21], off offset:256
	v_cvt_pk_bf16_f32 v16, v22, v23
	v_cvt_pk_bf16_f32 v17, v24, v25
	v_lshl_add_u64 v[18:19], v[14:15], 1, v[146:147]
	v_cvt_pk_bf16_f32 v14, v26, v27
	v_cvt_pk_bf16_f32 v15, v28, v29
	v_cvt_pk_bf16_f32 v10, v10, v11
	v_cvt_pk_bf16_f32 v11, v12, v13
	v_cvt_pk_bf16_f32 v12, v6, v7
	v_cvt_pk_bf16_f32 v13, v8, v9
	s_and_b64 vcc, exec, s[4:5]
	s_mov_b64 s[2:3], s[10:11]
	s_mov_b32 s27, s71
	s_mov_b64 s[14:15], s[8:9]
	s_mov_b64 s[12:13], s[6:7]
	global_store_dwordx4 v[34:35], v[30:33], off
	global_store_dwordx4 v[18:19], v[14:17], off
	global_store_dwordx4 v[18:19], v[10:13], off offset:256
	s_cbranch_vccz .LBB0_171
	s_cmp_eq_u32 s100, 1
	s_cbranch_scc1 .Lg_inv_done_1
	s_mov_b32 s100, 1
	v_readfirstlane_b32 s98, v217
	s_cmp_lt_u32 s98, 0x1c0
	s_cbranch_scc1 .Lg_inv_done_1
	buffer_inv sc1
.Lg_inv_done_1:
	s_waitcnt vmcnt(0)
	s_cmpk_gt_u32 s20, 0xff
	s_cbranch_scc1 .LBB0_185
	s_barrier

; __device__ __forceinline__ void xcd_barrier(const XcdBarrier& b) {
;     asm volatile("s_waitcnt vmcnt(0)" ::: "memory");
;     __syncthreads();
;     int tid0 = threadIdx.x; asm volatile("" : "+v"(tid0));
;     if (tid0 == 0) {
;         unsigned* bar = b.bar;
;         __builtin_amdgcn_s_waitcnt(0);
;         unsigned nloc = b.st[0], nx = b.st[1];
;         if (nloc == 0u) { xcd_barrier_complete(bar, b.x, nloc, nx); b.st[0] = nloc; b.st[1] = nx; }
.LBB0_186:
	s_mov_b64 s[4:5], 0
	s_getreg_b32 s6, hwreg(HW_REG_XCC_ID, 0, 4)
	s_cselect_b32 s99, 1, 0
	s_cmp_eq_u32 s100, 1
	s_cbranch_scc1 .Lxb_noinv_2
	v_readfirstlane_b32 s98, v217
	s_cmp_lt_u32 s98, 0x1c0
	s_cbranch_scc1 .Lxb_noinv_2
	buffer_inv sc1
.Lxb_noinv_2:
	s_mov_b32 s100, 0
	s_cmp_lg_u32 s99, 0
	s_waitcnt vmcnt(0)
	v_mov_b32_e32 v2, v217
	s_waitcnt vmcnt(0) lgkmcnt(0)
	s_barrier
	s_nop 0
	v_cmp_eq_u32_e32 vcc, 0, v2
	s_and_saveexec_b64 s[2:3], vcc
	s_xor_b64 s[2:3], exec, s[2:3]
	s_cbranch_execz .LBB0_239
	v_readlane_b32 s7, v255, 23
	s_waitcnt vmcnt(0) expcnt(0) lgkmcnt(0)
	s_lshl_b64 s[4:5], s[4:5], 2
	v_mov_b32_e32 v2, s7
	ds_read_b32 v4, v2
	v_readlane_b32 s7, v255, 24
	s_add_u32 s4, s96, s4
	s_addc_u32 s5, s97, s5
	v_mov_b32_e32 v2, s7
	ds_read_b32 v2, v2
	s_waitcnt lgkmcnt(1)
	v_cmp_ne_u32_e32 vcc, 0, v4
	s_and_b32 s22, s6, 15
	s_cbranch_vccnz .LBB0_202
	v_readlane_b32 s6, v255, 0
	v_readlane_b32 s7, v255, 1
	s_load_dwordx2 s[10:11], s[6:7], 0x4
	s_add_u32 s6, s4, 0x1000
	s_addc_u32 s7, s5, 0
	s_add_u32 s8, s4, 0x1100
	s_addc_u32 s9, s5, 0
	s_waitcnt lgkmcnt(0)
	s_mul_i32 s23, s10, s34
	s_add_u32 s10, s4, 0x1200
	s_mul_i32 s23, s23, s11
	s_addc_u32 s11, s5, 0
	s_add_u32 s12, s4, 0x1300
	s_addc_u32 s13, s5, 0
	s_mov_b32 s24, 1
	s_branch .LBB0_190

; __device__ __forceinline__ void xcd_barrier(const XcdBarrier& b) {
;     asm volatile("s_waitcnt vmcnt(0)" ::: "memory");
;     __syncthreads();
;     int tid0 = threadIdx.x; asm volatile("" : "+v"(tid0));
;     if (tid0 == 0) {
;         unsigned* bar = b.bar;
;         __builtin_amdgcn_s_waitcnt(0);
;         unsigned nloc = b.st[0], nx = b.st[1];
;         if (nloc == 0u) { xcd_barrier_complete(bar, b.x, nloc, nx); b.st[0] = nloc; b.st[1] = nx; }
.LBB0_283:
	s_waitcnt lgkmcnt(0)
	s_mov_b64 s[4:5], 0
	s_getreg_b32 s6, hwreg(HW_REG_XCC_ID, 0, 4)
	s_cselect_b32 s99, 1, 0
	s_cmp_eq_u32 s100, 1
	s_cbranch_scc1 .Lxb_noinv_3
	v_readfirstlane_b32 s98, v217
	s_cmp_lt_u32 s98, 0x1c0
	s_cbranch_scc1 .Lxb_noinv_3
	buffer_inv sc1
.Lxb_noinv_3:
	s_mov_b32 s100, 0
	s_cmp_lg_u32 s99, 0
	s_waitcnt vmcnt(0)
	v_mov_b32_e32 v2, v217
	s_barrier
	s_nop 0
	v_cmp_eq_u32_e32 vcc, 0, v2
	s_and_saveexec_b64 s[2:3], vcc
	s_xor_b64 s[2:3], exec, s[2:3]
	v_readlane_b32 s34, v255, 2
	s_cbranch_execz .LBB0_336
	v_readlane_b32 s7, v255, 23
	s_waitcnt vmcnt(0) expcnt(0) lgkmcnt(0)
	s_lshl_b64 s[4:5], s[4:5], 2
	v_mov_b32_e32 v2, s7
	ds_read_b32 v4, v2
	v_readlane_b32 s7, v255, 24
	s_add_u32 s4, s96, s4
	s_addc_u32 s5, s97, s5
	v_mov_b32_e32 v2, s7
	ds_read_b32 v2, v2
	s_waitcnt lgkmcnt(1)
	v_cmp_ne_u32_e32 vcc, 0, v4
	s_and_b32 s22, s6, 15
	s_cbranch_vccnz .LBB0_299
	v_readlane_b32 s6, v255, 0
	v_readlane_b32 s7, v255, 1
	s_load_dwordx2 s[10:11], s[6:7], 0x4
	s_add_u32 s6, s4, 0x1000
	s_addc_u32 s7, s5, 0
	s_add_u32 s8, s4, 0x1100
	s_addc_u32 s9, s5, 0
	s_waitcnt lgkmcnt(0)
	s_mul_i32 s23, s10, s34
	s_add_u32 s10, s4, 0x1200
	s_mul_i32 s23, s23, s11
	s_addc_u32 s11, s5, 0
	s_add_u32 s12, s4, 0x1300
	s_addc_u32 s13, s5, 0
	s_mov_b32 s24, 1
	s_branch .LBB0_287

; __device__ __forceinline__ void xcd_barrier(const XcdBarrier& b) {
;     asm volatile("s_waitcnt vmcnt(0)" ::: "memory");
;     __syncthreads();
;     int tid0 = threadIdx.x; asm volatile("" : "+v"(tid0));
;     if (tid0 == 0) {
;         unsigned* bar = b.bar;
;         __builtin_amdgcn_s_waitcnt(0);
;         unsigned nloc = b.st[0], nx = b.st[1];
;         if (nloc == 0u) { xcd_barrier_complete(bar, b.x, nloc, nx); b.st[0] = nloc; b.st[1] = nx; }
.Lxb_noinv_4:
	s_mov_b32 s100, 0
	s_cmp_lg_u32 s99, 0
	s_waitcnt vmcnt(0)
	v_mov_b32_e32 v2, v217
	s_waitcnt lgkmcnt(0)
	s_barrier
	s_nop 0
	v_cmp_eq_u32_e32 vcc, 0, v2
	s_and_saveexec_b64 s[2:3], vcc
	v_readlane_b32 s92, v255, 35
	v_readlane_b32 s94, v255, 37
	v_readlane_b32 s96, v255, 39
	v_readlane_b32 s90, v255, 34
	v_readlane_b32 s93, v255, 36
	v_readlane_b32 s95, v255, 38
	v_readlane_b32 s97, v255, 40
	s_cbranch_execz .LBB0_457
	v_readlane_b32 s7, v255, 23
	s_waitcnt vmcnt(0) expcnt(0) lgkmcnt(0)
	s_lshl_b64 s[4:5], s[4:5], 2
	v_mov_b32_e32 v2, s7
	ds_read_b32 v4, v2
	v_readlane_b32 s7, v255, 24
	s_add_u32 s4, s96, s4
	s_addc_u32 s5, s97, s5
	v_mov_b32_e32 v2, s7
	ds_read_b32 v2, v2
	s_waitcnt lgkmcnt(1)
	v_cmp_ne_u32_e32 vcc, 0, v4
	s_and_b32 s22, s6, 15
	s_cbranch_vccnz .LBB0_421
	v_readlane_b32 s6, v255, 0
	v_readlane_b32 s7, v255, 1
	s_load_dwordx2 s[10:11], s[6:7], 0x4
	s_add_u32 s6, s4, 0x1000
	s_addc_u32 s7, s5, 0
	s_add_u32 s8, s4, 0x1100
	s_addc_u32 s9, s5, 0
	s_waitcnt lgkmcnt(0)
	s_mul_i32 s23, s10, s34
	s_add_u32 s10, s4, 0x1200
	s_mul_i32 s23, s23, s11
	s_addc_u32 s11, s5, 0
	s_add_u32 s12, s4, 0x1300
	s_addc_u32 s13, s5, 0
	s_mov_b32 s24, 1
	s_branch .LBB0_409

; __device__ __forceinline__ void xcd_barrier(const XcdBarrier& b) {
;     asm volatile("s_waitcnt vmcnt(0)" ::: "memory");
;     __syncthreads();
;     int tid0 = threadIdx.x; asm volatile("" : "+v"(tid0));
;     if (tid0 == 0) {
;         unsigned* bar = b.bar;
;         __builtin_amdgcn_s_waitcnt(0);
;         unsigned nloc = b.st[0], nx = b.st[1];
;         if (nloc == 0u) { xcd_barrier_complete(bar, b.x, nloc, nx); b.st[0] = nloc; b.st[1] = nx; }
.Lxb_noinv_5:
	s_mov_b32 s100, 0
	s_cmp_lg_u32 s99, 0
	s_waitcnt vmcnt(0)
	v_mov_b32_e32 v2, v217
	s_barrier
	s_nop 0
	v_cmp_eq_u32_e32 vcc, 0, v2
	s_and_saveexec_b64 s[2:3], vcc
	s_xor_b64 s[2:3], exec, s[2:3]
	s_cbranch_execz .LBB0_516
	v_readlane_b32 s7, v255, 23
	s_waitcnt vmcnt(0) expcnt(0) lgkmcnt(0)
	s_lshl_b64 s[4:5], s[4:5], 2
	v_mov_b32_e32 v2, s7
	ds_read_b32 v4, v2
	v_readlane_b32 s7, v255, 24
	s_add_u32 s4, s96, s4
	s_addc_u32 s5, s97, s5
	v_mov_b32_e32 v2, s7
	ds_read_b32 v2, v2
	s_waitcnt lgkmcnt(1)
	v_cmp_ne_u32_e32 vcc, 0, v4
	s_and_b32 s22, s6, 15
	s_cbranch_vccnz .LBB0_479
	v_readlane_b32 s6, v255, 0
	v_readlane_b32 s7, v255, 1
	s_load_dwordx2 s[10:11], s[6:7], 0x4
	s_add_u32 s6, s4, 0x1000
	s_addc_u32 s7, s5, 0
	s_add_u32 s8, s4, 0x1100
	s_addc_u32 s9, s5, 0
	s_waitcnt lgkmcnt(0)
	s_mul_i32 s23, s10, s34
	s_add_u32 s10, s4, 0x1200
	s_mul_i32 s23, s23, s11
	s_addc_u32 s11, s5, 0
	s_add_u32 s12, s4, 0x1300
	s_addc_u32 s13, s5, 0
	s_mov_b32 s24, 1
	s_branch .LBB0_467

; #define PG8_STAGE(bufoff, gbase, voff) do { _Pragma("unroll") for (int _i = 0; _i < 2; ++_i) \
;         __builtin_amdgcn_global_load_lds((const unsigned*)((const char*)(gbase) + (voff)[_i]), (LAS unsigned*)(lds + (bufoff) + ldsw + _i * 8192), 16, 0, 0); } while (0)
; #define PG8_LDA(dst, b, h) do { _Pragma("unroll") for (int m = 0; m < 4; ++m) _Pragma("unroll") for (int k = 0; k < 2; ++k) dst[m][k] = *(const LAS bf16x8*)(lds + PG8_SA(b, h) + aoff + m * 2048 + k * 1024); } while (0)
; #define PG8_LDB(dst, b, h) do { _Pragma("unroll") for (int n = 0; n < 2; ++n) _Pragma("unroll") for (int k = 0; k < 2; ++k) dst[n][k] = *(const LAS bf16x8*)(lds + PG8_SB(b, h) + boff + n * 2048 + k * 1024); } while (0)
; #define PG8_MMA(ai, bj, At, Bt) do { __builtin_amdgcn_s_setprio(1); _Pragma("unroll") for (int m = 0; m < 4; ++m) _Pragma("unroll") for (int n = 0; n < 2; ++n) _Pragma("unroll") for (int k = 0; k < 2; ++k) \
;         acc[ai][bj][m][n] = __builtin_amdgcn_mfma_f32_16x16x32_bf16(Bt[n][k], At[m][k], acc[ai][bj][m][n], 0, 0, 0); __builtin_amdgcn_s_setprio(0); } while (0)
; #define PG8_WAIT_L(n) asm volatile("s_waitcnt lgkmcnt(" #n ")" ::: "memory")
; #define PG8_BAR __builtin_amdgcn_s_barrier()
; #define PG8_SCHED __builtin_amdgcn_sched_barrier(0)
; template <class Epi, class Sched>
; __device__ __forceinline__ void gemm_phase(LAS unsigned char* lds, const int tid, const int ldk, const int Kloop, const Sched& S, const Epi& E) {
;     ...
;         for (int t = 0; t < nt; t += 2) {
;             const bool last = (t == nt - 2);
;             const char* a1 = cA + (size_t)(t + 1) * kstep;
;             const char* a2 = last ? nA : cA + (size_t)(t + 2) * kstep; const char* b2 = last ? nB : cB + (size_t)(t + 2) * kstep;
;             const char* a3 = a2 + kstep; const char* b3 = b2 + kstep;
;             PG8_LDB(B0, 0, 0); PG8_SCHED; PG8_LDA(At, 0, 0); PG8_STAGE(PG8_SA(1, 1), a1 + hstep, voffA);
;             PG8_WAIT_L(8); PG8_BAR; PG8_WAIT_L(0); PG8_MMA(0, 0, At, B0); PG8_BAR; PG8_SCHED;
;             PG8_LDB(B1, 0, 1); PG8_STAGE(PG8_SB(0, 0), b2, voffB);
;             PG8_BAR; PG8_WAIT_L(0); PG8_MMA(0, 1, At, B1); PG8_BAR;
;             PG8_LDA(At, 0, 1); PG8_STAGE(PG8_SA(0, 0), a2, voffA);
;             PG8_BAR; PG8_WAIT_L(0); PG8_MMA(1, 0, At, B0); PG8_BAR; PG8_SCHED;
.LBB0_523:
	s_add_u32 s14, s12, 0xfff80080
	s_addc_u32 s15, s13, -1
	s_add_i32 s67, 0, 0x10000
	v_add_u32_e32 v158, s67, v144
	ds_read_b128 v[146:149], v158
	ds_read_b128 v[150:153], v158 offset:1024
	ds_read_b128 v[154:157], v158 offset:2048
	ds_read_b128 v[158:161], v158 offset:3072
	s_cmp_eq_u32 s66, 4
	s_cselect_b32 s17, s3, s15
	s_cselect_b32 s16, s2, s14
	s_cselect_b32 s15, s5, s57
	s_cselect_b32 s14, s4, s56
	v_lshl_add_u64 v[172:173], s[12:13], 0, v[138:139]
	s_add_i32 m0, s30, 0xc000
	ds_read_b128 v[162:165], v145
	ds_read_b128 v[166:169], v145 offset:1024
	ds_read_b128 v[176:179], v145 offset:2048
	ds_read_b128 v[180:183], v145 offset:3072
	ds_read_b128 v[184:187], v145 offset:4096
	ds_read_b128 v[188:191], v145 offset:5120
	ds_read_b128 v[192:195], v145 offset:6144
	ds_read_b128 v[196:199], v145 offset:7168
	global_load_lds_dwordx4 v[172:173], off
	v_lshl_add_u64 v[172:173], s[12:13], 0, v[140:141]
	s_add_i32 m0, s30, 0xe000
	s_nop 0
	global_load_lds_dwordx4 v[172:173], off
	s_waitcnt lgkmcnt(8)
	s_barrier
	s_waitcnt lgkmcnt(0)
	s_setprio 1
	s_waitcnt lgkmcnt(0)
	v_mfma_f32_16x16x32_bf16 v[130:133], v[146:149], v[162:165], v[130:133]
	v_mfma_f32_16x16x32_bf16 v[126:129], v[154:157], v[162:165], v[126:129]
	v_mfma_f32_16x16x32_bf16 v[122:125], v[146:149], v[176:179], v[122:125]
	v_mfma_f32_16x16x32_bf16 v[118:121], v[154:157], v[176:179], v[118:121]
	v_mfma_f32_16x16x32_bf16 v[106:109], v[146:149], v[184:187], v[106:109]
	v_mfma_f32_16x16x32_bf16 v[102:105], v[154:157], v[184:187], v[102:105]
	v_mfma_f32_16x16x32_bf16 v[90:93], v[146:149], v[192:195], v[90:93]
	v_mfma_f32_16x16x32_bf16 v[86:89], v[154:157], v[192:195], v[86:89]
	v_mfma_f32_16x16x32_bf16 v[130:133], v[150:153], v[166:169], v[130:133]
	v_mfma_f32_16x16x32_bf16 v[126:129], v[158:161], v[166:169], v[126:129]
	v_mfma_f32_16x16x32_bf16 v[122:125], v[150:153], v[180:183], v[122:125]
	v_mfma_f32_16x16x32_bf16 v[118:121], v[158:161], v[180:183], v[118:121]
	v_mfma_f32_16x16x32_bf16 v[106:109], v[150:153], v[188:191], v[106:109]
	v_mfma_f32_16x16x32_bf16 v[102:105], v[158:161], v[188:191], v[102:105]
	v_mfma_f32_16x16x32_bf16 v[90:93], v[150:153], v[196:199], v[90:93]
	v_mfma_f32_16x16x32_bf16 v[86:89], v[158:161], v[196:199], v[86:89]
	s_setprio 0
	s_barrier
	s_add_i32 s70, 0, 0x14000
	s_add_i32 s67, s67, s27
	v_add_u32_e32 v170, s70, v144
	v_lshl_add_u64 v[172:173], s[14:15], 0, v[4:5]
	s_mov_b32 m0, s67
	ds_read_b128 v[200:203], v170
	ds_read_b128 v[204:207], v170 offset:1024
	ds_read_b128 v[222:225], v170 offset:2048
	ds_read_b128 v[226:229], v170 offset:3072
	global_load_lds_dwordx4 v[172:173], off
	v_lshl_add_u64 v[208:209], s[14:15], 0, v[2:3]
	s_add_i32 m0, s67, 0x2000
	s_nop 0
	global_load_lds_dwordx4 v[208:209], off
	s_barrier
	s_waitcnt lgkmcnt(0)
	s_setprio 1
	s_waitcnt lgkmcnt(0)
	v_mfma_f32_16x16x32_bf16 v[114:117], v[200:203], v[162:165], v[114:117]
	v_mfma_f32_16x16x32_bf16 v[110:113], v[222:225], v[162:165], v[110:113]
	v_mfma_f32_16x16x32_bf16 v[98:101], v[200:203], v[176:179], v[98:101]
	v_mfma_f32_16x16x32_bf16 v[94:97], v[222:225], v[176:179], v[94:97]
	v_mfma_f32_16x16x32_bf16 v[82:85], v[200:203], v[184:187], v[82:85]
	v_mfma_f32_16x16x32_bf16 v[78:81], v[222:225], v[184:187], v[78:81]
	v_mfma_f32_16x16x32_bf16 v[74:77], v[200:203], v[192:195], v[74:77]
	v_mfma_f32_16x16x32_bf16 v[70:73], v[222:225], v[192:195], v[70:73]
	v_mfma_f32_16x16x32_bf16 v[114:117], v[204:207], v[166:169], v[114:117]
	v_mfma_f32_16x16x32_bf16 v[110:113], v[226:229], v[166:169], v[110:113]
	v_mfma_f32_16x16x32_bf16 v[98:101], v[204:207], v[180:183], v[98:101]
	v_mfma_f32_16x16x32_bf16 v[94:97], v[226:229], v[180:183], v[94:97]
	v_mfma_f32_16x16x32_bf16 v[82:85], v[204:207], v[188:191], v[82:85]
	v_mfma_f32_16x16x32_bf16 v[78:81], v[226:229], v[188:191], v[78:81]
	v_mfma_f32_16x16x32_bf16 v[74:77], v[204:207], v[196:199], v[74:77]
	v_mfma_f32_16x16x32_bf16 v[70:73], v[226:229], v[196:199], v[70:73]
	s_setprio 0
	s_mov_b32 m0, s30
	v_lshl_add_u64 v[210:211], s[16:17], 0, v[136:137]
	s_barrier
	ds_read_b128 v[162:165], v145 offset:16384
	ds_read_b128 v[166:169], v145 offset:17408
	ds_read_b128 v[176:179], v145 offset:18432
	ds_read_b128 v[180:183], v145 offset:19456
	ds_read_b128 v[184:187], v145 offset:20480
	ds_read_b128 v[188:191], v145 offset:21504
	ds_read_b128 v[192:195], v145 offset:22528
	ds_read_b128 v[196:199], v145 offset:23552
	global_load_lds_dwordx4 v[210:211], off
	v_lshl_add_u64 v[218:219], s[16:17], 0, v[134:135]
	s_mov_b32 m0, s31
	s_nop 0
	global_load_lds_dwordx4 v[218:219], off
	s_barrier
	s_waitcnt lgkmcnt(0)
	s_setprio 1
	s_waitcnt lgkmcnt(0)
	v_mfma_f32_16x16x32_bf16 v[66:69], v[146:149], v[162:165], v[66:69]
	v_mfma_f32_16x16x32_bf16 v[62:65], v[154:157], v[162:165], v[62:65]
	v_mfma_f32_16x16x32_bf16 v[58:61], v[146:149], v[176:179], v[58:61]
	v_mfma_f32_16x16x32_bf16 v[54:57], v[154:157], v[176:179], v[54:57]
	v_mfma_f32_16x16x32_bf16 v[42:45], v[146:149], v[184:187], v[42:45]
	v_mfma_f32_16x16x32_bf16 v[38:41], v[154:157], v[184:187], v[38:41]
	v_mfma_f32_16x16x32_bf16 v[26:29], v[146:149], v[192:195], v[26:29]
	v_mfma_f32_16x16x32_bf16 v[22:25], v[154:157], v[192:195], v[22:25]
	v_mfma_f32_16x16x32_bf16 v[66:69], v[150:153], v[166:169], v[66:69]
	v_mfma_f32_16x16x32_bf16 v[62:65], v[158:161], v[166:169], v[62:65]
	v_mfma_f32_16x16x32_bf16 v[58:61], v[150:153], v[180:183], v[58:61]
	v_mfma_f32_16x16x32_bf16 v[54:57], v[158:161], v[180:183], v[54:57]
	v_mfma_f32_16x16x32_bf16 v[42:45], v[150:153], v[188:191], v[42:45]
	v_mfma_f32_16x16x32_bf16 v[38:41], v[158:161], v[188:191], v[38:41]
	v_mfma_f32_16x16x32_bf16 v[26:29], v[150:153], v[196:199], v[26:29]
	v_mfma_f32_16x16x32_bf16 v[22:25], v[158:161], v[196:199], v[22:25]
	s_setprio 0
	s_barrier
; #define PG8_STAGE(bufoff, gbase, voff) do { _Pragma("unroll") for (int _i = 0; _i < 2; ++_i) \
;         __builtin_amdgcn_global_load_lds((const unsigned*)((const char*)(gbase) + (voff)[_i]), (LAS unsigned*)(lds + (bufoff) + ldsw + _i * 8192), 16, 0, 0); } while (0)
; #define PG8_LDA(dst, b, h) do { _Pragma("unroll") for (int m = 0; m < 4; ++m) _Pragma("unroll") for (int k = 0; k < 2; ++k) dst[m][k] = *(const LAS bf16x8*)(lds + PG8_SA(b, h) + aoff + m * 2048 + k * 1024); } while (0)
; #define PG8_LDB(dst, b, h) do { _Pragma("unroll") for (int n = 0; n < 2; ++n) _Pragma("unroll") for (int k = 0; k < 2; ++k) dst[n][k] = *(const LAS bf16x8*)(lds + PG8_SB(b, h) + boff + n * 2048 + k * 1024); } while (0)
; #define PG8_MMA(ai, bj, At, Bt) do { __builtin_amdgcn_s_setprio(1); _Pragma("unroll") for (int m = 0; m < 4; ++m) _Pragma("unroll") for (int n = 0; n < 2; ++n) _Pragma("unroll") for (int k = 0; k < 2; ++k) \
;         acc[ai][bj][m][n] = __builtin_amdgcn_mfma_f32_16x16x32_bf16(Bt[n][k], At[m][k], acc[ai][bj][m][n], 0, 0, 0); __builtin_amdgcn_s_setprio(0); } while (0)
; #define PG8_WAIT_V(n) asm volatile("s_waitcnt vmcnt(" #n ")" ::: "memory")
; #define PG8_WAIT_L(n) asm volatile("s_waitcnt lgkmcnt(" #n ")" ::: "memory")
; #define PG8_BAR __builtin_amdgcn_s_barrier()
; #define PG8_SCHED __builtin_amdgcn_sched_barrier(0)
; template <class Epi, class Sched>
; __device__ __forceinline__ void gemm_phase(LAS unsigned char* lds, const int tid, const int ldk, const int Kloop, const Sched& S, const Epi& E) {
;     ...
;             PG8_STAGE(PG8_SB(0, 1), b2 + hstep, voffB);
;             PG8_WAIT_V(6); PG8_BAR; PG8_MMA(1, 1, At, B1); PG8_BAR;
;             PG8_LDB(B0, 1, 0); PG8_SCHED; PG8_LDA(At, 1, 0); PG8_STAGE(PG8_SA(0, 1), a2 + hstep, voffA);
;             PG8_WAIT_L(8); PG8_BAR; PG8_WAIT_L(0); PG8_MMA(0, 0, At, B0); PG8_BAR; PG8_SCHED;
;             PG8_LDB(B1, 1, 1); PG8_STAGE(PG8_SB(1, 0), b3, voffB);
;             PG8_BAR; PG8_WAIT_L(0); PG8_MMA(0, 1, At, B1); PG8_BAR;
;             PG8_LDA(At, 1, 1); PG8_STAGE(PG8_SA(1, 0), a3, voffA);
;             PG8_BAR; PG8_WAIT_L(0); PG8_MMA(1, 0, At, B0); PG8_BAR; PG8_SCHED;
	s_add_u32 s68, s14, 0x80000
	s_addc_u32 s69, s15, 0
	s_add_i32 s67, s70, s27
	v_lshl_add_u64 v[146:147], s[68:69], 0, v[4:5]
	s_mov_b32 m0, s67
	s_nop 0
	global_load_lds_dwordx4 v[146:147], off
	v_lshl_add_u64 v[146:147], s[68:69], 0, v[2:3]
	s_add_i32 m0, s67, 0x2000
	s_nop 0
	global_load_lds_dwordx4 v[146:147], off
	s_waitcnt vmcnt(6)
	s_barrier
	s_setprio 1
	v_mfma_f32_16x16x32_bf16 v[50:53], v[200:203], v[162:165], v[50:53]
	v_mfma_f32_16x16x32_bf16 v[46:49], v[222:225], v[162:165], v[46:49]
	v_mfma_f32_16x16x32_bf16 v[34:37], v[200:203], v[176:179], v[34:37]
	v_mfma_f32_16x16x32_bf16 v[30:33], v[222:225], v[176:179], v[30:33]
	v_mfma_f32_16x16x32_bf16 v[18:21], v[200:203], v[184:187], v[18:21]
	v_mfma_f32_16x16x32_bf16 v[14:17], v[222:225], v[184:187], v[14:17]
	v_mfma_f32_16x16x32_bf16 v[10:13], v[200:203], v[192:195], v[10:13]
	v_mfma_f32_16x16x32_bf16 v[6:9], v[222:225], v[192:195], v[6:9]
	v_mfma_f32_16x16x32_bf16 v[50:53], v[204:207], v[166:169], v[50:53]
	v_mfma_f32_16x16x32_bf16 v[46:49], v[226:229], v[166:169], v[46:49]
	v_mfma_f32_16x16x32_bf16 v[34:37], v[204:207], v[180:183], v[34:37]
	v_mfma_f32_16x16x32_bf16 v[30:33], v[226:229], v[180:183], v[30:33]
	v_mfma_f32_16x16x32_bf16 v[18:21], v[204:207], v[188:191], v[18:21]
	v_mfma_f32_16x16x32_bf16 v[14:17], v[226:229], v[188:191], v[14:17]
	v_mfma_f32_16x16x32_bf16 v[10:13], v[204:207], v[196:199], v[10:13]
	v_mfma_f32_16x16x32_bf16 v[6:9], v[226:229], v[196:199], v[6:9]
	s_setprio 0
	s_add_i32 s67, 0, 0x18000
	v_add_u32_e32 v158, s67, v144
	s_barrier
	ds_read_b128 v[146:149], v158
	ds_read_b128 v[150:153], v158 offset:1024
	ds_read_b128 v[154:157], v158 offset:2048
	ds_read_b128 v[158:161], v158 offset:3072
	s_add_u32 s16, s16, 0x80000
	s_addc_u32 s17, s17, 0
	s_mov_b32 m0, s34
	v_lshl_add_u64 v[200:201], s[16:17], 0, v[136:137]
	ds_read_b128 v[162:165], v145 offset:32768
	ds_read_b128 v[166:169], v145 offset:33792
	ds_read_b128 v[176:179], v145 offset:34816
	ds_read_b128 v[180:183], v145 offset:35840
	ds_read_b128 v[184:187], v145 offset:36864
	ds_read_b128 v[188:191], v145 offset:37888
	ds_read_b128 v[192:195], v145 offset:38912
	ds_read_b128 v[196:199], v145 offset:39936
	global_load_lds_dwordx4 v[200:201], off
	v_lshl_add_u64 v[200:201], s[16:17], 0, v[134:135]
	s_mov_b32 m0, s35
	s_nop 0
	global_load_lds_dwordx4 v[200:201], off
	s_waitcnt lgkmcnt(8)
	s_barrier
	s_waitcnt lgkmcnt(0)
	s_setprio 1
	s_waitcnt lgkmcnt(0)
	v_mfma_f32_16x16x32_bf16 v[130:133], v[146:149], v[162:165], v[130:133]
	v_mfma_f32_16x16x32_bf16 v[126:129], v[154:157], v[162:165], v[126:129]
	v_mfma_f32_16x16x32_bf16 v[122:125], v[146:149], v[176:179], v[122:125]
	v_mfma_f32_16x16x32_bf16 v[118:121], v[154:157], v[176:179], v[118:121]
	v_mfma_f32_16x16x32_bf16 v[106:109], v[146:149], v[184:187], v[106:109]
	v_mfma_f32_16x16x32_bf16 v[102:105], v[154:157], v[184:187], v[102:105]
	v_mfma_f32_16x16x32_bf16 v[90:93], v[146:149], v[192:195], v[90:93]
	v_mfma_f32_16x16x32_bf16 v[86:89], v[154:157], v[192:195], v[86:89]
	v_mfma_f32_16x16x32_bf16 v[130:133], v[150:153], v[166:169], v[130:133]
	v_mfma_f32_16x16x32_bf16 v[126:129], v[158:161], v[166:169], v[126:129]
	v_mfma_f32_16x16x32_bf16 v[122:125], v[150:153], v[180:183], v[122:125]
	v_mfma_f32_16x16x32_bf16 v[118:121], v[158:161], v[180:183], v[118:121]
	v_mfma_f32_16x16x32_bf16 v[106:109], v[150:153], v[188:191], v[106:109]
	v_mfma_f32_16x16x32_bf16 v[102:105], v[158:161], v[188:191], v[102:105]
	v_mfma_f32_16x16x32_bf16 v[90:93], v[150:153], v[196:199], v[90:93]
	v_mfma_f32_16x16x32_bf16 v[86:89], v[158:161], v[196:199], v[86:89]
	s_setprio 0
	s_barrier
	s_add_i32 s16, 0, 0x1c000
	s_add_i32 s17, s67, s27
	v_add_u32_e32 v170, s16, v144
	v_lshl_add_u64 v[172:173], v[172:173], 0, s[42:43]
	s_mov_b32 m0, s17
	ds_read_b128 v[200:203], v170
	ds_read_b128 v[204:207], v170 offset:1024
	ds_read_b128 v[222:225], v170 offset:2048
	ds_read_b128 v[226:229], v170 offset:3072
	global_load_lds_dwordx4 v[172:173], off
	v_lshl_add_u64 v[172:173], v[208:209], 0, s[42:43]
	s_add_i32 m0, s17, 0x2000
	s_nop 0
	global_load_lds_dwordx4 v[172:173], off
	s_barrier
	s_waitcnt lgkmcnt(0)
	s_setprio 1
	s_waitcnt lgkmcnt(0)
	v_mfma_f32_16x16x32_bf16 v[114:117], v[200:203], v[162:165], v[114:117]
	v_mfma_f32_16x16x32_bf16 v[110:113], v[222:225], v[162:165], v[110:113]
	v_mfma_f32_16x16x32_bf16 v[98:101], v[200:203], v[176:179], v[98:101]
	v_mfma_f32_16x16x32_bf16 v[94:97], v[222:225], v[176:179], v[94:97]
	v_mfma_f32_16x16x32_bf16 v[82:85], v[200:203], v[184:187], v[82:85]
	v_mfma_f32_16x16x32_bf16 v[78:81], v[222:225], v[184:187], v[78:81]
	v_mfma_f32_16x16x32_bf16 v[74:77], v[200:203], v[192:195], v[74:77]
	v_mfma_f32_16x16x32_bf16 v[70:73], v[222:225], v[192:195], v[70:73]
	v_mfma_f32_16x16x32_bf16 v[114:117], v[204:207], v[166:169], v[114:117]
	v_mfma_f32_16x16x32_bf16 v[110:113], v[226:229], v[166:169], v[110:113]
	v_mfma_f32_16x16x32_bf16 v[98:101], v[204:207], v[180:183], v[98:101]
	v_mfma_f32_16x16x32_bf16 v[94:97], v[226:229], v[180:183], v[94:97]
	v_mfma_f32_16x16x32_bf16 v[82:85], v[204:207], v[188:191], v[82:85]
	v_mfma_f32_16x16x32_bf16 v[78:81], v[226:229], v[188:191], v[78:81]
	v_mfma_f32_16x16x32_bf16 v[74:77], v[204:207], v[196:199], v[74:77]
	v_mfma_f32_16x16x32_bf16 v[70:73], v[226:229], v[196:199], v[70:73]
	s_setprio 0
	s_mov_b32 m0, s46
	v_lshl_add_u64 v[172:173], v[210:211], 0, s[42:43]
	s_barrier
	ds_read_b128 v[162:165], v145 offset:49152
	ds_read_b128 v[166:169], v145 offset:50176
	ds_read_b128 v[176:179], v145 offset:51200
	ds_read_b128 v[180:183], v145 offset:52224
	ds_read_b128 v[184:187], v145 offset:53248
	ds_read_b128 v[188:191], v145 offset:54272
	ds_read_b128 v[192:195], v145 offset:55296
	ds_read_b128 v[196:199], v145 offset:56320
	global_load_lds_dwordx4 v[172:173], off
	v_lshl_add_u64 v[172:173], v[218:219], 0, s[42:43]
	s_mov_b32 m0, s47
	s_nop 0
	global_load_lds_dwordx4 v[172:173], off
	s_barrier
; #define PG8_STAGE(bufoff, gbase, voff) do { _Pragma("unroll") for (int _i = 0; _i < 2; ++_i) \
;         __builtin_amdgcn_global_load_lds((const unsigned*)((const char*)(gbase) + (voff)[_i]), (LAS unsigned*)(lds + (bufoff) + ldsw + _i * 8192), 16, 0, 0); } while (0)
; #define PG8_MMA(ai, bj, At, Bt) do { __builtin_amdgcn_s_setprio(1); _Pragma("unroll") for (int m = 0; m < 4; ++m) _Pragma("unroll") for (int n = 0; n < 2; ++n) _Pragma("unroll") for (int k = 0; k < 2; ++k) \
;         acc[ai][bj][m][n] = __builtin_amdgcn_mfma_f32_16x16x32_bf16(Bt[n][k], At[m][k], acc[ai][bj][m][n], 0, 0, 0); __builtin_amdgcn_s_setprio(0); } while (0)
; #define PG8_WAIT_V(n) asm volatile("s_waitcnt vmcnt(" #n ")" ::: "memory")
; #define PG8_WAIT_L(n) asm volatile("s_waitcnt lgkmcnt(" #n ")" ::: "memory")
; #define PG8_BAR __builtin_amdgcn_s_barrier()
; #define PG8_SCHED __builtin_amdgcn_sched_barrier(0)
; template <class Epi, class Sched>
; __device__ __forceinline__ void gemm_phase(LAS unsigned char* lds, const int tid, const int ldk, const int Kloop, const Sched& S, const Epi& E) {
;     ...
;             PG8_BAR; PG8_WAIT_L(0); PG8_MMA(1, 0, At, B0); PG8_BAR; PG8_SCHED;
;             PG8_STAGE(PG8_SB(1, 1), b3 + hstep, voffB);
;             PG8_WAIT_V(6); PG8_BAR; PG8_MMA(1, 1, At, B1); PG8_BAR;
;         }
	s_waitcnt lgkmcnt(0)
	s_setprio 1
	s_waitcnt lgkmcnt(0)
	v_mfma_f32_16x16x32_bf16 v[66:69], v[146:149], v[162:165], v[66:69]
	v_mfma_f32_16x16x32_bf16 v[62:65], v[154:157], v[162:165], v[62:65]
	v_mfma_f32_16x16x32_bf16 v[58:61], v[146:149], v[176:179], v[58:61]
	v_mfma_f32_16x16x32_bf16 v[54:57], v[154:157], v[176:179], v[54:57]
	v_mfma_f32_16x16x32_bf16 v[42:45], v[146:149], v[184:187], v[42:45]
	v_mfma_f32_16x16x32_bf16 v[38:41], v[154:157], v[184:187], v[38:41]
	v_mfma_f32_16x16x32_bf16 v[26:29], v[146:149], v[192:195], v[26:29]
	v_mfma_f32_16x16x32_bf16 v[22:25], v[154:157], v[192:195], v[22:25]
	v_mfma_f32_16x16x32_bf16 v[66:69], v[150:153], v[166:169], v[66:69]
	v_mfma_f32_16x16x32_bf16 v[62:65], v[158:161], v[166:169], v[62:65]
	v_mfma_f32_16x16x32_bf16 v[58:61], v[150:153], v[180:183], v[58:61]
	v_mfma_f32_16x16x32_bf16 v[54:57], v[158:161], v[180:183], v[54:57]
	v_mfma_f32_16x16x32_bf16 v[42:45], v[150:153], v[188:191], v[42:45]
	v_mfma_f32_16x16x32_bf16 v[38:41], v[158:161], v[188:191], v[38:41]
	v_mfma_f32_16x16x32_bf16 v[26:29], v[150:153], v[196:199], v[26:29]
	v_mfma_f32_16x16x32_bf16 v[22:25], v[158:161], v[196:199], v[22:25]
	s_setprio 0
	s_barrier
	s_add_u32 s14, s14, 0x80080
	s_addc_u32 s15, s15, 0
	s_add_i32 s16, s16, s27
	v_lshl_add_u64 v[146:147], s[14:15], 0, v[4:5]
	s_mov_b32 m0, s16
	s_nop 0
	global_load_lds_dwordx4 v[146:147], off
	v_lshl_add_u64 v[146:147], s[14:15], 0, v[2:3]
	s_add_i32 m0, s16, 0x2000
	s_nop 0
	global_load_lds_dwordx4 v[146:147], off
	s_waitcnt vmcnt(6)
	s_barrier
	s_setprio 1
	v_mfma_f32_16x16x32_bf16 v[50:53], v[200:203], v[162:165], v[50:53]
	v_mfma_f32_16x16x32_bf16 v[46:49], v[222:225], v[162:165], v[46:49]
	v_mfma_f32_16x16x32_bf16 v[34:37], v[200:203], v[176:179], v[34:37]
	v_mfma_f32_16x16x32_bf16 v[30:33], v[222:225], v[176:179], v[30:33]
	v_mfma_f32_16x16x32_bf16 v[18:21], v[200:203], v[184:187], v[18:21]
	v_mfma_f32_16x16x32_bf16 v[14:17], v[222:225], v[184:187], v[14:17]
	v_mfma_f32_16x16x32_bf16 v[10:13], v[200:203], v[192:195], v[10:13]
	v_mfma_f32_16x16x32_bf16 v[6:9], v[222:225], v[192:195], v[6:9]
	v_mfma_f32_16x16x32_bf16 v[50:53], v[204:207], v[166:169], v[50:53]
	v_mfma_f32_16x16x32_bf16 v[46:49], v[226:229], v[166:169], v[46:49]
	v_mfma_f32_16x16x32_bf16 v[34:37], v[204:207], v[180:183], v[34:37]
	v_mfma_f32_16x16x32_bf16 v[30:33], v[226:229], v[180:183], v[30:33]
	v_mfma_f32_16x16x32_bf16 v[18:21], v[204:207], v[188:191], v[18:21]
	v_mfma_f32_16x16x32_bf16 v[14:17], v[226:229], v[188:191], v[14:17]
	v_mfma_f32_16x16x32_bf16 v[10:13], v[204:207], v[196:199], v[10:13]
	v_mfma_f32_16x16x32_bf16 v[6:9], v[226:229], v[196:199], v[6:9]
	s_setprio 0
	s_add_i32 s66, s66, 2
	s_add_u32 s12, s12, 0x100
	s_addc_u32 s13, s13, 0
	s_add_u32 s56, s56, 0x100
	s_addc_u32 s57, s57, 0
	s_cmp_gt_u32 s66, 5
	s_barrier
	s_cbranch_scc0 .LBB0_523
; __device__ __forceinline__ unsigned pk2(float lo, float hi) { const bf2_t r = __builtin_convertvector((f32x2){lo, hi}, bf2_t); unsigned u; __builtin_memcpy(&u, &r, 4); return u; }
; #define PG8_WAIT_V(n) asm volatile("s_waitcnt vmcnt(" #n ")" ::: "memory")
; #define PG8_BAR __builtin_amdgcn_s_barrier()
;     __device__ __forceinline__ void operator()(const f32x4 (&acc)[2][2][4][2], const Unit& u, int wr, int wc, int fr, int fq) const {
;     ...
;         for (int ai = 0; ai < 2; ++ai)
; #pragma unroll
;             for (int m = 0; m < 4; ++m) { bf16_t* rowp = base + (size_t)(ai * HALF + wr * 64 + m * 16 + fr) * u.ldc + wc * 32 + 8 * fq;
; #pragma unroll
;                 for (int bj = 0; bj < 2; ++bj) { const f32x4 v0 = acc[ai][bj][m][0], v1 = acc[ai][bj][m][1];
;                     u32x4 w; w.x = pk2(v0[0], v0[1]); w.y = pk2(v0[2], v0[3]); w.z = pk2(v1[0], v1[1]); w.w = pk2(v1[2], v1[3]);
;                     *(u32x4*)(rowp + bj * HALF) = w; } }
; template <class Epi, class Sched>
; __device__ __forceinline__ void gemm_phase(LAS unsigned char* lds, const int tid, const int ldk, const int Kloop, const Sched& S, const Epi& E) {
;     ...
;         if (!has_next) break;
; #pragma unroll
;         for (int a = 0; a < 2; ++a)
; #pragma unroll
;             for (int b = 0; b < 2; ++b)
; #pragma unroll
;                 for (int m = 0; m < 4; ++m)
; #pragma unroll
;                     for (int n = 0; n < 2; ++n) acc[a][b][m][n] = (f32x4){0.f, 0.f, 0.f, 0.f};
;         cur = nxt; cA = nA; cB = nB; ++ui;
;     }
;     PG8_WAIT_V(0);
;     if (wr == 0) PG8_BAR;
	v_mov_b32_e32 v146, v142
	v_mov_b32_e32 v147, v143
	s_add_u32 s10, s10, s55
	v_add_u32_e32 v146, s45, v146
	v_lshlrev_b32_e32 v148, 3, v147
	v_cvt_pk_bf16_f32 v74, v74, v75
	v_cvt_pk_bf16_f32 v75, v76, v77
	v_cvt_pk_bf16_f32 v76, v70, v71
	v_add_u32_e32 v70, 0x80, v146
	s_addc_u32 s11, s11, 0
	v_ashrrev_i32_e32 v149, 31, v148
	v_ashrrev_i32_e32 v147, 31, v146
	v_cvt_pk_bf16_f32 v114, v114, v115
	v_cvt_pk_bf16_f32 v115, v116, v117
	v_cvt_pk_bf16_f32 v116, v110, v111
	v_add_u32_e32 v110, 16, v146
	v_ashrrev_i32_e32 v71, 31, v70
	v_cvt_pk_bf16_f32 v50, v50, v51
	v_cvt_pk_bf16_f32 v51, v52, v53
	v_cvt_pk_bf16_f32 v52, v46, v47
	v_add_u32_e32 v46, 0x90, v146
	v_lshl_add_u64 v[148:149], v[148:149], 1, s[10:11]
	v_lshlrev_b64 v[150:151], 11, v[146:147]
	v_ashrrev_i32_e32 v111, 31, v110
	v_cvt_pk_bf16_f32 v98, v98, v99
	v_cvt_pk_bf16_f32 v99, v100, v101
	v_cvt_pk_bf16_f32 v100, v94, v95
	v_add_u32_e32 v94, 32, v146
	v_lshlrev_b64 v[70:71], 11, v[70:71]
	v_ashrrev_i32_e32 v47, 31, v46
	v_cvt_pk_bf16_f32 v34, v34, v35
	v_cvt_pk_bf16_f32 v35, v36, v37
	v_cvt_pk_bf16_f32 v36, v30, v31
	v_add_u32_e32 v30, 0xa0, v146
	v_lshl_add_u64 v[150:151], v[148:149], 0, v[150:151]
	v_cvt_pk_bf16_f32 v117, v112, v113
	v_lshlrev_b64 v[110:111], 11, v[110:111]
	v_ashrrev_i32_e32 v95, 31, v94
	v_cvt_pk_bf16_f32 v82, v82, v83
	v_cvt_pk_bf16_f32 v83, v84, v85
	v_cvt_pk_bf16_f32 v84, v78, v79
	v_add_u32_e32 v78, 48, v146
	v_lshl_add_u64 v[70:71], v[148:149], 0, v[70:71]
	v_cvt_pk_bf16_f32 v53, v48, v49
	v_lshlrev_b64 v[46:47], 11, v[46:47]
	v_ashrrev_i32_e32 v31, 31, v30
	v_cvt_pk_bf16_f32 v18, v18, v19
	v_cvt_pk_bf16_f32 v19, v20, v21
	v_cvt_pk_bf16_f32 v20, v14, v15
	v_add_u32_e32 v14, 0xb0, v146
	global_store_dwordx4 v[150:151], v[114:117], off offset:256
	v_cvt_pk_bf16_f32 v101, v96, v97
	v_lshlrev_b64 v[94:95], 11, v[94:95]
	v_lshl_add_u64 v[114:115], v[148:149], 0, v[110:111]
	v_ashrrev_i32_e32 v79, 31, v78
	global_store_dwordx4 v[70:71], v[50:53], off offset:256
	v_cvt_pk_bf16_f32 v37, v32, v33
	v_lshlrev_b64 v[30:31], 11, v[30:31]
	v_lshl_add_u64 v[50:51], v[148:149], 0, v[46:47]
	v_ashrrev_i32_e32 v15, 31, v14
	global_store_dwordx4 v[114:115], v[98:101], off offset:256
	v_cvt_pk_bf16_f32 v85, v80, v81
	v_lshlrev_b64 v[78:79], 11, v[78:79]
	v_lshl_add_u64 v[98:99], v[148:149], 0, v[94:95]
	global_store_dwordx4 v[50:51], v[34:37], off offset:256
	v_cvt_pk_bf16_f32 v21, v16, v17
	v_lshlrev_b64 v[14:15], 11, v[14:15]
	v_lshl_add_u64 v[34:35], v[148:149], 0, v[30:31]
	v_cvt_pk_bf16_f32 v130, v130, v131
	v_cvt_pk_bf16_f32 v131, v132, v133
	v_cvt_pk_bf16_f32 v132, v126, v127
	v_cvt_pk_bf16_f32 v133, v128, v129
	v_cvt_pk_bf16_f32 v110, v122, v123
	v_cvt_pk_bf16_f32 v111, v124, v125
	v_cvt_pk_bf16_f32 v112, v118, v119
	v_cvt_pk_bf16_f32 v113, v120, v121
	v_cvt_pk_bf16_f32 v94, v106, v107
	v_cvt_pk_bf16_f32 v95, v108, v109
	v_cvt_pk_bf16_f32 v96, v102, v103
	v_cvt_pk_bf16_f32 v97, v104, v105
	global_store_dwordx4 v[98:99], v[82:85], off offset:256
	v_cvt_pk_bf16_f32 v80, v86, v87
	v_cvt_pk_bf16_f32 v81, v88, v89
	v_lshl_add_u64 v[82:83], v[148:149], 0, v[78:79]
	v_cvt_pk_bf16_f32 v78, v90, v91
	v_cvt_pk_bf16_f32 v79, v92, v93
	v_cvt_pk_bf16_f32 v77, v72, v73
	v_cvt_pk_bf16_f32 v66, v66, v67
	v_cvt_pk_bf16_f32 v67, v68, v69
	v_cvt_pk_bf16_f32 v68, v62, v63
	v_cvt_pk_bf16_f32 v69, v64, v65
	v_cvt_pk_bf16_f32 v46, v58, v59
	v_cvt_pk_bf16_f32 v47, v60, v61
	v_cvt_pk_bf16_f32 v48, v54, v55
	v_cvt_pk_bf16_f32 v49, v56, v57
	v_cvt_pk_bf16_f32 v30, v42, v43
	v_cvt_pk_bf16_f32 v31, v44, v45
	v_cvt_pk_bf16_f32 v32, v38, v39
	v_cvt_pk_bf16_f32 v33, v40, v41
	global_store_dwordx4 v[34:35], v[18:21], off offset:256
	v_cvt_pk_bf16_f32 v16, v22, v23
	v_cvt_pk_bf16_f32 v17, v24, v25
	v_lshl_add_u64 v[18:19], v[148:149], 0, v[14:15]
	v_cvt_pk_bf16_f32 v14, v26, v27
	v_cvt_pk_bf16_f32 v15, v28, v29
	v_cvt_pk_bf16_f32 v10, v10, v11
	v_cvt_pk_bf16_f32 v11, v12, v13
	v_cvt_pk_bf16_f32 v12, v6, v7
	v_cvt_pk_bf16_f32 v13, v8, v9
	s_and_b64 vcc, exec, s[6:7]
	s_mov_b64 s[10:11], s[8:9]
	s_mov_b64 s[14:15], s[4:5]
	s_mov_b64 s[12:13], s[2:3]
	global_store_dwordx4 v[150:151], v[130:133], off
	global_store_dwordx4 v[114:115], v[110:113], off
	global_store_dwordx4 v[98:99], v[94:97], off
	global_store_dwordx4 v[82:83], v[78:81], off
	global_store_dwordx4 v[82:83], v[74:77], off offset:256
	global_store_dwordx4 v[70:71], v[66:69], off
	global_store_dwordx4 v[50:51], v[46:49], off
	global_store_dwordx4 v[34:35], v[30:33], off
	global_store_dwordx4 v[18:19], v[14:17], off
	global_store_dwordx4 v[18:19], v[10:13], off offset:256
	s_cbranch_vccz .LBB0_520
	s_cmp_eq_u32 s100, 1
	s_cbranch_scc1 .Lg_inv_done_2
	s_mov_b32 s100, 1
	v_readfirstlane_b32 s98, v217
	s_cmp_lt_u32 s98, 0x1c0
	s_cbranch_scc1 .Lg_inv_done_2
	buffer_inv sc1

; #define PG8_STAGE(bufoff, gbase, voff) do { _Pragma("unroll") for (int _i = 0; _i < 2; ++_i) \
;         __builtin_amdgcn_global_load_lds((const unsigned*)((const char*)(gbase) + (voff)[_i]), (LAS unsigned*)(lds + (bufoff) + ldsw + _i * 8192), 16, 0, 0); } while (0)
; #define PG8_LDA(dst, b, h) do { _Pragma("unroll") for (int m = 0; m < 4; ++m) _Pragma("unroll") for (int k = 0; k < 2; ++k) dst[m][k] = *(const LAS bf16x8*)(lds + PG8_SA(b, h) + aoff + m * 2048 + k * 1024); } while (0)
; #define PG8_LDB(dst, b, h) do { _Pragma("unroll") for (int n = 0; n < 2; ++n) _Pragma("unroll") for (int k = 0; k < 2; ++k) dst[n][k] = *(const LAS bf16x8*)(lds + PG8_SB(b, h) + boff + n * 2048 + k * 1024); } while (0)
; #define PG8_MMA(ai, bj, At, Bt) do { __builtin_amdgcn_s_setprio(1); _Pragma("unroll") for (int m = 0; m < 4; ++m) _Pragma("unroll") for (int n = 0; n < 2; ++n) _Pragma("unroll") for (int k = 0; k < 2; ++k) \
;         acc[ai][bj][m][n] = __builtin_amdgcn_mfma_f32_16x16x32_bf16(Bt[n][k], At[m][k], acc[ai][bj][m][n], 0, 0, 0); __builtin_amdgcn_s_setprio(0); } while (0)
; #define PG8_WAIT_L(n) asm volatile("s_waitcnt lgkmcnt(" #n ")" ::: "memory")
; #define PG8_BAR __builtin_amdgcn_s_barrier()
; #define PG8_SCHED __builtin_amdgcn_sched_barrier(0)
; template <class Epi, class Sched>
; __device__ __forceinline__ void gemm_phase(LAS unsigned char* lds, const int tid, const int ldk, const int Kloop, const Sched& S, const Epi& E) {
;     ...
;         for (int t = 0; t < nt; t += 2) {
;             const bool last = (t == nt - 2);
;             const char* a1 = cA + (size_t)(t + 1) * kstep;
;             const char* a2 = last ? nA : cA + (size_t)(t + 2) * kstep; const char* b2 = last ? nB : cB + (size_t)(t + 2) * kstep;
;             const char* a3 = a2 + kstep; const char* b3 = b2 + kstep;
;             PG8_LDB(B0, 0, 0); PG8_SCHED; PG8_LDA(At, 0, 0); PG8_STAGE(PG8_SA(1, 1), a1 + hstep, voffA);
;             PG8_WAIT_L(8); PG8_BAR; PG8_WAIT_L(0); PG8_MMA(0, 0, At, B0); PG8_BAR; PG8_SCHED;
;             PG8_LDB(B1, 0, 1); PG8_STAGE(PG8_SB(0, 0), b2, voffB);
;             PG8_BAR; PG8_WAIT_L(0); PG8_MMA(0, 1, At, B1); PG8_BAR;
;             PG8_LDA(At, 0, 1); PG8_STAGE(PG8_SA(0, 0), a2, voffA);
;             PG8_BAR; PG8_WAIT_L(0); PG8_MMA(1, 0, At, B0); PG8_BAR; PG8_SCHED;
.LBB0_654:
	s_add_u32 s14, s12, 0xfffc0080
	s_addc_u32 s15, s13, -1
	s_add_i32 s69, 0, 0x10000
	v_add_u32_e32 v158, s69, v144
	ds_read_b128 v[146:149], v158
	ds_read_b128 v[150:153], v158 offset:1024
	ds_read_b128 v[154:157], v158 offset:2048
	ds_read_b128 v[158:161], v158 offset:3072
	s_cmp_eq_u32 s68, 12
	s_cselect_b32 s17, s7, s15
	s_cselect_b32 s16, s6, s14
	s_cselect_b32 s15, s9, s67
	s_cselect_b32 s14, s8, s66
	v_lshl_add_u64 v[172:173], s[12:13], 0, v[138:139]
	s_add_i32 m0, s35, 0xc000
	ds_read_b128 v[162:165], v145
	ds_read_b128 v[166:169], v145 offset:1024
	ds_read_b128 v[176:179], v145 offset:2048
	ds_read_b128 v[180:183], v145 offset:3072
	ds_read_b128 v[184:187], v145 offset:4096
	ds_read_b128 v[188:191], v145 offset:5120
	ds_read_b128 v[192:195], v145 offset:6144
	ds_read_b128 v[196:199], v145 offset:7168
	global_load_lds_dwordx4 v[172:173], off
	v_lshl_add_u64 v[172:173], s[12:13], 0, v[140:141]
	s_add_i32 m0, s35, 0xe000
	s_nop 0
	global_load_lds_dwordx4 v[172:173], off
	s_waitcnt lgkmcnt(8)
	s_barrier
	s_waitcnt lgkmcnt(0)
	s_setprio 1
	s_waitcnt lgkmcnt(0)
	v_mfma_f32_16x16x32_bf16 v[130:133], v[146:149], v[162:165], v[130:133]
	v_mfma_f32_16x16x32_bf16 v[126:129], v[154:157], v[162:165], v[126:129]
	v_mfma_f32_16x16x32_bf16 v[122:125], v[146:149], v[176:179], v[122:125]
	v_mfma_f32_16x16x32_bf16 v[118:121], v[154:157], v[176:179], v[118:121]
	v_mfma_f32_16x16x32_bf16 v[106:109], v[146:149], v[184:187], v[106:109]
	v_mfma_f32_16x16x32_bf16 v[102:105], v[154:157], v[184:187], v[102:105]
	v_mfma_f32_16x16x32_bf16 v[90:93], v[146:149], v[192:195], v[90:93]
	v_mfma_f32_16x16x32_bf16 v[86:89], v[154:157], v[192:195], v[86:89]
	v_mfma_f32_16x16x32_bf16 v[130:133], v[150:153], v[166:169], v[130:133]
	v_mfma_f32_16x16x32_bf16 v[126:129], v[158:161], v[166:169], v[126:129]
	v_mfma_f32_16x16x32_bf16 v[122:125], v[150:153], v[180:183], v[122:125]
	v_mfma_f32_16x16x32_bf16 v[118:121], v[158:161], v[180:183], v[118:121]
	v_mfma_f32_16x16x32_bf16 v[106:109], v[150:153], v[188:191], v[106:109]
	v_mfma_f32_16x16x32_bf16 v[102:105], v[158:161], v[188:191], v[102:105]
	v_mfma_f32_16x16x32_bf16 v[90:93], v[150:153], v[196:199], v[90:93]
	v_mfma_f32_16x16x32_bf16 v[86:89], v[158:161], v[196:199], v[86:89]
	s_setprio 0
	s_barrier
	s_add_i32 s72, 0, 0x14000
	s_add_i32 s69, s69, s34
	v_add_u32_e32 v170, s72, v144
	v_lshl_add_u64 v[172:173], s[14:15], 0, v[4:5]
	s_mov_b32 m0, s69
	ds_read_b128 v[200:203], v170
	ds_read_b128 v[204:207], v170 offset:1024
	ds_read_b128 v[222:225], v170 offset:2048
	ds_read_b128 v[226:229], v170 offset:3072
	global_load_lds_dwordx4 v[172:173], off
	v_lshl_add_u64 v[208:209], s[14:15], 0, v[136:137]
	s_add_i32 m0, s69, 0x2000
	s_nop 0
	global_load_lds_dwordx4 v[208:209], off
	s_barrier
	s_waitcnt lgkmcnt(0)
	s_setprio 1
	s_waitcnt lgkmcnt(0)
	v_mfma_f32_16x16x32_bf16 v[114:117], v[200:203], v[162:165], v[114:117]
	v_mfma_f32_16x16x32_bf16 v[110:113], v[222:225], v[162:165], v[110:113]
	v_mfma_f32_16x16x32_bf16 v[98:101], v[200:203], v[176:179], v[98:101]
	v_mfma_f32_16x16x32_bf16 v[94:97], v[222:225], v[176:179], v[94:97]
	v_mfma_f32_16x16x32_bf16 v[82:85], v[200:203], v[184:187], v[82:85]
	v_mfma_f32_16x16x32_bf16 v[78:81], v[222:225], v[184:187], v[78:81]
	v_mfma_f32_16x16x32_bf16 v[74:77], v[200:203], v[192:195], v[74:77]
	v_mfma_f32_16x16x32_bf16 v[70:73], v[222:225], v[192:195], v[70:73]
	v_mfma_f32_16x16x32_bf16 v[114:117], v[204:207], v[166:169], v[114:117]
	v_mfma_f32_16x16x32_bf16 v[110:113], v[226:229], v[166:169], v[110:113]
	v_mfma_f32_16x16x32_bf16 v[98:101], v[204:207], v[180:183], v[98:101]
	v_mfma_f32_16x16x32_bf16 v[94:97], v[226:229], v[180:183], v[94:97]
	v_mfma_f32_16x16x32_bf16 v[82:85], v[204:207], v[188:191], v[82:85]
	v_mfma_f32_16x16x32_bf16 v[78:81], v[226:229], v[188:191], v[78:81]
	v_mfma_f32_16x16x32_bf16 v[74:77], v[204:207], v[196:199], v[74:77]
	v_mfma_f32_16x16x32_bf16 v[70:73], v[226:229], v[196:199], v[70:73]
	s_setprio 0
	s_mov_b32 m0, s35
	v_lshl_add_u64 v[210:211], s[16:17], 0, v[2:3]
	s_barrier
	ds_read_b128 v[162:165], v145 offset:16384
	ds_read_b128 v[166:169], v145 offset:17408
	ds_read_b128 v[176:179], v145 offset:18432
	ds_read_b128 v[180:183], v145 offset:19456
	ds_read_b128 v[184:187], v145 offset:20480
	ds_read_b128 v[188:191], v145 offset:21504
	ds_read_b128 v[192:195], v145 offset:22528
	ds_read_b128 v[196:199], v145 offset:23552
	global_load_lds_dwordx4 v[210:211], off
	v_lshl_add_u64 v[218:219], s[16:17], 0, v[134:135]
	s_mov_b32 m0, s39
	s_nop 0
	global_load_lds_dwordx4 v[218:219], off
	s_barrier
	s_waitcnt lgkmcnt(0)
	s_setprio 1
	s_waitcnt lgkmcnt(0)
	v_mfma_f32_16x16x32_bf16 v[66:69], v[146:149], v[162:165], v[66:69]
	v_mfma_f32_16x16x32_bf16 v[62:65], v[154:157], v[162:165], v[62:65]
	v_mfma_f32_16x16x32_bf16 v[58:61], v[146:149], v[176:179], v[58:61]
	v_mfma_f32_16x16x32_bf16 v[54:57], v[154:157], v[176:179], v[54:57]
	v_mfma_f32_16x16x32_bf16 v[42:45], v[146:149], v[184:187], v[42:45]
	v_mfma_f32_16x16x32_bf16 v[38:41], v[154:157], v[184:187], v[38:41]
	v_mfma_f32_16x16x32_bf16 v[26:29], v[146:149], v[192:195], v[26:29]
	v_mfma_f32_16x16x32_bf16 v[22:25], v[154:157], v[192:195], v[22:25]
	v_mfma_f32_16x16x32_bf16 v[66:69], v[150:153], v[166:169], v[66:69]
	v_mfma_f32_16x16x32_bf16 v[62:65], v[158:161], v[166:169], v[62:65]
	v_mfma_f32_16x16x32_bf16 v[58:61], v[150:153], v[180:183], v[58:61]
	v_mfma_f32_16x16x32_bf16 v[54:57], v[158:161], v[180:183], v[54:57]
	v_mfma_f32_16x16x32_bf16 v[42:45], v[150:153], v[188:191], v[42:45]
	v_mfma_f32_16x16x32_bf16 v[38:41], v[158:161], v[188:191], v[38:41]
	v_mfma_f32_16x16x32_bf16 v[26:29], v[150:153], v[196:199], v[26:29]
	v_mfma_f32_16x16x32_bf16 v[22:25], v[158:161], v[196:199], v[22:25]
	s_setprio 0
	s_barrier
; #define PG8_STAGE(bufoff, gbase, voff) do { _Pragma("unroll") for (int _i = 0; _i < 2; ++_i) \
;         __builtin_amdgcn_global_load_lds((const unsigned*)((const char*)(gbase) + (voff)[_i]), (LAS unsigned*)(lds + (bufoff) + ldsw + _i * 8192), 16, 0, 0); } while (0)
; #define PG8_LDA(dst, b, h) do { _Pragma("unroll") for (int m = 0; m < 4; ++m) _Pragma("unroll") for (int k = 0; k < 2; ++k) dst[m][k] = *(const LAS bf16x8*)(lds + PG8_SA(b, h) + aoff + m * 2048 + k * 1024); } while (0)
; #define PG8_LDB(dst, b, h) do { _Pragma("unroll") for (int n = 0; n < 2; ++n) _Pragma("unroll") for (int k = 0; k < 2; ++k) dst[n][k] = *(const LAS bf16x8*)(lds + PG8_SB(b, h) + boff + n * 2048 + k * 1024); } while (0)
; #define PG8_MMA(ai, bj, At, Bt) do { __builtin_amdgcn_s_setprio(1); _Pragma("unroll") for (int m = 0; m < 4; ++m) _Pragma("unroll") for (int n = 0; n < 2; ++n) _Pragma("unroll") for (int k = 0; k < 2; ++k) \
;         acc[ai][bj][m][n] = __builtin_amdgcn_mfma_f32_16x16x32_bf16(Bt[n][k], At[m][k], acc[ai][bj][m][n], 0, 0, 0); __builtin_amdgcn_s_setprio(0); } while (0)
; #define PG8_WAIT_V(n) asm volatile("s_waitcnt vmcnt(" #n ")" ::: "memory")
; #define PG8_WAIT_L(n) asm volatile("s_waitcnt lgkmcnt(" #n ")" ::: "memory")
; #define PG8_BAR __builtin_amdgcn_s_barrier()
; #define PG8_SCHED __builtin_amdgcn_sched_barrier(0)
; template <class Epi, class Sched>
; __device__ __forceinline__ void gemm_phase(LAS unsigned char* lds, const int tid, const int ldk, const int Kloop, const Sched& S, const Epi& E) {
;     ...
;             PG8_STAGE(PG8_SB(0, 1), b2 + hstep, voffB);
;             PG8_WAIT_V(6); PG8_BAR; PG8_MMA(1, 1, At, B1); PG8_BAR;
;             PG8_LDB(B0, 1, 0); PG8_SCHED; PG8_LDA(At, 1, 0); PG8_STAGE(PG8_SA(0, 1), a2 + hstep, voffA);
;             PG8_WAIT_L(8); PG8_BAR; PG8_WAIT_L(0); PG8_MMA(0, 0, At, B0); PG8_BAR; PG8_SCHED;
;             PG8_LDB(B1, 1, 1); PG8_STAGE(PG8_SB(1, 0), b3, voffB);
;             PG8_BAR; PG8_WAIT_L(0); PG8_MMA(0, 1, At, B1); PG8_BAR;
;             PG8_LDA(At, 1, 1); PG8_STAGE(PG8_SA(1, 0), a3, voffA);
;             PG8_BAR; PG8_WAIT_L(0); PG8_MMA(1, 0, At, B0); PG8_BAR; PG8_SCHED;
	s_add_u32 s70, s14, 0x40000
	s_addc_u32 s71, s15, 0
	s_add_i32 s69, s72, s34
	v_lshl_add_u64 v[146:147], s[70:71], 0, v[4:5]
	s_mov_b32 m0, s69
	s_nop 0
	global_load_lds_dwordx4 v[146:147], off
	v_lshl_add_u64 v[146:147], s[70:71], 0, v[136:137]
	s_add_i32 m0, s69, 0x2000
	s_nop 0
	global_load_lds_dwordx4 v[146:147], off
	s_waitcnt vmcnt(6)
	s_barrier
	s_setprio 1
	v_mfma_f32_16x16x32_bf16 v[50:53], v[200:203], v[162:165], v[50:53]
	v_mfma_f32_16x16x32_bf16 v[46:49], v[222:225], v[162:165], v[46:49]
	v_mfma_f32_16x16x32_bf16 v[34:37], v[200:203], v[176:179], v[34:37]
	v_mfma_f32_16x16x32_bf16 v[30:33], v[222:225], v[176:179], v[30:33]
	v_mfma_f32_16x16x32_bf16 v[18:21], v[200:203], v[184:187], v[18:21]
	v_mfma_f32_16x16x32_bf16 v[14:17], v[222:225], v[184:187], v[14:17]
	v_mfma_f32_16x16x32_bf16 v[10:13], v[200:203], v[192:195], v[10:13]
	v_mfma_f32_16x16x32_bf16 v[6:9], v[222:225], v[192:195], v[6:9]
	v_mfma_f32_16x16x32_bf16 v[50:53], v[204:207], v[166:169], v[50:53]
	v_mfma_f32_16x16x32_bf16 v[46:49], v[226:229], v[166:169], v[46:49]
	v_mfma_f32_16x16x32_bf16 v[34:37], v[204:207], v[180:183], v[34:37]
	v_mfma_f32_16x16x32_bf16 v[30:33], v[226:229], v[180:183], v[30:33]
	v_mfma_f32_16x16x32_bf16 v[18:21], v[204:207], v[188:191], v[18:21]
	v_mfma_f32_16x16x32_bf16 v[14:17], v[226:229], v[188:191], v[14:17]
	v_mfma_f32_16x16x32_bf16 v[10:13], v[204:207], v[196:199], v[10:13]
	v_mfma_f32_16x16x32_bf16 v[6:9], v[226:229], v[196:199], v[6:9]
	s_setprio 0
	s_add_i32 s69, 0, 0x18000
	v_add_u32_e32 v158, s69, v144
	s_barrier
	ds_read_b128 v[146:149], v158
	ds_read_b128 v[150:153], v158 offset:1024
	ds_read_b128 v[154:157], v158 offset:2048
	ds_read_b128 v[158:161], v158 offset:3072
	s_add_u32 s16, s16, 0x40000
	s_addc_u32 s17, s17, 0
	s_mov_b32 m0, s40
	v_lshl_add_u64 v[200:201], s[16:17], 0, v[2:3]
	ds_read_b128 v[162:165], v145 offset:32768
	ds_read_b128 v[166:169], v145 offset:33792
	ds_read_b128 v[176:179], v145 offset:34816
	ds_read_b128 v[180:183], v145 offset:35840
	ds_read_b128 v[184:187], v145 offset:36864
	ds_read_b128 v[188:191], v145 offset:37888
	ds_read_b128 v[192:195], v145 offset:38912
	ds_read_b128 v[196:199], v145 offset:39936
	global_load_lds_dwordx4 v[200:201], off
	v_lshl_add_u64 v[200:201], s[16:17], 0, v[134:135]
	s_mov_b32 m0, s45
	s_nop 0
	global_load_lds_dwordx4 v[200:201], off
	s_waitcnt lgkmcnt(8)
	s_barrier
	s_waitcnt lgkmcnt(0)
	s_setprio 1
	s_waitcnt lgkmcnt(0)
	v_mfma_f32_16x16x32_bf16 v[130:133], v[146:149], v[162:165], v[130:133]
	v_mfma_f32_16x16x32_bf16 v[126:129], v[154:157], v[162:165], v[126:129]
	v_mfma_f32_16x16x32_bf16 v[122:125], v[146:149], v[176:179], v[122:125]
	v_mfma_f32_16x16x32_bf16 v[118:121], v[154:157], v[176:179], v[118:121]
	v_mfma_f32_16x16x32_bf16 v[106:109], v[146:149], v[184:187], v[106:109]
	v_mfma_f32_16x16x32_bf16 v[102:105], v[154:157], v[184:187], v[102:105]
	v_mfma_f32_16x16x32_bf16 v[90:93], v[146:149], v[192:195], v[90:93]
	v_mfma_f32_16x16x32_bf16 v[86:89], v[154:157], v[192:195], v[86:89]
	v_mfma_f32_16x16x32_bf16 v[130:133], v[150:153], v[166:169], v[130:133]
	v_mfma_f32_16x16x32_bf16 v[126:129], v[158:161], v[166:169], v[126:129]
	v_mfma_f32_16x16x32_bf16 v[122:125], v[150:153], v[180:183], v[122:125]
	v_mfma_f32_16x16x32_bf16 v[118:121], v[158:161], v[180:183], v[118:121]
	v_mfma_f32_16x16x32_bf16 v[106:109], v[150:153], v[188:191], v[106:109]
	v_mfma_f32_16x16x32_bf16 v[102:105], v[158:161], v[188:191], v[102:105]
	v_mfma_f32_16x16x32_bf16 v[90:93], v[150:153], v[196:199], v[90:93]
	v_mfma_f32_16x16x32_bf16 v[86:89], v[158:161], v[196:199], v[86:89]
	s_setprio 0
	s_barrier
	s_add_i32 s16, 0, 0x1c000
	s_add_i32 s17, s69, s34
	v_add_u32_e32 v170, s16, v144
	v_lshl_add_u64 v[172:173], v[172:173], 0, s[42:43]
	s_mov_b32 m0, s17
	ds_read_b128 v[200:203], v170
	ds_read_b128 v[204:207], v170 offset:1024
	ds_read_b128 v[222:225], v170 offset:2048
	ds_read_b128 v[226:229], v170 offset:3072
	global_load_lds_dwordx4 v[172:173], off
	v_lshl_add_u64 v[172:173], v[208:209], 0, s[42:43]
	s_add_i32 m0, s17, 0x2000
	s_nop 0
	global_load_lds_dwordx4 v[172:173], off
	s_barrier
	s_waitcnt lgkmcnt(0)
	s_setprio 1
	s_waitcnt lgkmcnt(0)
	v_mfma_f32_16x16x32_bf16 v[114:117], v[200:203], v[162:165], v[114:117]
	v_mfma_f32_16x16x32_bf16 v[110:113], v[222:225], v[162:165], v[110:113]
	v_mfma_f32_16x16x32_bf16 v[98:101], v[200:203], v[176:179], v[98:101]
	v_mfma_f32_16x16x32_bf16 v[94:97], v[222:225], v[176:179], v[94:97]
	v_mfma_f32_16x16x32_bf16 v[82:85], v[200:203], v[184:187], v[82:85]
	v_mfma_f32_16x16x32_bf16 v[78:81], v[222:225], v[184:187], v[78:81]
	v_mfma_f32_16x16x32_bf16 v[74:77], v[200:203], v[192:195], v[74:77]
	v_mfma_f32_16x16x32_bf16 v[70:73], v[222:225], v[192:195], v[70:73]
	v_mfma_f32_16x16x32_bf16 v[114:117], v[204:207], v[166:169], v[114:117]
	v_mfma_f32_16x16x32_bf16 v[110:113], v[226:229], v[166:169], v[110:113]
	v_mfma_f32_16x16x32_bf16 v[98:101], v[204:207], v[180:183], v[98:101]
	v_mfma_f32_16x16x32_bf16 v[94:97], v[226:229], v[180:183], v[94:97]
	v_mfma_f32_16x16x32_bf16 v[82:85], v[204:207], v[188:191], v[82:85]
	v_mfma_f32_16x16x32_bf16 v[78:81], v[226:229], v[188:191], v[78:81]
	v_mfma_f32_16x16x32_bf16 v[74:77], v[204:207], v[196:199], v[74:77]
	v_mfma_f32_16x16x32_bf16 v[70:73], v[226:229], v[196:199], v[70:73]
	s_setprio 0
	s_mov_b32 m0, s47
	v_lshl_add_u64 v[172:173], v[210:211], 0, s[42:43]
	s_barrier
	ds_read_b128 v[162:165], v145 offset:49152
	ds_read_b128 v[166:169], v145 offset:50176
	ds_read_b128 v[176:179], v145 offset:51200
	ds_read_b128 v[180:183], v145 offset:52224
	ds_read_b128 v[184:187], v145 offset:53248
	ds_read_b128 v[188:191], v145 offset:54272
	ds_read_b128 v[192:195], v145 offset:55296
	ds_read_b128 v[196:199], v145 offset:56320
	global_load_lds_dwordx4 v[172:173], off
	v_lshl_add_u64 v[172:173], v[218:219], 0, s[42:43]
	s_mov_b32 m0, s54
	s_nop 0
	global_load_lds_dwordx4 v[172:173], off
	s_barrier
; #define PG8_STAGE(bufoff, gbase, voff) do { _Pragma("unroll") for (int _i = 0; _i < 2; ++_i) \
;         __builtin_amdgcn_global_load_lds((const unsigned*)((const char*)(gbase) + (voff)[_i]), (LAS unsigned*)(lds + (bufoff) + ldsw + _i * 8192), 16, 0, 0); } while (0)
; #define PG8_MMA(ai, bj, At, Bt) do { __builtin_amdgcn_s_setprio(1); _Pragma("unroll") for (int m = 0; m < 4; ++m) _Pragma("unroll") for (int n = 0; n < 2; ++n) _Pragma("unroll") for (int k = 0; k < 2; ++k) \
;         acc[ai][bj][m][n] = __builtin_amdgcn_mfma_f32_16x16x32_bf16(Bt[n][k], At[m][k], acc[ai][bj][m][n], 0, 0, 0); __builtin_amdgcn_s_setprio(0); } while (0)
; #define PG8_WAIT_V(n) asm volatile("s_waitcnt vmcnt(" #n ")" ::: "memory")
; #define PG8_WAIT_L(n) asm volatile("s_waitcnt lgkmcnt(" #n ")" ::: "memory")
; #define PG8_BAR __builtin_amdgcn_s_barrier()
; #define PG8_SCHED __builtin_amdgcn_sched_barrier(0)
; template <class Epi, class Sched>
; __device__ __forceinline__ void gemm_phase(LAS unsigned char* lds, const int tid, const int ldk, const int Kloop, const Sched& S, const Epi& E) {
;     ...
;             PG8_BAR; PG8_WAIT_L(0); PG8_MMA(1, 0, At, B0); PG8_BAR; PG8_SCHED;
;             PG8_STAGE(PG8_SB(1, 1), b3 + hstep, voffB);
;             PG8_WAIT_V(6); PG8_BAR; PG8_MMA(1, 1, At, B1); PG8_BAR;
;         }
	s_waitcnt lgkmcnt(0)
	s_setprio 1
	s_waitcnt lgkmcnt(0)
	v_mfma_f32_16x16x32_bf16 v[66:69], v[146:149], v[162:165], v[66:69]
	v_mfma_f32_16x16x32_bf16 v[62:65], v[154:157], v[162:165], v[62:65]
	v_mfma_f32_16x16x32_bf16 v[58:61], v[146:149], v[176:179], v[58:61]
	v_mfma_f32_16x16x32_bf16 v[54:57], v[154:157], v[176:179], v[54:57]
	v_mfma_f32_16x16x32_bf16 v[42:45], v[146:149], v[184:187], v[42:45]
	v_mfma_f32_16x16x32_bf16 v[38:41], v[154:157], v[184:187], v[38:41]
	v_mfma_f32_16x16x32_bf16 v[26:29], v[146:149], v[192:195], v[26:29]
	v_mfma_f32_16x16x32_bf16 v[22:25], v[154:157], v[192:195], v[22:25]
	v_mfma_f32_16x16x32_bf16 v[66:69], v[150:153], v[166:169], v[66:69]
	v_mfma_f32_16x16x32_bf16 v[62:65], v[158:161], v[166:169], v[62:65]
	v_mfma_f32_16x16x32_bf16 v[58:61], v[150:153], v[180:183], v[58:61]
	v_mfma_f32_16x16x32_bf16 v[54:57], v[158:161], v[180:183], v[54:57]
	v_mfma_f32_16x16x32_bf16 v[42:45], v[150:153], v[188:191], v[42:45]
	v_mfma_f32_16x16x32_bf16 v[38:41], v[158:161], v[188:191], v[38:41]
	v_mfma_f32_16x16x32_bf16 v[26:29], v[150:153], v[196:199], v[26:29]
	v_mfma_f32_16x16x32_bf16 v[22:25], v[158:161], v[196:199], v[22:25]
	s_setprio 0
	s_barrier
	s_add_u32 s14, s14, 0x40080
	s_addc_u32 s15, s15, 0
	s_add_i32 s16, s16, s34
	v_lshl_add_u64 v[146:147], s[14:15], 0, v[4:5]
	s_mov_b32 m0, s16
	s_nop 0
	global_load_lds_dwordx4 v[146:147], off
	v_lshl_add_u64 v[146:147], s[14:15], 0, v[136:137]
	s_add_i32 m0, s16, 0x2000
	s_nop 0
	global_load_lds_dwordx4 v[146:147], off
	s_waitcnt vmcnt(6)
	s_barrier
	s_setprio 1
	v_mfma_f32_16x16x32_bf16 v[50:53], v[200:203], v[162:165], v[50:53]
	v_mfma_f32_16x16x32_bf16 v[46:49], v[222:225], v[162:165], v[46:49]
	v_mfma_f32_16x16x32_bf16 v[34:37], v[200:203], v[176:179], v[34:37]
	v_mfma_f32_16x16x32_bf16 v[30:33], v[222:225], v[176:179], v[30:33]
	v_mfma_f32_16x16x32_bf16 v[18:21], v[200:203], v[184:187], v[18:21]
	v_mfma_f32_16x16x32_bf16 v[14:17], v[222:225], v[184:187], v[14:17]
	v_mfma_f32_16x16x32_bf16 v[10:13], v[200:203], v[192:195], v[10:13]
	v_mfma_f32_16x16x32_bf16 v[6:9], v[222:225], v[192:195], v[6:9]
	v_mfma_f32_16x16x32_bf16 v[50:53], v[204:207], v[166:169], v[50:53]
	v_mfma_f32_16x16x32_bf16 v[46:49], v[226:229], v[166:169], v[46:49]
	v_mfma_f32_16x16x32_bf16 v[34:37], v[204:207], v[180:183], v[34:37]
	v_mfma_f32_16x16x32_bf16 v[30:33], v[226:229], v[180:183], v[30:33]
	v_mfma_f32_16x16x32_bf16 v[18:21], v[204:207], v[188:191], v[18:21]
	v_mfma_f32_16x16x32_bf16 v[14:17], v[226:229], v[188:191], v[14:17]
	v_mfma_f32_16x16x32_bf16 v[10:13], v[204:207], v[196:199], v[10:13]
	v_mfma_f32_16x16x32_bf16 v[6:9], v[226:229], v[196:199], v[6:9]
	s_setprio 0
	s_add_i32 s68, s68, 2
	s_add_u32 s12, s12, 0x100
	s_addc_u32 s13, s13, 0
	s_add_u32 s66, s66, 0x100
	s_addc_u32 s67, s67, 0
	s_cmp_gt_u32 s68, 13
	s_barrier
	s_cbranch_scc0 .LBB0_654
; __device__ __forceinline__ unsigned pk2(float lo, float hi) { const bf2_t r = __builtin_convertvector((f32x2){lo, hi}, bf2_t); unsigned u; __builtin_memcpy(&u, &r, 4); return u; }
; #define PG8_WAIT_V(n) asm volatile("s_waitcnt vmcnt(" #n ")" ::: "memory")
; #define PG8_BAR __builtin_amdgcn_s_barrier()
;     __device__ __forceinline__ void operator()(const f32x4 (&acc)[2][2][4][2], const Unit& u, int wr, int wc, int fr, int fq) const {
;     ...
;         for (int ai = 0; ai < 2; ++ai)
; #pragma unroll
;             for (int m = 0; m < 4; ++m) { bf16_t* rowp = base + (size_t)(ai * HALF + wr * 64 + m * 16 + fr) * u.ldc + wc * 32 + 8 * fq;
; #pragma unroll
;                 for (int bj = 0; bj < 2; ++bj) { const f32x4 v0 = acc[ai][bj][m][0], v1 = acc[ai][bj][m][1];
;                     u32x4 w; w.x = pk2(v0[0], v0[1]); w.y = pk2(v0[2], v0[3]); w.z = pk2(v1[0], v1[1]); w.w = pk2(v1[2], v1[3]);
;                     *(u32x4*)(rowp + bj * HALF) = w; } }
; template <class Epi, class Sched>
; __device__ __forceinline__ void gemm_phase(LAS unsigned char* lds, const int tid, const int ldk, const int Kloop, const Sched& S, const Epi& E) {
;     ...
;         if (!has_next) break;
; #pragma unroll
;         for (int a = 0; a < 2; ++a)
; #pragma unroll
;             for (int b = 0; b < 2; ++b)
; #pragma unroll
;                 for (int m = 0; m < 4; ++m)
; #pragma unroll
;                     for (int n = 0; n < 2; ++n) acc[a][b][m][n] = (f32x4){0.f, 0.f, 0.f, 0.f};
;         cur = nxt; cA = nA; cB = nB; ++ui;
;     }
;     PG8_WAIT_V(0);
;     if (wr == 0) PG8_BAR;
	v_mov_b32_e32 v146, v143
	v_mov_b32_e32 v147, v142
	s_add_u32 s4, s4, s56
	v_lshlrev_b32_e32 v146, 3, v146
	v_add_u32_e32 v150, s46, v147
	s_addc_u32 s5, s5, 0
	v_ashrrev_i32_e32 v147, 31, v146
	v_lshl_add_u64 v[146:147], v[146:147], 1, s[4:5]
	v_mad_i64_i32 v[148:149], s[4:5], v150, s31, 0
	v_cvt_pk_bf16_f32 v114, v114, v115
	v_cvt_pk_bf16_f32 v115, v116, v117
	v_cvt_pk_bf16_f32 v116, v110, v111
	v_add_u32_e32 v110, 16, v150
	v_lshl_add_u64 v[148:149], v[148:149], 1, v[146:147]
	v_cvt_pk_bf16_f32 v117, v112, v113
	v_mad_i64_i32 v[110:111], s[4:5], v110, s31, 0
	v_cvt_pk_bf16_f32 v98, v98, v99
	v_cvt_pk_bf16_f32 v99, v100, v101
	v_cvt_pk_bf16_f32 v100, v94, v95
	v_add_u32_e32 v94, 32, v150
	v_cvt_pk_bf16_f32 v130, v130, v131
	v_cvt_pk_bf16_f32 v131, v132, v133
	v_cvt_pk_bf16_f32 v132, v126, v127
	v_cvt_pk_bf16_f32 v133, v128, v129
	global_store_dwordx4 v[148:149], v[114:117], off offset:256
	v_cvt_pk_bf16_f32 v101, v96, v97
	v_mad_i64_i32 v[94:95], s[4:5], v94, s31, 0
	v_lshl_add_u64 v[114:115], v[110:111], 1, v[146:147]
	v_cvt_pk_bf16_f32 v82, v82, v83
	v_cvt_pk_bf16_f32 v83, v84, v85
	v_cvt_pk_bf16_f32 v84, v78, v79
	v_add_u32_e32 v78, 48, v150
	v_cvt_pk_bf16_f32 v74, v74, v75
	v_cvt_pk_bf16_f32 v75, v76, v77
	v_cvt_pk_bf16_f32 v76, v70, v71
	v_add_u32_e32 v70, 0x80, v150
	global_store_dwordx4 v[148:149], v[130:133], off
	v_cvt_pk_bf16_f32 v110, v122, v123
	v_cvt_pk_bf16_f32 v111, v124, v125
	v_cvt_pk_bf16_f32 v112, v118, v119
	v_cvt_pk_bf16_f32 v113, v120, v121
	global_store_dwordx4 v[114:115], v[98:101], off offset:256
	v_cvt_pk_bf16_f32 v85, v80, v81
	v_mad_i64_i32 v[78:79], s[4:5], v78, s31, 0
	v_lshl_add_u64 v[98:99], v[94:95], 1, v[146:147]
	v_mad_i64_i32 v[70:71], s[4:5], v70, s31, 0
	v_cvt_pk_bf16_f32 v50, v50, v51
	v_cvt_pk_bf16_f32 v51, v52, v53
	v_cvt_pk_bf16_f32 v52, v46, v47
	v_add_u32_e32 v46, 0x90, v150
	global_store_dwordx4 v[114:115], v[110:113], off
	v_cvt_pk_bf16_f32 v94, v106, v107
	v_cvt_pk_bf16_f32 v95, v108, v109
	v_cvt_pk_bf16_f32 v96, v102, v103
	v_cvt_pk_bf16_f32 v97, v104, v105
	global_store_dwordx4 v[98:99], v[82:85], off offset:256
	v_cvt_pk_bf16_f32 v80, v86, v87
	v_cvt_pk_bf16_f32 v81, v88, v89
	v_lshl_add_u64 v[82:83], v[78:79], 1, v[146:147]
	v_cvt_pk_bf16_f32 v78, v90, v91
	v_cvt_pk_bf16_f32 v79, v92, v93
	v_cvt_pk_bf16_f32 v77, v72, v73
	v_lshl_add_u64 v[70:71], v[70:71], 1, v[146:147]
	v_cvt_pk_bf16_f32 v53, v48, v49
	v_mad_i64_i32 v[46:47], s[4:5], v46, s31, 0
	v_cvt_pk_bf16_f32 v34, v34, v35
	v_cvt_pk_bf16_f32 v35, v36, v37
	v_cvt_pk_bf16_f32 v36, v30, v31
	v_add_u32_e32 v30, 0xa0, v150
	global_store_dwordx4 v[98:99], v[94:97], off
	global_store_dwordx4 v[82:83], v[78:81], off
	global_store_dwordx4 v[82:83], v[74:77], off offset:256
	v_cvt_pk_bf16_f32 v66, v66, v67
	v_cvt_pk_bf16_f32 v67, v68, v69
	v_cvt_pk_bf16_f32 v68, v62, v63
	v_cvt_pk_bf16_f32 v69, v64, v65
	global_store_dwordx4 v[70:71], v[50:53], off offset:256
	v_cvt_pk_bf16_f32 v37, v32, v33
	v_mad_i64_i32 v[30:31], s[4:5], v30, s31, 0
	v_lshl_add_u64 v[50:51], v[46:47], 1, v[146:147]
	v_cvt_pk_bf16_f32 v18, v18, v19
	v_cvt_pk_bf16_f32 v19, v20, v21
	v_cvt_pk_bf16_f32 v20, v14, v15
	v_add_u32_e32 v14, 0xb0, v150
	global_store_dwordx4 v[70:71], v[66:69], off
	v_cvt_pk_bf16_f32 v46, v58, v59
	v_cvt_pk_bf16_f32 v47, v60, v61
	v_cvt_pk_bf16_f32 v48, v54, v55
	v_cvt_pk_bf16_f32 v49, v56, v57
	global_store_dwordx4 v[50:51], v[34:37], off offset:256
	v_cvt_pk_bf16_f32 v21, v16, v17
	v_mad_i64_i32 v[14:15], s[4:5], v14, s31, 0
	v_lshl_add_u64 v[34:35], v[30:31], 1, v[146:147]
	global_store_dwordx4 v[50:51], v[46:49], off
	v_cvt_pk_bf16_f32 v30, v42, v43
	v_cvt_pk_bf16_f32 v31, v44, v45
	v_cvt_pk_bf16_f32 v32, v38, v39
	v_cvt_pk_bf16_f32 v33, v40, v41
	global_store_dwordx4 v[34:35], v[18:21], off offset:256
	v_cvt_pk_bf16_f32 v16, v22, v23
	v_cvt_pk_bf16_f32 v17, v24, v25
	v_lshl_add_u64 v[18:19], v[14:15], 1, v[146:147]
	v_cvt_pk_bf16_f32 v14, v26, v27
	v_cvt_pk_bf16_f32 v15, v28, v29
	v_cvt_pk_bf16_f32 v10, v10, v11
	v_cvt_pk_bf16_f32 v11, v12, v13
	v_cvt_pk_bf16_f32 v12, v6, v7
	v_cvt_pk_bf16_f32 v13, v8, v9
	s_and_b64 vcc, exec, s[2:3]
	s_mov_b64 s[4:5], s[10:11]
	s_mov_b32 s31, s57
	s_mov_b64 s[14:15], s[8:9]
	s_mov_b64 s[12:13], s[6:7]
	global_store_dwordx4 v[34:35], v[30:33], off
	global_store_dwordx4 v[18:19], v[14:17], off
	global_store_dwordx4 v[18:19], v[10:13], off offset:256
	s_cbranch_vccz .LBB0_646
	s_cmp_eq_u32 s100, 1
	s_cbranch_scc1 .Lg_inv_done_3
	s_mov_b32 s100, 1
	v_readfirstlane_b32 s98, v217
	s_cmp_lt_u32 s98, 0x1c0
	s_cbranch_scc1 .Lg_inv_done_3
	buffer_inv sc1

; __device__ __forceinline__ void xcd_barrier(const XcdBarrier& b) {
;     asm volatile("s_waitcnt vmcnt(0)" ::: "memory");
;     __syncthreads();
;     int tid0 = threadIdx.x; asm volatile("" : "+v"(tid0));
;     if (tid0 == 0) {
;         unsigned* bar = b.bar;
;         __builtin_amdgcn_s_waitcnt(0);
;         unsigned nloc = b.st[0], nx = b.st[1];
;         if (nloc == 0u) { xcd_barrier_complete(bar, b.x, nloc, nx); b.st[0] = nloc; b.st[1] = nx; }
.Lxb_noinv_9:
	s_mov_b32 s100, 0
	s_cmp_lg_u32 s99, 0
	s_waitcnt vmcnt(0)
	v_mov_b32_e32 v2, v217
	s_waitcnt lgkmcnt(0)
	s_barrier
	s_nop 0
	v_cmp_eq_u32_e32 vcc, 0, v2
	s_and_saveexec_b64 s[2:3], vcc
	s_xor_b64 s[2:3], exec, s[2:3]
	s_cbranch_execz .LBB0_815
	v_readlane_b32 s7, v255, 23
	s_waitcnt vmcnt(0) expcnt(0) lgkmcnt(0)
	s_lshl_b64 s[4:5], s[4:5], 2
	v_mov_b32_e32 v2, s7
	ds_read_b32 v4, v2
	v_readlane_b32 s7, v255, 24
	s_add_u32 s4, s96, s4
	s_addc_u32 s5, s97, s5
	v_mov_b32_e32 v2, s7
	ds_read_b32 v2, v2
	s_waitcnt lgkmcnt(1)
	v_cmp_ne_u32_e32 vcc, 0, v4
	s_and_b32 s24, s6, 15
	s_cbranch_vccnz .LBB0_778
	v_readlane_b32 s6, v255, 0
	v_readlane_b32 s7, v255, 1
	s_load_dwordx2 s[10:11], s[6:7], 0x4
	s_add_u32 s6, s4, 0x1000
	s_addc_u32 s7, s5, 0
	s_add_u32 s8, s4, 0x1100
	s_addc_u32 s9, s5, 0
	s_waitcnt lgkmcnt(0)
	s_mul_i32 s25, s10, s34
	s_add_u32 s10, s4, 0x1200
	s_mul_i32 s25, s25, s11
	s_addc_u32 s11, s5, 0
	s_add_u32 s12, s4, 0x1300
	s_addc_u32 s13, s5, 0
	s_mov_b32 s26, 1
	s_branch .LBB0_766

; __device__ __forceinline__ void xcd_barrier(const XcdBarrier& b) {
;     asm volatile("s_waitcnt vmcnt(0)" ::: "memory");
;     __syncthreads();
;     int tid0 = threadIdx.x; asm volatile("" : "+v"(tid0));
;     if (tid0 == 0) {
;         unsigned* bar = b.bar;
;         __builtin_amdgcn_s_waitcnt(0);
;         unsigned nloc = b.st[0], nx = b.st[1];
;         if (nloc == 0u) { xcd_barrier_complete(bar, b.x, nloc, nx); b.st[0] = nloc; b.st[1] = nx; }
.Lxb_noinv_10:
	s_mov_b32 s100, 0
	s_cmp_lg_u32 s99, 0
	s_waitcnt vmcnt(0)
	v_mov_b32_e32 v2, v217
	s_waitcnt lgkmcnt(0)
	s_barrier
	s_nop 0
	v_cmp_eq_u32_e32 vcc, 0, v2
	s_and_saveexec_b64 s[2:3], vcc
	s_mov_b32 s22, 0x1000000
	s_cbranch_execz .LBB0_989
	v_readlane_b32 s7, v255, 23
	s_waitcnt vmcnt(0) expcnt(0) lgkmcnt(0)
	s_lshl_b64 s[4:5], s[4:5], 2
	v_mov_b32_e32 v2, s7
	ds_read_b32 v4, v2
	v_readlane_b32 s7, v255, 24
	s_add_u32 s4, s96, s4
	s_addc_u32 s5, s97, s5
	v_mov_b32_e32 v2, s7
	ds_read_b32 v2, v2
	s_waitcnt lgkmcnt(1)
	v_cmp_ne_u32_e32 vcc, 0, v4
	s_and_b32 s22, s6, 15
	s_cbranch_vccnz .LBB0_953
	v_readlane_b32 s6, v255, 0
	v_readlane_b32 s7, v255, 1
	s_load_dwordx2 s[10:11], s[6:7], 0x4
	s_add_u32 s6, s4, 0x1000
	s_addc_u32 s7, s5, 0
	s_add_u32 s8, s4, 0x1100
	s_addc_u32 s9, s5, 0
	s_waitcnt lgkmcnt(0)
	s_mul_i32 s23, s10, s34
	s_add_u32 s10, s4, 0x1200
	s_mul_i32 s23, s23, s11
	s_addc_u32 s11, s5, 0
	s_add_u32 s12, s4, 0x1300
	s_addc_u32 s13, s5, 0
	s_mov_b32 s24, 1
	s_branch .LBB0_941

; #define PG8_STAGE(bufoff, gbase, voff) do { _Pragma("unroll") for (int _i = 0; _i < 2; ++_i) \
;         __builtin_amdgcn_global_load_lds((const unsigned*)((const char*)(gbase) + (voff)[_i]), (LAS unsigned*)(lds + (bufoff) + ldsw + _i * 8192), 16, 0, 0); } while (0)
; #define PG8_LDA(dst, b, h) do { _Pragma("unroll") for (int m = 0; m < 4; ++m) _Pragma("unroll") for (int k = 0; k < 2; ++k) dst[m][k] = *(const LAS bf16x8*)(lds + PG8_SA(b, h) + aoff + m * 2048 + k * 1024); } while (0)
; #define PG8_LDB(dst, b, h) do { _Pragma("unroll") for (int n = 0; n < 2; ++n) _Pragma("unroll") for (int k = 0; k < 2; ++k) dst[n][k] = *(const LAS bf16x8*)(lds + PG8_SB(b, h) + boff + n * 2048 + k * 1024); } while (0)
; #define PG8_MMA(ai, bj, At, Bt) do { __builtin_amdgcn_s_setprio(1); _Pragma("unroll") for (int m = 0; m < 4; ++m) _Pragma("unroll") for (int n = 0; n < 2; ++n) _Pragma("unroll") for (int k = 0; k < 2; ++k) \
;         acc[ai][bj][m][n] = __builtin_amdgcn_mfma_f32_16x16x32_bf16(Bt[n][k], At[m][k], acc[ai][bj][m][n], 0, 0, 0); __builtin_amdgcn_s_setprio(0); } while (0)
; #define PG8_WAIT_L(n) asm volatile("s_waitcnt lgkmcnt(" #n ")" ::: "memory")
; #define PG8_BAR __builtin_amdgcn_s_barrier()
; #define PG8_SCHED __builtin_amdgcn_sched_barrier(0)
; template <class Epi, class Sched>
; __device__ __forceinline__ void gemm_phase(LAS unsigned char* lds, const int tid, const int ldk, const int Kloop, const Sched& S, const Epi& E) {
;     ...
;         for (int t = 0; t < nt; t += 2) {
;             const bool last = (t == nt - 2);
;             const char* a1 = cA + (size_t)(t + 1) * kstep;
;             const char* a2 = last ? nA : cA + (size_t)(t + 2) * kstep; const char* b2 = last ? nB : cB + (size_t)(t + 2) * kstep;
;             const char* a3 = a2 + kstep; const char* b3 = b2 + kstep;
;             PG8_LDB(B0, 0, 0); PG8_SCHED; PG8_LDA(At, 0, 0); PG8_STAGE(PG8_SA(1, 1), a1 + hstep, voffA);
;             PG8_WAIT_L(8); PG8_BAR; PG8_WAIT_L(0); PG8_MMA(0, 0, At, B0); PG8_BAR; PG8_SCHED;
;             PG8_LDB(B1, 0, 1); PG8_STAGE(PG8_SB(0, 0), b2, voffB);
;             PG8_BAR; PG8_WAIT_L(0); PG8_MMA(0, 1, At, B1); PG8_BAR;
;             PG8_LDA(At, 0, 1); PG8_STAGE(PG8_SA(0, 0), a2, voffA);
;             PG8_BAR; PG8_WAIT_L(0); PG8_MMA(1, 0, At, B0); PG8_BAR; PG8_SCHED;
.LBB0_996:
	s_add_u32 s14, s12, 0xfff80080
	s_addc_u32 s15, s13, -1
	s_add_i32 s67, 0, 0x10000
	v_add_u32_e32 v158, s67, v144
	ds_read_b128 v[146:149], v158
	ds_read_b128 v[150:153], v158 offset:1024
	ds_read_b128 v[154:157], v158 offset:2048
	ds_read_b128 v[158:161], v158 offset:3072
	s_cmp_eq_u32 s66, 4
	s_cselect_b32 s17, s3, s15
	s_cselect_b32 s16, s2, s14
	s_cselect_b32 s15, s5, s57
	s_cselect_b32 s14, s4, s56
	v_lshl_add_u64 v[172:173], s[12:13], 0, v[138:139]
	s_add_i32 m0, s30, 0xc000
	ds_read_b128 v[162:165], v145
	ds_read_b128 v[166:169], v145 offset:1024
	ds_read_b128 v[176:179], v145 offset:2048
	ds_read_b128 v[180:183], v145 offset:3072
	ds_read_b128 v[184:187], v145 offset:4096
	ds_read_b128 v[188:191], v145 offset:5120
	ds_read_b128 v[192:195], v145 offset:6144
	ds_read_b128 v[196:199], v145 offset:7168
	global_load_lds_dwordx4 v[172:173], off
	v_lshl_add_u64 v[172:173], s[12:13], 0, v[140:141]
	s_add_i32 m0, s30, 0xe000
	s_nop 0
	global_load_lds_dwordx4 v[172:173], off
	s_waitcnt lgkmcnt(8)
	s_barrier
	s_waitcnt lgkmcnt(0)
	s_setprio 1
	s_waitcnt lgkmcnt(0)
	v_mfma_f32_16x16x32_bf16 v[130:133], v[146:149], v[162:165], v[130:133]
	v_mfma_f32_16x16x32_bf16 v[126:129], v[154:157], v[162:165], v[126:129]
	v_mfma_f32_16x16x32_bf16 v[122:125], v[146:149], v[176:179], v[122:125]
	v_mfma_f32_16x16x32_bf16 v[118:121], v[154:157], v[176:179], v[118:121]
	v_mfma_f32_16x16x32_bf16 v[106:109], v[146:149], v[184:187], v[106:109]
	v_mfma_f32_16x16x32_bf16 v[102:105], v[154:157], v[184:187], v[102:105]
	v_mfma_f32_16x16x32_bf16 v[90:93], v[146:149], v[192:195], v[90:93]
	v_mfma_f32_16x16x32_bf16 v[86:89], v[154:157], v[192:195], v[86:89]
	v_mfma_f32_16x16x32_bf16 v[130:133], v[150:153], v[166:169], v[130:133]
	v_mfma_f32_16x16x32_bf16 v[126:129], v[158:161], v[166:169], v[126:129]
	v_mfma_f32_16x16x32_bf16 v[122:125], v[150:153], v[180:183], v[122:125]
	v_mfma_f32_16x16x32_bf16 v[118:121], v[158:161], v[180:183], v[118:121]
	v_mfma_f32_16x16x32_bf16 v[106:109], v[150:153], v[188:191], v[106:109]
	v_mfma_f32_16x16x32_bf16 v[102:105], v[158:161], v[188:191], v[102:105]
	v_mfma_f32_16x16x32_bf16 v[90:93], v[150:153], v[196:199], v[90:93]
	v_mfma_f32_16x16x32_bf16 v[86:89], v[158:161], v[196:199], v[86:89]
	s_setprio 0
	s_barrier
	s_add_i32 s70, 0, 0x14000
	s_add_i32 s67, s67, s27
	v_add_u32_e32 v170, s70, v144
	v_lshl_add_u64 v[172:173], s[14:15], 0, v[4:5]
	s_mov_b32 m0, s67
	ds_read_b128 v[200:203], v170
	ds_read_b128 v[204:207], v170 offset:1024
	ds_read_b128 v[208:211], v170 offset:2048
	ds_read_b128 v[218:221], v170 offset:3072
	global_load_lds_dwordx4 v[172:173], off
	v_lshl_add_u64 v[222:223], s[14:15], 0, v[2:3]
	s_add_i32 m0, s67, 0x2000
	s_nop 0
	global_load_lds_dwordx4 v[222:223], off
	s_barrier
	s_waitcnt lgkmcnt(0)
	s_setprio 1
	s_waitcnt lgkmcnt(0)
	v_mfma_f32_16x16x32_bf16 v[114:117], v[200:203], v[162:165], v[114:117]
	v_mfma_f32_16x16x32_bf16 v[110:113], v[208:211], v[162:165], v[110:113]
	v_mfma_f32_16x16x32_bf16 v[98:101], v[200:203], v[176:179], v[98:101]
	v_mfma_f32_16x16x32_bf16 v[94:97], v[208:211], v[176:179], v[94:97]
	v_mfma_f32_16x16x32_bf16 v[82:85], v[200:203], v[184:187], v[82:85]
	v_mfma_f32_16x16x32_bf16 v[78:81], v[208:211], v[184:187], v[78:81]
	v_mfma_f32_16x16x32_bf16 v[74:77], v[200:203], v[192:195], v[74:77]
	v_mfma_f32_16x16x32_bf16 v[70:73], v[208:211], v[192:195], v[70:73]
	v_mfma_f32_16x16x32_bf16 v[114:117], v[204:207], v[166:169], v[114:117]
	v_mfma_f32_16x16x32_bf16 v[110:113], v[218:221], v[166:169], v[110:113]
	v_mfma_f32_16x16x32_bf16 v[98:101], v[204:207], v[180:183], v[98:101]
	v_mfma_f32_16x16x32_bf16 v[94:97], v[218:221], v[180:183], v[94:97]
	v_mfma_f32_16x16x32_bf16 v[82:85], v[204:207], v[188:191], v[82:85]
	v_mfma_f32_16x16x32_bf16 v[78:81], v[218:221], v[188:191], v[78:81]
	v_mfma_f32_16x16x32_bf16 v[74:77], v[204:207], v[196:199], v[74:77]
	v_mfma_f32_16x16x32_bf16 v[70:73], v[218:221], v[196:199], v[70:73]
	s_setprio 0
	s_mov_b32 m0, s30
	v_lshl_add_u64 v[224:225], s[16:17], 0, v[136:137]
	s_barrier
	ds_read_b128 v[162:165], v145 offset:16384
	ds_read_b128 v[166:169], v145 offset:17408
	ds_read_b128 v[176:179], v145 offset:18432
	ds_read_b128 v[180:183], v145 offset:19456
	ds_read_b128 v[184:187], v145 offset:20480
	ds_read_b128 v[188:191], v145 offset:21504
	ds_read_b128 v[192:195], v145 offset:22528
	ds_read_b128 v[196:199], v145 offset:23552
	global_load_lds_dwordx4 v[224:225], off
	v_lshl_add_u64 v[226:227], s[16:17], 0, v[134:135]
	s_mov_b32 m0, s31
	s_nop 0
	global_load_lds_dwordx4 v[226:227], off
	s_barrier
	s_waitcnt lgkmcnt(0)
	s_setprio 1
	s_waitcnt lgkmcnt(0)
	v_mfma_f32_16x16x32_bf16 v[66:69], v[146:149], v[162:165], v[66:69]
	v_mfma_f32_16x16x32_bf16 v[62:65], v[154:157], v[162:165], v[62:65]
	v_mfma_f32_16x16x32_bf16 v[58:61], v[146:149], v[176:179], v[58:61]
	v_mfma_f32_16x16x32_bf16 v[54:57], v[154:157], v[176:179], v[54:57]
	v_mfma_f32_16x16x32_bf16 v[42:45], v[146:149], v[184:187], v[42:45]
	v_mfma_f32_16x16x32_bf16 v[38:41], v[154:157], v[184:187], v[38:41]
	v_mfma_f32_16x16x32_bf16 v[26:29], v[146:149], v[192:195], v[26:29]
	v_mfma_f32_16x16x32_bf16 v[22:25], v[154:157], v[192:195], v[22:25]
	v_mfma_f32_16x16x32_bf16 v[66:69], v[150:153], v[166:169], v[66:69]
	v_mfma_f32_16x16x32_bf16 v[62:65], v[158:161], v[166:169], v[62:65]
	v_mfma_f32_16x16x32_bf16 v[58:61], v[150:153], v[180:183], v[58:61]
	v_mfma_f32_16x16x32_bf16 v[54:57], v[158:161], v[180:183], v[54:57]
	v_mfma_f32_16x16x32_bf16 v[42:45], v[150:153], v[188:191], v[42:45]
	v_mfma_f32_16x16x32_bf16 v[38:41], v[158:161], v[188:191], v[38:41]
	v_mfma_f32_16x16x32_bf16 v[26:29], v[150:153], v[196:199], v[26:29]
	v_mfma_f32_16x16x32_bf16 v[22:25], v[158:161], v[196:199], v[22:25]
	s_setprio 0
	s_barrier
; #define PG8_STAGE(bufoff, gbase, voff) do { _Pragma("unroll") for (int _i = 0; _i < 2; ++_i) \
;         __builtin_amdgcn_global_load_lds((const unsigned*)((const char*)(gbase) + (voff)[_i]), (LAS unsigned*)(lds + (bufoff) + ldsw + _i * 8192), 16, 0, 0); } while (0)
; #define PG8_LDA(dst, b, h) do { _Pragma("unroll") for (int m = 0; m < 4; ++m) _Pragma("unroll") for (int k = 0; k < 2; ++k) dst[m][k] = *(const LAS bf16x8*)(lds + PG8_SA(b, h) + aoff + m * 2048 + k * 1024); } while (0)
; #define PG8_LDB(dst, b, h) do { _Pragma("unroll") for (int n = 0; n < 2; ++n) _Pragma("unroll") for (int k = 0; k < 2; ++k) dst[n][k] = *(const LAS bf16x8*)(lds + PG8_SB(b, h) + boff + n * 2048 + k * 1024); } while (0)
; #define PG8_MMA(ai, bj, At, Bt) do { __builtin_amdgcn_s_setprio(1); _Pragma("unroll") for (int m = 0; m < 4; ++m) _Pragma("unroll") for (int n = 0; n < 2; ++n) _Pragma("unroll") for (int k = 0; k < 2; ++k) \
;         acc[ai][bj][m][n] = __builtin_amdgcn_mfma_f32_16x16x32_bf16(Bt[n][k], At[m][k], acc[ai][bj][m][n], 0, 0, 0); __builtin_amdgcn_s_setprio(0); } while (0)
; #define PG8_WAIT_V(n) asm volatile("s_waitcnt vmcnt(" #n ")" ::: "memory")
; #define PG8_WAIT_L(n) asm volatile("s_waitcnt lgkmcnt(" #n ")" ::: "memory")
; #define PG8_BAR __builtin_amdgcn_s_barrier()
; #define PG8_SCHED __builtin_amdgcn_sched_barrier(0)
; template <class Epi, class Sched>
; __device__ __forceinline__ void gemm_phase(LAS unsigned char* lds, const int tid, const int ldk, const int Kloop, const Sched& S, const Epi& E) {
;     ...
;             PG8_STAGE(PG8_SB(0, 1), b2 + hstep, voffB);
;             PG8_WAIT_V(6); PG8_BAR; PG8_MMA(1, 1, At, B1); PG8_BAR;
;             PG8_LDB(B0, 1, 0); PG8_SCHED; PG8_LDA(At, 1, 0); PG8_STAGE(PG8_SA(0, 1), a2 + hstep, voffA);
;             PG8_WAIT_L(8); PG8_BAR; PG8_WAIT_L(0); PG8_MMA(0, 0, At, B0); PG8_BAR; PG8_SCHED;
;             PG8_LDB(B1, 1, 1); PG8_STAGE(PG8_SB(1, 0), b3, voffB);
;             PG8_BAR; PG8_WAIT_L(0); PG8_MMA(0, 1, At, B1); PG8_BAR;
;             PG8_LDA(At, 1, 1); PG8_STAGE(PG8_SA(1, 0), a3, voffA);
;             PG8_BAR; PG8_WAIT_L(0); PG8_MMA(1, 0, At, B0); PG8_BAR; PG8_SCHED;
	s_add_u32 s68, s14, 0x80000
	s_addc_u32 s69, s15, 0
	s_add_i32 s67, s70, s27
	v_lshl_add_u64 v[146:147], s[68:69], 0, v[4:5]
	s_mov_b32 m0, s67
	s_nop 0
	global_load_lds_dwordx4 v[146:147], off
	v_lshl_add_u64 v[146:147], s[68:69], 0, v[2:3]
	s_add_i32 m0, s67, 0x2000
	s_nop 0
	global_load_lds_dwordx4 v[146:147], off
	s_waitcnt vmcnt(6)
	s_barrier
	s_setprio 1
	v_mfma_f32_16x16x32_bf16 v[50:53], v[200:203], v[162:165], v[50:53]
	v_mfma_f32_16x16x32_bf16 v[46:49], v[208:211], v[162:165], v[46:49]
	v_mfma_f32_16x16x32_bf16 v[34:37], v[200:203], v[176:179], v[34:37]
	v_mfma_f32_16x16x32_bf16 v[30:33], v[208:211], v[176:179], v[30:33]
	v_mfma_f32_16x16x32_bf16 v[18:21], v[200:203], v[184:187], v[18:21]
	v_mfma_f32_16x16x32_bf16 v[14:17], v[208:211], v[184:187], v[14:17]
	v_mfma_f32_16x16x32_bf16 v[10:13], v[200:203], v[192:195], v[10:13]
	v_mfma_f32_16x16x32_bf16 v[6:9], v[208:211], v[192:195], v[6:9]
	v_mfma_f32_16x16x32_bf16 v[50:53], v[204:207], v[166:169], v[50:53]
	v_mfma_f32_16x16x32_bf16 v[46:49], v[218:221], v[166:169], v[46:49]
	v_mfma_f32_16x16x32_bf16 v[34:37], v[204:207], v[180:183], v[34:37]
	v_mfma_f32_16x16x32_bf16 v[30:33], v[218:221], v[180:183], v[30:33]
	v_mfma_f32_16x16x32_bf16 v[18:21], v[204:207], v[188:191], v[18:21]
	v_mfma_f32_16x16x32_bf16 v[14:17], v[218:221], v[188:191], v[14:17]
	v_mfma_f32_16x16x32_bf16 v[10:13], v[204:207], v[196:199], v[10:13]
	v_mfma_f32_16x16x32_bf16 v[6:9], v[218:221], v[196:199], v[6:9]
	s_setprio 0
	s_add_i32 s67, 0, 0x18000
	v_add_u32_e32 v158, s67, v144
	s_barrier
	ds_read_b128 v[146:149], v158
	ds_read_b128 v[150:153], v158 offset:1024
	ds_read_b128 v[154:157], v158 offset:2048
	ds_read_b128 v[158:161], v158 offset:3072
	s_add_u32 s16, s16, 0x80000
	s_addc_u32 s17, s17, 0
	s_mov_b32 m0, s34
	v_lshl_add_u64 v[200:201], s[16:17], 0, v[136:137]
	ds_read_b128 v[162:165], v145 offset:32768
	ds_read_b128 v[166:169], v145 offset:33792
	ds_read_b128 v[176:179], v145 offset:34816
	ds_read_b128 v[180:183], v145 offset:35840
	ds_read_b128 v[184:187], v145 offset:36864
	ds_read_b128 v[188:191], v145 offset:37888
	ds_read_b128 v[192:195], v145 offset:38912
	ds_read_b128 v[196:199], v145 offset:39936
	global_load_lds_dwordx4 v[200:201], off
	v_lshl_add_u64 v[200:201], s[16:17], 0, v[134:135]
	s_mov_b32 m0, s35
	s_nop 0
	global_load_lds_dwordx4 v[200:201], off
	s_waitcnt lgkmcnt(8)
	s_barrier
	s_waitcnt lgkmcnt(0)
	s_setprio 1
	s_waitcnt lgkmcnt(0)
	v_mfma_f32_16x16x32_bf16 v[130:133], v[146:149], v[162:165], v[130:133]
	v_mfma_f32_16x16x32_bf16 v[126:129], v[154:157], v[162:165], v[126:129]
	v_mfma_f32_16x16x32_bf16 v[122:125], v[146:149], v[176:179], v[122:125]
	v_mfma_f32_16x16x32_bf16 v[118:121], v[154:157], v[176:179], v[118:121]
	v_mfma_f32_16x16x32_bf16 v[106:109], v[146:149], v[184:187], v[106:109]
	v_mfma_f32_16x16x32_bf16 v[102:105], v[154:157], v[184:187], v[102:105]
	v_mfma_f32_16x16x32_bf16 v[90:93], v[146:149], v[192:195], v[90:93]
	v_mfma_f32_16x16x32_bf16 v[86:89], v[154:157], v[192:195], v[86:89]
	v_mfma_f32_16x16x32_bf16 v[130:133], v[150:153], v[166:169], v[130:133]
	v_mfma_f32_16x16x32_bf16 v[126:129], v[158:161], v[166:169], v[126:129]
	v_mfma_f32_16x16x32_bf16 v[122:125], v[150:153], v[180:183], v[122:125]
	v_mfma_f32_16x16x32_bf16 v[118:121], v[158:161], v[180:183], v[118:121]
	v_mfma_f32_16x16x32_bf16 v[106:109], v[150:153], v[188:191], v[106:109]
	v_mfma_f32_16x16x32_bf16 v[102:105], v[158:161], v[188:191], v[102:105]
	v_mfma_f32_16x16x32_bf16 v[90:93], v[150:153], v[196:199], v[90:93]
	v_mfma_f32_16x16x32_bf16 v[86:89], v[158:161], v[196:199], v[86:89]
	s_setprio 0
	s_barrier
	s_add_i32 s16, 0, 0x1c000
	s_add_i32 s17, s67, s27
	v_add_u32_e32 v170, s16, v144
	v_lshl_add_u64 v[172:173], v[172:173], 0, s[42:43]
	s_mov_b32 m0, s17
	ds_read_b128 v[200:203], v170
	ds_read_b128 v[204:207], v170 offset:1024
	ds_read_b128 v[208:211], v170 offset:2048
	ds_read_b128 v[218:221], v170 offset:3072
	global_load_lds_dwordx4 v[172:173], off
	v_lshl_add_u64 v[172:173], v[222:223], 0, s[42:43]
	s_add_i32 m0, s17, 0x2000
	s_nop 0
	global_load_lds_dwordx4 v[172:173], off
	s_barrier
	s_waitcnt lgkmcnt(0)
	s_setprio 1
	s_waitcnt lgkmcnt(0)
	v_mfma_f32_16x16x32_bf16 v[114:117], v[200:203], v[162:165], v[114:117]
	v_mfma_f32_16x16x32_bf16 v[110:113], v[208:211], v[162:165], v[110:113]
	v_mfma_f32_16x16x32_bf16 v[98:101], v[200:203], v[176:179], v[98:101]
	v_mfma_f32_16x16x32_bf16 v[94:97], v[208:211], v[176:179], v[94:97]
	v_mfma_f32_16x16x32_bf16 v[82:85], v[200:203], v[184:187], v[82:85]
	v_mfma_f32_16x16x32_bf16 v[78:81], v[208:211], v[184:187], v[78:81]
	v_mfma_f32_16x16x32_bf16 v[74:77], v[200:203], v[192:195], v[74:77]
	v_mfma_f32_16x16x32_bf16 v[70:73], v[208:211], v[192:195], v[70:73]
	v_mfma_f32_16x16x32_bf16 v[114:117], v[204:207], v[166:169], v[114:117]
	v_mfma_f32_16x16x32_bf16 v[110:113], v[218:221], v[166:169], v[110:113]
	v_mfma_f32_16x16x32_bf16 v[98:101], v[204:207], v[180:183], v[98:101]
	v_mfma_f32_16x16x32_bf16 v[94:97], v[218:221], v[180:183], v[94:97]
	v_mfma_f32_16x16x32_bf16 v[82:85], v[204:207], v[188:191], v[82:85]
	v_mfma_f32_16x16x32_bf16 v[78:81], v[218:221], v[188:191], v[78:81]
	v_mfma_f32_16x16x32_bf16 v[74:77], v[204:207], v[196:199], v[74:77]
	v_mfma_f32_16x16x32_bf16 v[70:73], v[218:221], v[196:199], v[70:73]
	s_setprio 0
	s_mov_b32 m0, s46
	v_lshl_add_u64 v[172:173], v[224:225], 0, s[42:43]
	s_barrier
	ds_read_b128 v[162:165], v145 offset:49152
	ds_read_b128 v[166:169], v145 offset:50176
	ds_read_b128 v[176:179], v145 offset:51200
	ds_read_b128 v[180:183], v145 offset:52224
	ds_read_b128 v[184:187], v145 offset:53248
	ds_read_b128 v[188:191], v145 offset:54272
	ds_read_b128 v[192:195], v145 offset:55296
	ds_read_b128 v[196:199], v145 offset:56320
	global_load_lds_dwordx4 v[172:173], off
	v_lshl_add_u64 v[172:173], v[226:227], 0, s[42:43]
	s_mov_b32 m0, s47
	s_nop 0
	global_load_lds_dwordx4 v[172:173], off
	s_barrier
; #define PG8_STAGE(bufoff, gbase, voff) do { _Pragma("unroll") for (int _i = 0; _i < 2; ++_i) \
;         __builtin_amdgcn_global_load_lds((const unsigned*)((const char*)(gbase) + (voff)[_i]), (LAS unsigned*)(lds + (bufoff) + ldsw + _i * 8192), 16, 0, 0); } while (0)
; #define PG8_MMA(ai, bj, At, Bt) do { __builtin_amdgcn_s_setprio(1); _Pragma("unroll") for (int m = 0; m < 4; ++m) _Pragma("unroll") for (int n = 0; n < 2; ++n) _Pragma("unroll") for (int k = 0; k < 2; ++k) \
;         acc[ai][bj][m][n] = __builtin_amdgcn_mfma_f32_16x16x32_bf16(Bt[n][k], At[m][k], acc[ai][bj][m][n], 0, 0, 0); __builtin_amdgcn_s_setprio(0); } while (0)
; #define PG8_WAIT_V(n) asm volatile("s_waitcnt vmcnt(" #n ")" ::: "memory")
; #define PG8_WAIT_L(n) asm volatile("s_waitcnt lgkmcnt(" #n ")" ::: "memory")
; #define PG8_BAR __builtin_amdgcn_s_barrier()
; #define PG8_SCHED __builtin_amdgcn_sched_barrier(0)
; template <class Epi, class Sched>
; __device__ __forceinline__ void gemm_phase(LAS unsigned char* lds, const int tid, const int ldk, const int Kloop, const Sched& S, const Epi& E) {
;     ...
;             PG8_BAR; PG8_WAIT_L(0); PG8_MMA(1, 0, At, B0); PG8_BAR; PG8_SCHED;
;             PG8_STAGE(PG8_SB(1, 1), b3 + hstep, voffB);
;             PG8_WAIT_V(6); PG8_BAR; PG8_MMA(1, 1, At, B1); PG8_BAR;
;         }
	s_waitcnt lgkmcnt(0)
	s_setprio 1
	s_waitcnt lgkmcnt(0)
	v_mfma_f32_16x16x32_bf16 v[66:69], v[146:149], v[162:165], v[66:69]
	v_mfma_f32_16x16x32_bf16 v[62:65], v[154:157], v[162:165], v[62:65]
	v_mfma_f32_16x16x32_bf16 v[58:61], v[146:149], v[176:179], v[58:61]
	v_mfma_f32_16x16x32_bf16 v[54:57], v[154:157], v[176:179], v[54:57]
	v_mfma_f32_16x16x32_bf16 v[42:45], v[146:149], v[184:187], v[42:45]
	v_mfma_f32_16x16x32_bf16 v[38:41], v[154:157], v[184:187], v[38:41]
	v_mfma_f32_16x16x32_bf16 v[26:29], v[146:149], v[192:195], v[26:29]
	v_mfma_f32_16x16x32_bf16 v[22:25], v[154:157], v[192:195], v[22:25]
	v_mfma_f32_16x16x32_bf16 v[66:69], v[150:153], v[166:169], v[66:69]
	v_mfma_f32_16x16x32_bf16 v[62:65], v[158:161], v[166:169], v[62:65]
	v_mfma_f32_16x16x32_bf16 v[58:61], v[150:153], v[180:183], v[58:61]
	v_mfma_f32_16x16x32_bf16 v[54:57], v[158:161], v[180:183], v[54:57]
	v_mfma_f32_16x16x32_bf16 v[42:45], v[150:153], v[188:191], v[42:45]
	v_mfma_f32_16x16x32_bf16 v[38:41], v[158:161], v[188:191], v[38:41]
	v_mfma_f32_16x16x32_bf16 v[26:29], v[150:153], v[196:199], v[26:29]
	v_mfma_f32_16x16x32_bf16 v[22:25], v[158:161], v[196:199], v[22:25]
	s_setprio 0
	s_barrier
	s_add_u32 s14, s14, 0x80080
	s_addc_u32 s15, s15, 0
	s_add_i32 s16, s16, s27
	v_lshl_add_u64 v[146:147], s[14:15], 0, v[4:5]
	s_mov_b32 m0, s16
	s_nop 0
	global_load_lds_dwordx4 v[146:147], off
	v_lshl_add_u64 v[146:147], s[14:15], 0, v[2:3]
	s_add_i32 m0, s16, 0x2000
	s_nop 0
	global_load_lds_dwordx4 v[146:147], off
	s_waitcnt vmcnt(6)
	s_barrier
	s_setprio 1
	v_mfma_f32_16x16x32_bf16 v[50:53], v[200:203], v[162:165], v[50:53]
	v_mfma_f32_16x16x32_bf16 v[46:49], v[208:211], v[162:165], v[46:49]
	v_mfma_f32_16x16x32_bf16 v[34:37], v[200:203], v[176:179], v[34:37]
	v_mfma_f32_16x16x32_bf16 v[30:33], v[208:211], v[176:179], v[30:33]
	v_mfma_f32_16x16x32_bf16 v[18:21], v[200:203], v[184:187], v[18:21]
	v_mfma_f32_16x16x32_bf16 v[14:17], v[208:211], v[184:187], v[14:17]
	v_mfma_f32_16x16x32_bf16 v[10:13], v[200:203], v[192:195], v[10:13]
	v_mfma_f32_16x16x32_bf16 v[6:9], v[208:211], v[192:195], v[6:9]
	v_mfma_f32_16x16x32_bf16 v[50:53], v[204:207], v[166:169], v[50:53]
	v_mfma_f32_16x16x32_bf16 v[46:49], v[218:221], v[166:169], v[46:49]
	v_mfma_f32_16x16x32_bf16 v[34:37], v[204:207], v[180:183], v[34:37]
	v_mfma_f32_16x16x32_bf16 v[30:33], v[218:221], v[180:183], v[30:33]
	v_mfma_f32_16x16x32_bf16 v[18:21], v[204:207], v[188:191], v[18:21]
	v_mfma_f32_16x16x32_bf16 v[14:17], v[218:221], v[188:191], v[14:17]
	v_mfma_f32_16x16x32_bf16 v[10:13], v[204:207], v[196:199], v[10:13]
	v_mfma_f32_16x16x32_bf16 v[6:9], v[218:221], v[196:199], v[6:9]
	s_setprio 0
	s_add_i32 s66, s66, 2
	s_add_u32 s12, s12, 0x100
	s_addc_u32 s13, s13, 0
	s_add_u32 s56, s56, 0x100
	s_addc_u32 s57, s57, 0
	s_cmp_gt_u32 s66, 5
	s_barrier
	s_cbranch_scc0 .LBB0_996
; __device__ __forceinline__ unsigned pk2(float lo, float hi) { const bf2_t r = __builtin_convertvector((f32x2){lo, hi}, bf2_t); unsigned u; __builtin_memcpy(&u, &r, 4); return u; }
; #define PG8_WAIT_V(n) asm volatile("s_waitcnt vmcnt(" #n ")" ::: "memory")
; #define PG8_BAR __builtin_amdgcn_s_barrier()
;     __device__ __forceinline__ void operator()(const f32x4 (&acc)[2][2][4][2], const Unit& u, int wr, int wc, int fr, int fq) const {
;     ...
;         for (int ai = 0; ai < 2; ++ai)
; #pragma unroll
;             for (int m = 0; m < 4; ++m) { bf16_t* rowp = base + (size_t)(ai * HALF + wr * 64 + m * 16 + fr) * u.ldc + wc * 32 + 8 * fq;
; #pragma unroll
;                 for (int bj = 0; bj < 2; ++bj) { const f32x4 v0 = acc[ai][bj][m][0], v1 = acc[ai][bj][m][1];
;                     u32x4 w; w.x = pk2(v0[0], v0[1]); w.y = pk2(v0[2], v0[3]); w.z = pk2(v1[0], v1[1]); w.w = pk2(v1[2], v1[3]);
;                     *(u32x4*)(rowp + bj * HALF) = w; } }
; template <class Epi, class Sched>
; __device__ __forceinline__ void gemm_phase(LAS unsigned char* lds, const int tid, const int ldk, const int Kloop, const Sched& S, const Epi& E) {
;     ...
;         if (!has_next) break;
; #pragma unroll
;         for (int a = 0; a < 2; ++a)
; #pragma unroll
;             for (int b = 0; b < 2; ++b)
; #pragma unroll
;                 for (int m = 0; m < 4; ++m)
; #pragma unroll
;                     for (int n = 0; n < 2; ++n) acc[a][b][m][n] = (f32x4){0.f, 0.f, 0.f, 0.f};
;         cur = nxt; cA = nA; cB = nB; ++ui;
;     }
;     PG8_WAIT_V(0);
;     if (wr == 0) PG8_BAR;
	v_mov_b32_e32 v147, v143
	v_mov_b32_e32 v146, v142
	s_add_u32 s10, s10, s55
	v_add_u32_e32 v146, s45, v146
	v_lshlrev_b32_e32 v148, 3, v147
	v_cvt_pk_bf16_f32 v74, v74, v75
	v_cvt_pk_bf16_f32 v75, v76, v77
	v_cvt_pk_bf16_f32 v76, v70, v71
	v_add_u32_e32 v70, 0x80, v146
	s_addc_u32 s11, s11, 0
	v_ashrrev_i32_e32 v149, 31, v148
	v_ashrrev_i32_e32 v147, 31, v146
	v_cvt_pk_bf16_f32 v114, v114, v115
	v_cvt_pk_bf16_f32 v115, v116, v117
	v_cvt_pk_bf16_f32 v116, v110, v111
	v_add_u32_e32 v110, 16, v146
	v_ashrrev_i32_e32 v71, 31, v70
	v_cvt_pk_bf16_f32 v50, v50, v51
	v_cvt_pk_bf16_f32 v51, v52, v53
	v_cvt_pk_bf16_f32 v52, v46, v47
	v_add_u32_e32 v46, 0x90, v146
	v_lshl_add_u64 v[148:149], v[148:149], 1, s[10:11]
	v_lshlrev_b64 v[150:151], 11, v[146:147]
	v_ashrrev_i32_e32 v111, 31, v110
	v_cvt_pk_bf16_f32 v98, v98, v99
	v_cvt_pk_bf16_f32 v99, v100, v101
	v_cvt_pk_bf16_f32 v100, v94, v95
	v_add_u32_e32 v94, 32, v146
	v_lshlrev_b64 v[70:71], 11, v[70:71]
	v_ashrrev_i32_e32 v47, 31, v46
	v_cvt_pk_bf16_f32 v34, v34, v35
	v_cvt_pk_bf16_f32 v35, v36, v37
	v_cvt_pk_bf16_f32 v36, v30, v31
	v_add_u32_e32 v30, 0xa0, v146
	v_lshl_add_u64 v[150:151], v[148:149], 0, v[150:151]
	v_cvt_pk_bf16_f32 v117, v112, v113
	v_lshlrev_b64 v[110:111], 11, v[110:111]
	v_ashrrev_i32_e32 v95, 31, v94
	v_cvt_pk_bf16_f32 v82, v82, v83
	v_cvt_pk_bf16_f32 v83, v84, v85
	v_cvt_pk_bf16_f32 v84, v78, v79
	v_add_u32_e32 v78, 48, v146
	v_lshl_add_u64 v[70:71], v[148:149], 0, v[70:71]
	v_cvt_pk_bf16_f32 v53, v48, v49
	v_lshlrev_b64 v[46:47], 11, v[46:47]
	v_ashrrev_i32_e32 v31, 31, v30
	v_cvt_pk_bf16_f32 v18, v18, v19
	v_cvt_pk_bf16_f32 v19, v20, v21
	v_cvt_pk_bf16_f32 v20, v14, v15
	v_add_u32_e32 v14, 0xb0, v146
	global_store_dwordx4 v[150:151], v[114:117], off offset:256
	v_cvt_pk_bf16_f32 v101, v96, v97
	v_lshlrev_b64 v[94:95], 11, v[94:95]
	v_lshl_add_u64 v[114:115], v[148:149], 0, v[110:111]
	v_ashrrev_i32_e32 v79, 31, v78
	global_store_dwordx4 v[70:71], v[50:53], off offset:256
	v_cvt_pk_bf16_f32 v37, v32, v33
	v_lshlrev_b64 v[30:31], 11, v[30:31]
	v_lshl_add_u64 v[50:51], v[148:149], 0, v[46:47]
	v_ashrrev_i32_e32 v15, 31, v14
	global_store_dwordx4 v[114:115], v[98:101], off offset:256
	v_cvt_pk_bf16_f32 v85, v80, v81
	v_lshlrev_b64 v[78:79], 11, v[78:79]
	v_lshl_add_u64 v[98:99], v[148:149], 0, v[94:95]
	global_store_dwordx4 v[50:51], v[34:37], off offset:256
	v_cvt_pk_bf16_f32 v21, v16, v17
	v_lshlrev_b64 v[14:15], 11, v[14:15]
	v_lshl_add_u64 v[34:35], v[148:149], 0, v[30:31]
	v_cvt_pk_bf16_f32 v130, v130, v131
	v_cvt_pk_bf16_f32 v131, v132, v133
	v_cvt_pk_bf16_f32 v132, v126, v127
	v_cvt_pk_bf16_f32 v133, v128, v129
	v_cvt_pk_bf16_f32 v110, v122, v123
	v_cvt_pk_bf16_f32 v111, v124, v125
	v_cvt_pk_bf16_f32 v112, v118, v119
	v_cvt_pk_bf16_f32 v113, v120, v121
	v_cvt_pk_bf16_f32 v94, v106, v107
	v_cvt_pk_bf16_f32 v95, v108, v109
	v_cvt_pk_bf16_f32 v96, v102, v103
	v_cvt_pk_bf16_f32 v97, v104, v105
	global_store_dwordx4 v[98:99], v[82:85], off offset:256
	v_cvt_pk_bf16_f32 v80, v86, v87
	v_cvt_pk_bf16_f32 v81, v88, v89
	v_lshl_add_u64 v[82:83], v[148:149], 0, v[78:79]
	v_cvt_pk_bf16_f32 v78, v90, v91
	v_cvt_pk_bf16_f32 v79, v92, v93
	v_cvt_pk_bf16_f32 v77, v72, v73
	v_cvt_pk_bf16_f32 v66, v66, v67
	v_cvt_pk_bf16_f32 v67, v68, v69
	v_cvt_pk_bf16_f32 v68, v62, v63
	v_cvt_pk_bf16_f32 v69, v64, v65
	v_cvt_pk_bf16_f32 v46, v58, v59
	v_cvt_pk_bf16_f32 v47, v60, v61
	v_cvt_pk_bf16_f32 v48, v54, v55
	v_cvt_pk_bf16_f32 v49, v56, v57
	v_cvt_pk_bf16_f32 v30, v42, v43
	v_cvt_pk_bf16_f32 v31, v44, v45
	v_cvt_pk_bf16_f32 v32, v38, v39
	v_cvt_pk_bf16_f32 v33, v40, v41
	global_store_dwordx4 v[34:35], v[18:21], off offset:256
	v_cvt_pk_bf16_f32 v16, v22, v23
	v_cvt_pk_bf16_f32 v17, v24, v25
	v_lshl_add_u64 v[18:19], v[148:149], 0, v[14:15]
	v_cvt_pk_bf16_f32 v14, v26, v27
	v_cvt_pk_bf16_f32 v15, v28, v29
	v_cvt_pk_bf16_f32 v10, v10, v11
	v_cvt_pk_bf16_f32 v11, v12, v13
	v_cvt_pk_bf16_f32 v12, v6, v7
	v_cvt_pk_bf16_f32 v13, v8, v9
	s_and_b64 vcc, exec, s[6:7]
	s_mov_b64 s[10:11], s[8:9]
	s_mov_b64 s[14:15], s[4:5]
	s_mov_b64 s[12:13], s[2:3]
	global_store_dwordx4 v[150:151], v[130:133], off
	global_store_dwordx4 v[114:115], v[110:113], off
	global_store_dwordx4 v[98:99], v[94:97], off
	global_store_dwordx4 v[82:83], v[78:81], off
	global_store_dwordx4 v[82:83], v[74:77], off offset:256
	global_store_dwordx4 v[70:71], v[66:69], off
	global_store_dwordx4 v[50:51], v[46:49], off
	global_store_dwordx4 v[34:35], v[30:33], off
	global_store_dwordx4 v[18:19], v[14:17], off
	global_store_dwordx4 v[18:19], v[10:13], off offset:256
	s_cbranch_vccz .LBB0_993
	s_cmp_eq_u32 s100, 1
	s_cbranch_scc1 .Lg_inv_done_4
	s_mov_b32 s100, 1
	v_readfirstlane_b32 s98, v217
	s_cmp_lt_u32 s98, 0x1c0
	s_cbranch_scc1 .Lg_inv_done_4
	buffer_inv sc1

; #define PG8_STAGE(bufoff, gbase, voff) do { _Pragma("unroll") for (int _i = 0; _i < 2; ++_i) \
;         __builtin_amdgcn_global_load_lds((const unsigned*)((const char*)(gbase) + (voff)[_i]), (LAS unsigned*)(lds + (bufoff) + ldsw + _i * 8192), 16, 0, 0); } while (0)
; #define PG8_LDA(dst, b, h) do { _Pragma("unroll") for (int m = 0; m < 4; ++m) _Pragma("unroll") for (int k = 0; k < 2; ++k) dst[m][k] = *(const LAS bf16x8*)(lds + PG8_SA(b, h) + aoff + m * 2048 + k * 1024); } while (0)
; #define PG8_LDB(dst, b, h) do { _Pragma("unroll") for (int n = 0; n < 2; ++n) _Pragma("unroll") for (int k = 0; k < 2; ++k) dst[n][k] = *(const LAS bf16x8*)(lds + PG8_SB(b, h) + boff + n * 2048 + k * 1024); } while (0)
; #define PG8_MMA(ai, bj, At, Bt) do { __builtin_amdgcn_s_setprio(1); _Pragma("unroll") for (int m = 0; m < 4; ++m) _Pragma("unroll") for (int n = 0; n < 2; ++n) _Pragma("unroll") for (int k = 0; k < 2; ++k) \
;         acc[ai][bj][m][n] = __builtin_amdgcn_mfma_f32_16x16x32_bf16(Bt[n][k], At[m][k], acc[ai][bj][m][n], 0, 0, 0); __builtin_amdgcn_s_setprio(0); } while (0)
; #define PG8_WAIT_L(n) asm volatile("s_waitcnt lgkmcnt(" #n ")" ::: "memory")
; #define PG8_BAR __builtin_amdgcn_s_barrier()
; #define PG8_SCHED __builtin_amdgcn_sched_barrier(0)
; template <class Epi, class Sched>
; __device__ __forceinline__ void gemm_phase(LAS unsigned char* lds, const int tid, const int ldk, const int Kloop, const Sched& S, const Epi& E) {
;     ...
;         for (int t = 0; t < nt; t += 2) {
;             const bool last = (t == nt - 2);
;             const char* a1 = cA + (size_t)(t + 1) * kstep;
;             const char* a2 = last ? nA : cA + (size_t)(t + 2) * kstep; const char* b2 = last ? nB : cB + (size_t)(t + 2) * kstep;
;             const char* a3 = a2 + kstep; const char* b3 = b2 + kstep;
;             PG8_LDB(B0, 0, 0); PG8_SCHED; PG8_LDA(At, 0, 0); PG8_STAGE(PG8_SA(1, 1), a1 + hstep, voffA);
;             PG8_WAIT_L(8); PG8_BAR; PG8_WAIT_L(0); PG8_MMA(0, 0, At, B0); PG8_BAR; PG8_SCHED;
;             PG8_LDB(B1, 0, 1); PG8_STAGE(PG8_SB(0, 0), b2, voffB);
;             PG8_BAR; PG8_WAIT_L(0); PG8_MMA(0, 1, At, B1); PG8_BAR;
;             PG8_LDA(At, 0, 1); PG8_STAGE(PG8_SA(0, 0), a2, voffA);
;             PG8_BAR; PG8_WAIT_L(0); PG8_MMA(1, 0, At, B0); PG8_BAR; PG8_SCHED;
.LBB0_1009:
	s_add_u32 s14, s12, 0xfffc0080
	s_addc_u32 s15, s13, -1
	s_add_i32 s67, 0, 0x10000
	v_add_u32_e32 v158, s67, v144
	ds_read_b128 v[146:149], v158
	ds_read_b128 v[150:153], v158 offset:1024
	ds_read_b128 v[154:157], v158 offset:2048
	ds_read_b128 v[158:161], v158 offset:3072
	s_cmp_eq_u32 s66, 12
	s_cselect_b32 s17, s5, s15
	s_cselect_b32 s16, s4, s14
	s_cselect_b32 s15, s7, s57
	s_cselect_b32 s14, s6, s56
	v_lshl_add_u64 v[172:173], s[12:13], 0, v[138:139]
	s_add_i32 m0, s30, 0xc000
	ds_read_b128 v[162:165], v145
	ds_read_b128 v[166:169], v145 offset:1024
	ds_read_b128 v[176:179], v145 offset:2048
	ds_read_b128 v[180:183], v145 offset:3072
	ds_read_b128 v[184:187], v145 offset:4096
	ds_read_b128 v[188:191], v145 offset:5120
	ds_read_b128 v[192:195], v145 offset:6144
	ds_read_b128 v[196:199], v145 offset:7168
	global_load_lds_dwordx4 v[172:173], off
	v_lshl_add_u64 v[172:173], s[12:13], 0, v[140:141]
	s_add_i32 m0, s30, 0xe000
	s_nop 0
	global_load_lds_dwordx4 v[172:173], off
	s_waitcnt lgkmcnt(8)
	s_barrier
	s_waitcnt lgkmcnt(0)
	s_setprio 1
	s_waitcnt lgkmcnt(0)
	v_mfma_f32_16x16x32_bf16 v[130:133], v[146:149], v[162:165], v[130:133]
	v_mfma_f32_16x16x32_bf16 v[126:129], v[154:157], v[162:165], v[126:129]
	v_mfma_f32_16x16x32_bf16 v[122:125], v[146:149], v[176:179], v[122:125]
	v_mfma_f32_16x16x32_bf16 v[118:121], v[154:157], v[176:179], v[118:121]
	v_mfma_f32_16x16x32_bf16 v[106:109], v[146:149], v[184:187], v[106:109]
	v_mfma_f32_16x16x32_bf16 v[102:105], v[154:157], v[184:187], v[102:105]
	v_mfma_f32_16x16x32_bf16 v[90:93], v[146:149], v[192:195], v[90:93]
	v_mfma_f32_16x16x32_bf16 v[86:89], v[154:157], v[192:195], v[86:89]
	v_mfma_f32_16x16x32_bf16 v[130:133], v[150:153], v[166:169], v[130:133]
	v_mfma_f32_16x16x32_bf16 v[126:129], v[158:161], v[166:169], v[126:129]
	v_mfma_f32_16x16x32_bf16 v[122:125], v[150:153], v[180:183], v[122:125]
	v_mfma_f32_16x16x32_bf16 v[118:121], v[158:161], v[180:183], v[118:121]
	v_mfma_f32_16x16x32_bf16 v[106:109], v[150:153], v[188:191], v[106:109]
	v_mfma_f32_16x16x32_bf16 v[102:105], v[158:161], v[188:191], v[102:105]
	v_mfma_f32_16x16x32_bf16 v[90:93], v[150:153], v[196:199], v[90:93]
	v_mfma_f32_16x16x32_bf16 v[86:89], v[158:161], v[196:199], v[86:89]
	s_setprio 0
	s_barrier
	s_add_i32 s70, 0, 0x14000
	s_add_i32 s67, s67, s24
	v_add_u32_e32 v170, s70, v144
	v_lshl_add_u64 v[172:173], s[14:15], 0, v[4:5]
	s_mov_b32 m0, s67
	ds_read_b128 v[200:203], v170
	ds_read_b128 v[204:207], v170 offset:1024
	ds_read_b128 v[208:211], v170 offset:2048
	ds_read_b128 v[218:221], v170 offset:3072
	global_load_lds_dwordx4 v[172:173], off
	v_lshl_add_u64 v[222:223], s[14:15], 0, v[2:3]
	s_add_i32 m0, s67, 0x2000
	s_nop 0
	global_load_lds_dwordx4 v[222:223], off
	s_barrier
	s_waitcnt lgkmcnt(0)
	s_setprio 1
	s_waitcnt lgkmcnt(0)
	v_mfma_f32_16x16x32_bf16 v[114:117], v[200:203], v[162:165], v[114:117]
	v_mfma_f32_16x16x32_bf16 v[110:113], v[208:211], v[162:165], v[110:113]
	v_mfma_f32_16x16x32_bf16 v[98:101], v[200:203], v[176:179], v[98:101]
	v_mfma_f32_16x16x32_bf16 v[94:97], v[208:211], v[176:179], v[94:97]
	v_mfma_f32_16x16x32_bf16 v[82:85], v[200:203], v[184:187], v[82:85]
	v_mfma_f32_16x16x32_bf16 v[78:81], v[208:211], v[184:187], v[78:81]
	v_mfma_f32_16x16x32_bf16 v[74:77], v[200:203], v[192:195], v[74:77]
	v_mfma_f32_16x16x32_bf16 v[70:73], v[208:211], v[192:195], v[70:73]
	v_mfma_f32_16x16x32_bf16 v[114:117], v[204:207], v[166:169], v[114:117]
	v_mfma_f32_16x16x32_bf16 v[110:113], v[218:221], v[166:169], v[110:113]
	v_mfma_f32_16x16x32_bf16 v[98:101], v[204:207], v[180:183], v[98:101]
	v_mfma_f32_16x16x32_bf16 v[94:97], v[218:221], v[180:183], v[94:97]
	v_mfma_f32_16x16x32_bf16 v[82:85], v[204:207], v[188:191], v[82:85]
	v_mfma_f32_16x16x32_bf16 v[78:81], v[218:221], v[188:191], v[78:81]
	v_mfma_f32_16x16x32_bf16 v[74:77], v[204:207], v[196:199], v[74:77]
	v_mfma_f32_16x16x32_bf16 v[70:73], v[218:221], v[196:199], v[70:73]
	s_setprio 0
	s_mov_b32 m0, s30
	v_lshl_add_u64 v[224:225], s[16:17], 0, v[136:137]
	s_barrier
	ds_read_b128 v[162:165], v145 offset:16384
	ds_read_b128 v[166:169], v145 offset:17408
	ds_read_b128 v[176:179], v145 offset:18432
	ds_read_b128 v[180:183], v145 offset:19456
	ds_read_b128 v[184:187], v145 offset:20480
	ds_read_b128 v[188:191], v145 offset:21504
	ds_read_b128 v[192:195], v145 offset:22528
	ds_read_b128 v[196:199], v145 offset:23552
	global_load_lds_dwordx4 v[224:225], off
	v_lshl_add_u64 v[226:227], s[16:17], 0, v[134:135]
	s_mov_b32 m0, s31
	s_nop 0
	global_load_lds_dwordx4 v[226:227], off
	s_barrier
	s_waitcnt lgkmcnt(0)
	s_setprio 1
	s_waitcnt lgkmcnt(0)
	v_mfma_f32_16x16x32_bf16 v[66:69], v[146:149], v[162:165], v[66:69]
	v_mfma_f32_16x16x32_bf16 v[62:65], v[154:157], v[162:165], v[62:65]
	v_mfma_f32_16x16x32_bf16 v[58:61], v[146:149], v[176:179], v[58:61]
	v_mfma_f32_16x16x32_bf16 v[54:57], v[154:157], v[176:179], v[54:57]
	v_mfma_f32_16x16x32_bf16 v[42:45], v[146:149], v[184:187], v[42:45]
	v_mfma_f32_16x16x32_bf16 v[38:41], v[154:157], v[184:187], v[38:41]
	v_mfma_f32_16x16x32_bf16 v[26:29], v[146:149], v[192:195], v[26:29]
	v_mfma_f32_16x16x32_bf16 v[22:25], v[154:157], v[192:195], v[22:25]
	v_mfma_f32_16x16x32_bf16 v[66:69], v[150:153], v[166:169], v[66:69]
	v_mfma_f32_16x16x32_bf16 v[62:65], v[158:161], v[166:169], v[62:65]
	v_mfma_f32_16x16x32_bf16 v[58:61], v[150:153], v[180:183], v[58:61]
	v_mfma_f32_16x16x32_bf16 v[54:57], v[158:161], v[180:183], v[54:57]
	v_mfma_f32_16x16x32_bf16 v[42:45], v[150:153], v[188:191], v[42:45]
	v_mfma_f32_16x16x32_bf16 v[38:41], v[158:161], v[188:191], v[38:41]
	v_mfma_f32_16x16x32_bf16 v[26:29], v[150:153], v[196:199], v[26:29]
	v_mfma_f32_16x16x32_bf16 v[22:25], v[158:161], v[196:199], v[22:25]
	s_setprio 0
	s_barrier
; #define PG8_STAGE(bufoff, gbase, voff) do { _Pragma("unroll") for (int _i = 0; _i < 2; ++_i) \
;         __builtin_amdgcn_global_load_lds((const unsigned*)((const char*)(gbase) + (voff)[_i]), (LAS unsigned*)(lds + (bufoff) + ldsw + _i * 8192), 16, 0, 0); } while (0)
; #define PG8_LDA(dst, b, h) do { _Pragma("unroll") for (int m = 0; m < 4; ++m) _Pragma("unroll") for (int k = 0; k < 2; ++k) dst[m][k] = *(const LAS bf16x8*)(lds + PG8_SA(b, h) + aoff + m * 2048 + k * 1024); } while (0)
; #define PG8_LDB(dst, b, h) do { _Pragma("unroll") for (int n = 0; n < 2; ++n) _Pragma("unroll") for (int k = 0; k < 2; ++k) dst[n][k] = *(const LAS bf16x8*)(lds + PG8_SB(b, h) + boff + n * 2048 + k * 1024); } while (0)
; #define PG8_MMA(ai, bj, At, Bt) do { __builtin_amdgcn_s_setprio(1); _Pragma("unroll") for (int m = 0; m < 4; ++m) _Pragma("unroll") for (int n = 0; n < 2; ++n) _Pragma("unroll") for (int k = 0; k < 2; ++k) \
;         acc[ai][bj][m][n] = __builtin_amdgcn_mfma_f32_16x16x32_bf16(Bt[n][k], At[m][k], acc[ai][bj][m][n], 0, 0, 0); __builtin_amdgcn_s_setprio(0); } while (0)
; #define PG8_WAIT_V(n) asm volatile("s_waitcnt vmcnt(" #n ")" ::: "memory")
; #define PG8_WAIT_L(n) asm volatile("s_waitcnt lgkmcnt(" #n ")" ::: "memory")
; #define PG8_BAR __builtin_amdgcn_s_barrier()
; #define PG8_SCHED __builtin_amdgcn_sched_barrier(0)
; template <class Epi, class Sched>
; __device__ __forceinline__ void gemm_phase(LAS unsigned char* lds, const int tid, const int ldk, const int Kloop, const Sched& S, const Epi& E) {
;     ...
;             PG8_STAGE(PG8_SB(0, 1), b2 + hstep, voffB);
;             PG8_WAIT_V(6); PG8_BAR; PG8_MMA(1, 1, At, B1); PG8_BAR;
;             PG8_LDB(B0, 1, 0); PG8_SCHED; PG8_LDA(At, 1, 0); PG8_STAGE(PG8_SA(0, 1), a2 + hstep, voffA);
;             PG8_WAIT_L(8); PG8_BAR; PG8_WAIT_L(0); PG8_MMA(0, 0, At, B0); PG8_BAR; PG8_SCHED;
;             PG8_LDB(B1, 1, 1); PG8_STAGE(PG8_SB(1, 0), b3, voffB);
;             PG8_BAR; PG8_WAIT_L(0); PG8_MMA(0, 1, At, B1); PG8_BAR;
;             PG8_LDA(At, 1, 1); PG8_STAGE(PG8_SA(1, 0), a3, voffA);
;             PG8_BAR; PG8_WAIT_L(0); PG8_MMA(1, 0, At, B0); PG8_BAR; PG8_SCHED;
	s_add_u32 s68, s14, 0x40000
	s_addc_u32 s69, s15, 0
	s_add_i32 s67, s70, s24
	v_lshl_add_u64 v[146:147], s[68:69], 0, v[4:5]
	s_mov_b32 m0, s67
	s_nop 0
	global_load_lds_dwordx4 v[146:147], off
	v_lshl_add_u64 v[146:147], s[68:69], 0, v[2:3]
	s_add_i32 m0, s67, 0x2000
	s_nop 0
	global_load_lds_dwordx4 v[146:147], off
	s_waitcnt vmcnt(6)
	s_barrier
	s_setprio 1
	v_mfma_f32_16x16x32_bf16 v[50:53], v[200:203], v[162:165], v[50:53]
	v_mfma_f32_16x16x32_bf16 v[46:49], v[208:211], v[162:165], v[46:49]
	v_mfma_f32_16x16x32_bf16 v[34:37], v[200:203], v[176:179], v[34:37]
	v_mfma_f32_16x16x32_bf16 v[30:33], v[208:211], v[176:179], v[30:33]
	v_mfma_f32_16x16x32_bf16 v[18:21], v[200:203], v[184:187], v[18:21]
	v_mfma_f32_16x16x32_bf16 v[14:17], v[208:211], v[184:187], v[14:17]
	v_mfma_f32_16x16x32_bf16 v[10:13], v[200:203], v[192:195], v[10:13]
	v_mfma_f32_16x16x32_bf16 v[6:9], v[208:211], v[192:195], v[6:9]
	v_mfma_f32_16x16x32_bf16 v[50:53], v[204:207], v[166:169], v[50:53]
	v_mfma_f32_16x16x32_bf16 v[46:49], v[218:221], v[166:169], v[46:49]
	v_mfma_f32_16x16x32_bf16 v[34:37], v[204:207], v[180:183], v[34:37]
	v_mfma_f32_16x16x32_bf16 v[30:33], v[218:221], v[180:183], v[30:33]
	v_mfma_f32_16x16x32_bf16 v[18:21], v[204:207], v[188:191], v[18:21]
	v_mfma_f32_16x16x32_bf16 v[14:17], v[218:221], v[188:191], v[14:17]
	v_mfma_f32_16x16x32_bf16 v[10:13], v[204:207], v[196:199], v[10:13]
	v_mfma_f32_16x16x32_bf16 v[6:9], v[218:221], v[196:199], v[6:9]
	s_setprio 0
	s_add_i32 s67, 0, 0x18000
	v_add_u32_e32 v158, s67, v144
	s_barrier
	ds_read_b128 v[146:149], v158
	ds_read_b128 v[150:153], v158 offset:1024
	ds_read_b128 v[154:157], v158 offset:2048
	ds_read_b128 v[158:161], v158 offset:3072
	s_add_u32 s16, s16, 0x40000
	s_addc_u32 s17, s17, 0
	s_mov_b32 m0, s34
	v_lshl_add_u64 v[200:201], s[16:17], 0, v[136:137]
	ds_read_b128 v[162:165], v145 offset:32768
	ds_read_b128 v[166:169], v145 offset:33792
	ds_read_b128 v[176:179], v145 offset:34816
	ds_read_b128 v[180:183], v145 offset:35840
	ds_read_b128 v[184:187], v145 offset:36864
	ds_read_b128 v[188:191], v145 offset:37888
	ds_read_b128 v[192:195], v145 offset:38912
	ds_read_b128 v[196:199], v145 offset:39936
	global_load_lds_dwordx4 v[200:201], off
	v_lshl_add_u64 v[200:201], s[16:17], 0, v[134:135]
	s_mov_b32 m0, s35
	s_nop 0
	global_load_lds_dwordx4 v[200:201], off
	s_waitcnt lgkmcnt(8)
	s_barrier
	s_waitcnt lgkmcnt(0)
	s_setprio 1
	s_waitcnt lgkmcnt(0)
	v_mfma_f32_16x16x32_bf16 v[130:133], v[146:149], v[162:165], v[130:133]
	v_mfma_f32_16x16x32_bf16 v[126:129], v[154:157], v[162:165], v[126:129]
	v_mfma_f32_16x16x32_bf16 v[122:125], v[146:149], v[176:179], v[122:125]
	v_mfma_f32_16x16x32_bf16 v[118:121], v[154:157], v[176:179], v[118:121]
	v_mfma_f32_16x16x32_bf16 v[106:109], v[146:149], v[184:187], v[106:109]
	v_mfma_f32_16x16x32_bf16 v[102:105], v[154:157], v[184:187], v[102:105]
	v_mfma_f32_16x16x32_bf16 v[90:93], v[146:149], v[192:195], v[90:93]
	v_mfma_f32_16x16x32_bf16 v[86:89], v[154:157], v[192:195], v[86:89]
	v_mfma_f32_16x16x32_bf16 v[130:133], v[150:153], v[166:169], v[130:133]
	v_mfma_f32_16x16x32_bf16 v[126:129], v[158:161], v[166:169], v[126:129]
	v_mfma_f32_16x16x32_bf16 v[122:125], v[150:153], v[180:183], v[122:125]
	v_mfma_f32_16x16x32_bf16 v[118:121], v[158:161], v[180:183], v[118:121]
	v_mfma_f32_16x16x32_bf16 v[106:109], v[150:153], v[188:191], v[106:109]
	v_mfma_f32_16x16x32_bf16 v[102:105], v[158:161], v[188:191], v[102:105]
	v_mfma_f32_16x16x32_bf16 v[90:93], v[150:153], v[196:199], v[90:93]
	v_mfma_f32_16x16x32_bf16 v[86:89], v[158:161], v[196:199], v[86:89]
	s_setprio 0
	s_barrier
	s_add_i32 s16, 0, 0x1c000
	s_add_i32 s17, s67, s24
	v_add_u32_e32 v170, s16, v144
	v_lshl_add_u64 v[172:173], v[172:173], 0, s[42:43]
	s_mov_b32 m0, s17
	ds_read_b128 v[200:203], v170
	ds_read_b128 v[204:207], v170 offset:1024
	ds_read_b128 v[208:211], v170 offset:2048
	ds_read_b128 v[218:221], v170 offset:3072
	global_load_lds_dwordx4 v[172:173], off
	v_lshl_add_u64 v[172:173], v[222:223], 0, s[42:43]
	s_add_i32 m0, s17, 0x2000
	s_nop 0
	global_load_lds_dwordx4 v[172:173], off
	s_barrier
	s_waitcnt lgkmcnt(0)
	s_setprio 1
	s_waitcnt lgkmcnt(0)
	v_mfma_f32_16x16x32_bf16 v[114:117], v[200:203], v[162:165], v[114:117]
	v_mfma_f32_16x16x32_bf16 v[110:113], v[208:211], v[162:165], v[110:113]
	v_mfma_f32_16x16x32_bf16 v[98:101], v[200:203], v[176:179], v[98:101]
	v_mfma_f32_16x16x32_bf16 v[94:97], v[208:211], v[176:179], v[94:97]
	v_mfma_f32_16x16x32_bf16 v[82:85], v[200:203], v[184:187], v[82:85]
	v_mfma_f32_16x16x32_bf16 v[78:81], v[208:211], v[184:187], v[78:81]
	v_mfma_f32_16x16x32_bf16 v[74:77], v[200:203], v[192:195], v[74:77]
	v_mfma_f32_16x16x32_bf16 v[70:73], v[208:211], v[192:195], v[70:73]
	v_mfma_f32_16x16x32_bf16 v[114:117], v[204:207], v[166:169], v[114:117]
	v_mfma_f32_16x16x32_bf16 v[110:113], v[218:221], v[166:169], v[110:113]
	v_mfma_f32_16x16x32_bf16 v[98:101], v[204:207], v[180:183], v[98:101]
	v_mfma_f32_16x16x32_bf16 v[94:97], v[218:221], v[180:183], v[94:97]
	v_mfma_f32_16x16x32_bf16 v[82:85], v[204:207], v[188:191], v[82:85]
	v_mfma_f32_16x16x32_bf16 v[78:81], v[218:221], v[188:191], v[78:81]
	v_mfma_f32_16x16x32_bf16 v[74:77], v[204:207], v[196:199], v[74:77]
	v_mfma_f32_16x16x32_bf16 v[70:73], v[218:221], v[196:199], v[70:73]
	s_setprio 0
	s_mov_b32 m0, s46
	v_lshl_add_u64 v[172:173], v[224:225], 0, s[42:43]
	s_barrier
	ds_read_b128 v[162:165], v145 offset:49152
	ds_read_b128 v[166:169], v145 offset:50176
	ds_read_b128 v[176:179], v145 offset:51200
	ds_read_b128 v[180:183], v145 offset:52224
	ds_read_b128 v[184:187], v145 offset:53248
	ds_read_b128 v[188:191], v145 offset:54272
	ds_read_b128 v[192:195], v145 offset:55296
	ds_read_b128 v[196:199], v145 offset:56320
	global_load_lds_dwordx4 v[172:173], off
	v_lshl_add_u64 v[172:173], v[226:227], 0, s[42:43]
	s_mov_b32 m0, s47
	s_nop 0
	global_load_lds_dwordx4 v[172:173], off
	s_barrier
; #define PG8_STAGE(bufoff, gbase, voff) do { _Pragma("unroll") for (int _i = 0; _i < 2; ++_i) \
;         __builtin_amdgcn_global_load_lds((const unsigned*)((const char*)(gbase) + (voff)[_i]), (LAS unsigned*)(lds + (bufoff) + ldsw + _i * 8192), 16, 0, 0); } while (0)
; #define PG8_MMA(ai, bj, At, Bt) do { __builtin_amdgcn_s_setprio(1); _Pragma("unroll") for (int m = 0; m < 4; ++m) _Pragma("unroll") for (int n = 0; n < 2; ++n) _Pragma("unroll") for (int k = 0; k < 2; ++k) \
;         acc[ai][bj][m][n] = __builtin_amdgcn_mfma_f32_16x16x32_bf16(Bt[n][k], At[m][k], acc[ai][bj][m][n], 0, 0, 0); __builtin_amdgcn_s_setprio(0); } while (0)
; #define PG8_WAIT_V(n) asm volatile("s_waitcnt vmcnt(" #n ")" ::: "memory")
; #define PG8_WAIT_L(n) asm volatile("s_waitcnt lgkmcnt(" #n ")" ::: "memory")
; #define PG8_BAR __builtin_amdgcn_s_barrier()
; #define PG8_SCHED __builtin_amdgcn_sched_barrier(0)
; template <class Epi, class Sched>
; __device__ __forceinline__ void gemm_phase(LAS unsigned char* lds, const int tid, const int ldk, const int Kloop, const Sched& S, const Epi& E) {
;     ...
;             PG8_BAR; PG8_WAIT_L(0); PG8_MMA(1, 0, At, B0); PG8_BAR; PG8_SCHED;
;             PG8_STAGE(PG8_SB(1, 1), b3 + hstep, voffB);
;             PG8_WAIT_V(6); PG8_BAR; PG8_MMA(1, 1, At, B1); PG8_BAR;
;         }
	s_waitcnt lgkmcnt(0)
	s_setprio 1
	s_waitcnt lgkmcnt(0)
	v_mfma_f32_16x16x32_bf16 v[66:69], v[146:149], v[162:165], v[66:69]
	v_mfma_f32_16x16x32_bf16 v[62:65], v[154:157], v[162:165], v[62:65]
	v_mfma_f32_16x16x32_bf16 v[58:61], v[146:149], v[176:179], v[58:61]
	v_mfma_f32_16x16x32_bf16 v[54:57], v[154:157], v[176:179], v[54:57]
	v_mfma_f32_16x16x32_bf16 v[42:45], v[146:149], v[184:187], v[42:45]
	v_mfma_f32_16x16x32_bf16 v[38:41], v[154:157], v[184:187], v[38:41]
	v_mfma_f32_16x16x32_bf16 v[26:29], v[146:149], v[192:195], v[26:29]
	v_mfma_f32_16x16x32_bf16 v[22:25], v[154:157], v[192:195], v[22:25]
	v_mfma_f32_16x16x32_bf16 v[66:69], v[150:153], v[166:169], v[66:69]
	v_mfma_f32_16x16x32_bf16 v[62:65], v[158:161], v[166:169], v[62:65]
	v_mfma_f32_16x16x32_bf16 v[58:61], v[150:153], v[180:183], v[58:61]
	v_mfma_f32_16x16x32_bf16 v[54:57], v[158:161], v[180:183], v[54:57]
	v_mfma_f32_16x16x32_bf16 v[42:45], v[150:153], v[188:191], v[42:45]
	v_mfma_f32_16x16x32_bf16 v[38:41], v[158:161], v[188:191], v[38:41]
	v_mfma_f32_16x16x32_bf16 v[26:29], v[150:153], v[196:199], v[26:29]
	v_mfma_f32_16x16x32_bf16 v[22:25], v[158:161], v[196:199], v[22:25]
	s_setprio 0
	s_barrier
	s_add_u32 s14, s14, 0x40080
	s_addc_u32 s15, s15, 0
	s_add_i32 s16, s16, s24
	v_lshl_add_u64 v[146:147], s[14:15], 0, v[4:5]
	s_mov_b32 m0, s16
	s_nop 0
	global_load_lds_dwordx4 v[146:147], off
	v_lshl_add_u64 v[146:147], s[14:15], 0, v[2:3]
	s_add_i32 m0, s16, 0x2000
	s_nop 0
	global_load_lds_dwordx4 v[146:147], off
	s_waitcnt vmcnt(6)
	s_barrier
	s_setprio 1
	v_mfma_f32_16x16x32_bf16 v[50:53], v[200:203], v[162:165], v[50:53]
	v_mfma_f32_16x16x32_bf16 v[46:49], v[208:211], v[162:165], v[46:49]
	v_mfma_f32_16x16x32_bf16 v[34:37], v[200:203], v[176:179], v[34:37]
	v_mfma_f32_16x16x32_bf16 v[30:33], v[208:211], v[176:179], v[30:33]
	v_mfma_f32_16x16x32_bf16 v[18:21], v[200:203], v[184:187], v[18:21]
	v_mfma_f32_16x16x32_bf16 v[14:17], v[208:211], v[184:187], v[14:17]
	v_mfma_f32_16x16x32_bf16 v[10:13], v[200:203], v[192:195], v[10:13]
	v_mfma_f32_16x16x32_bf16 v[6:9], v[208:211], v[192:195], v[6:9]
	v_mfma_f32_16x16x32_bf16 v[50:53], v[204:207], v[166:169], v[50:53]
	v_mfma_f32_16x16x32_bf16 v[46:49], v[218:221], v[166:169], v[46:49]
	v_mfma_f32_16x16x32_bf16 v[34:37], v[204:207], v[180:183], v[34:37]
	v_mfma_f32_16x16x32_bf16 v[30:33], v[218:221], v[180:183], v[30:33]
	v_mfma_f32_16x16x32_bf16 v[18:21], v[204:207], v[188:191], v[18:21]
	v_mfma_f32_16x16x32_bf16 v[14:17], v[218:221], v[188:191], v[14:17]
	v_mfma_f32_16x16x32_bf16 v[10:13], v[204:207], v[196:199], v[10:13]
	v_mfma_f32_16x16x32_bf16 v[6:9], v[218:221], v[196:199], v[6:9]
	s_setprio 0
	s_add_i32 s66, s66, 2
	s_add_u32 s12, s12, 0x100
	s_addc_u32 s13, s13, 0
	s_add_u32 s56, s56, 0x100
	s_addc_u32 s57, s57, 0
	s_cmp_gt_u32 s66, 13
	s_barrier
	s_cbranch_scc0 .LBB0_1009
; __device__ __forceinline__ unsigned pk2(float lo, float hi) { const bf2_t r = __builtin_convertvector((f32x2){lo, hi}, bf2_t); unsigned u; __builtin_memcpy(&u, &r, 4); return u; }
; #define PG8_WAIT_V(n) asm volatile("s_waitcnt vmcnt(" #n ")" ::: "memory")
; #define PG8_BAR __builtin_amdgcn_s_barrier()
;     __device__ __forceinline__ void operator()(const f32x4 (&acc)[2][2][4][2], const Unit& u, int wr, int wc, int fr, int fq) const {
;     ...
;         for (int ai = 0; ai < 2; ++ai)
; #pragma unroll
;             for (int m = 0; m < 4; ++m) { bf16_t* rowp = base + (size_t)(ai * HALF + wr * 64 + m * 16 + fr) * u.ldc + wc * 32 + 8 * fq;
; #pragma unroll
;                 for (int bj = 0; bj < 2; ++bj) { const f32x4 v0 = acc[ai][bj][m][0], v1 = acc[ai][bj][m][1];
;                     u32x4 w; w.x = pk2(v0[0], v0[1]); w.y = pk2(v0[2], v0[3]); w.z = pk2(v1[0], v1[1]); w.w = pk2(v1[2], v1[3]);
;                     *(u32x4*)(rowp + bj * HALF) = w; } }
; template <class Epi, class Sched>
; __device__ __forceinline__ void gemm_phase(LAS unsigned char* lds, const int tid, const int ldk, const int Kloop, const Sched& S, const Epi& E) {
;     ...
;         if (!has_next) break;
; #pragma unroll
;         for (int a = 0; a < 2; ++a)
; #pragma unroll
;             for (int b = 0; b < 2; ++b)
; #pragma unroll
;                 for (int m = 0; m < 4; ++m)
; #pragma unroll
;                     for (int n = 0; n < 2; ++n) acc[a][b][m][n] = (f32x4){0.f, 0.f, 0.f, 0.f};
;         cur = nxt; cA = nA; cB = nB; ++ui;
;     }
;     PG8_WAIT_V(0);
;     if (wr == 0) PG8_BAR;
	v_mov_b32_e32 v146, v142
	v_mov_b32_e32 v147, v143
	s_add_u32 s10, s10, s55
	v_add_u32_e32 v146, s45, v146
	v_lshlrev_b32_e32 v148, 3, v147
	v_cvt_pk_bf16_f32 v74, v74, v75
	v_cvt_pk_bf16_f32 v75, v76, v77
	v_cvt_pk_bf16_f32 v76, v70, v71
	v_add_u32_e32 v70, 0x80, v146
	s_addc_u32 s11, s11, 0
	v_ashrrev_i32_e32 v149, 31, v148
	v_ashrrev_i32_e32 v147, 31, v146
	v_cvt_pk_bf16_f32 v114, v114, v115
	v_cvt_pk_bf16_f32 v115, v116, v117
	v_cvt_pk_bf16_f32 v116, v110, v111
	v_add_u32_e32 v110, 16, v146
	v_ashrrev_i32_e32 v71, 31, v70
	v_cvt_pk_bf16_f32 v50, v50, v51
	v_cvt_pk_bf16_f32 v51, v52, v53
	v_cvt_pk_bf16_f32 v52, v46, v47
	v_add_u32_e32 v46, 0x90, v146
	v_lshl_add_u64 v[148:149], v[148:149], 1, s[10:11]
	v_lshlrev_b64 v[150:151], 13, v[146:147]
	v_ashrrev_i32_e32 v111, 31, v110
	v_cvt_pk_bf16_f32 v98, v98, v99
	v_cvt_pk_bf16_f32 v99, v100, v101
	v_cvt_pk_bf16_f32 v100, v94, v95
	v_add_u32_e32 v94, 32, v146
	v_lshlrev_b64 v[70:71], 13, v[70:71]
	v_ashrrev_i32_e32 v47, 31, v46
	v_cvt_pk_bf16_f32 v34, v34, v35
	v_cvt_pk_bf16_f32 v35, v36, v37
	v_cvt_pk_bf16_f32 v36, v30, v31
	v_add_u32_e32 v30, 0xa0, v146
	v_lshl_add_u64 v[150:151], v[148:149], 0, v[150:151]
	v_cvt_pk_bf16_f32 v117, v112, v113
	v_lshlrev_b64 v[110:111], 13, v[110:111]
	v_ashrrev_i32_e32 v95, 31, v94
	v_cvt_pk_bf16_f32 v82, v82, v83
	v_cvt_pk_bf16_f32 v83, v84, v85
	v_cvt_pk_bf16_f32 v84, v78, v79
	v_add_u32_e32 v78, 48, v146
	v_lshl_add_u64 v[70:71], v[148:149], 0, v[70:71]
	v_cvt_pk_bf16_f32 v53, v48, v49
	v_lshlrev_b64 v[46:47], 13, v[46:47]
	v_ashrrev_i32_e32 v31, 31, v30
	v_cvt_pk_bf16_f32 v18, v18, v19
	v_cvt_pk_bf16_f32 v19, v20, v21
	v_cvt_pk_bf16_f32 v20, v14, v15
	v_add_u32_e32 v14, 0xb0, v146
	global_store_dwordx4 v[150:151], v[114:117], off offset:256
	v_cvt_pk_bf16_f32 v101, v96, v97
	v_lshlrev_b64 v[94:95], 13, v[94:95]
	v_lshl_add_u64 v[114:115], v[148:149], 0, v[110:111]
	v_ashrrev_i32_e32 v79, 31, v78
	global_store_dwordx4 v[70:71], v[50:53], off offset:256
	v_cvt_pk_bf16_f32 v37, v32, v33
	v_lshlrev_b64 v[30:31], 13, v[30:31]
	v_lshl_add_u64 v[50:51], v[148:149], 0, v[46:47]
	v_ashrrev_i32_e32 v15, 31, v14
	global_store_dwordx4 v[114:115], v[98:101], off offset:256
	v_cvt_pk_bf16_f32 v85, v80, v81
	v_lshlrev_b64 v[78:79], 13, v[78:79]
	v_lshl_add_u64 v[98:99], v[148:149], 0, v[94:95]
	global_store_dwordx4 v[50:51], v[34:37], off offset:256
	v_cvt_pk_bf16_f32 v21, v16, v17
	v_lshlrev_b64 v[14:15], 13, v[14:15]
	v_lshl_add_u64 v[34:35], v[148:149], 0, v[30:31]
	v_cvt_pk_bf16_f32 v130, v130, v131
	v_cvt_pk_bf16_f32 v131, v132, v133
	v_cvt_pk_bf16_f32 v132, v126, v127
	v_cvt_pk_bf16_f32 v133, v128, v129
	v_cvt_pk_bf16_f32 v110, v122, v123
	v_cvt_pk_bf16_f32 v111, v124, v125
	v_cvt_pk_bf16_f32 v112, v118, v119
	v_cvt_pk_bf16_f32 v113, v120, v121
	v_cvt_pk_bf16_f32 v94, v106, v107
	v_cvt_pk_bf16_f32 v95, v108, v109
	v_cvt_pk_bf16_f32 v96, v102, v103
	v_cvt_pk_bf16_f32 v97, v104, v105
	global_store_dwordx4 v[98:99], v[82:85], off offset:256
	v_cvt_pk_bf16_f32 v80, v86, v87
	v_cvt_pk_bf16_f32 v81, v88, v89
	v_lshl_add_u64 v[82:83], v[148:149], 0, v[78:79]
	v_cvt_pk_bf16_f32 v78, v90, v91
	v_cvt_pk_bf16_f32 v79, v92, v93
	v_cvt_pk_bf16_f32 v77, v72, v73
	v_cvt_pk_bf16_f32 v66, v66, v67
	v_cvt_pk_bf16_f32 v67, v68, v69
	v_cvt_pk_bf16_f32 v68, v62, v63
	v_cvt_pk_bf16_f32 v69, v64, v65
	v_cvt_pk_bf16_f32 v46, v58, v59
	v_cvt_pk_bf16_f32 v47, v60, v61
	v_cvt_pk_bf16_f32 v48, v54, v55
	v_cvt_pk_bf16_f32 v49, v56, v57
	v_cvt_pk_bf16_f32 v30, v42, v43
	v_cvt_pk_bf16_f32 v31, v44, v45
	v_cvt_pk_bf16_f32 v32, v38, v39
	v_cvt_pk_bf16_f32 v33, v40, v41
	global_store_dwordx4 v[34:35], v[18:21], off offset:256
	v_cvt_pk_bf16_f32 v16, v22, v23
	v_cvt_pk_bf16_f32 v17, v24, v25
	v_lshl_add_u64 v[18:19], v[148:149], 0, v[14:15]
	v_cvt_pk_bf16_f32 v14, v26, v27
	v_cvt_pk_bf16_f32 v15, v28, v29
	v_cvt_pk_bf16_f32 v10, v10, v11
	v_cvt_pk_bf16_f32 v11, v12, v13
	v_cvt_pk_bf16_f32 v12, v6, v7
	v_cvt_pk_bf16_f32 v13, v8, v9
	s_and_b64 vcc, exec, s[2:3]
	s_mov_b64 s[10:11], s[8:9]
	s_mov_b64 s[14:15], s[6:7]
	s_mov_b64 s[12:13], s[4:5]
	global_store_dwordx4 v[150:151], v[130:133], off
	global_store_dwordx4 v[114:115], v[110:113], off
	global_store_dwordx4 v[98:99], v[94:97], off
	global_store_dwordx4 v[82:83], v[78:81], off
	global_store_dwordx4 v[82:83], v[74:77], off offset:256
	global_store_dwordx4 v[70:71], v[66:69], off
	global_store_dwordx4 v[50:51], v[46:49], off
	global_store_dwordx4 v[34:35], v[30:33], off
	global_store_dwordx4 v[18:19], v[14:17], off
	global_store_dwordx4 v[18:19], v[10:13], off offset:256
	s_cbranch_vccz .LBB0_1006
	s_cmp_eq_u32 s100, 1
	s_cbranch_scc1 .Lg_inv_done_5
	s_mov_b32 s100, 1
	v_readfirstlane_b32 s98, v217
	s_cmp_lt_u32 s98, 0x1c0
	s_cbranch_scc1 .Lg_inv_done_5
	buffer_inv sc1

; __device__ __forceinline__ void xcd_barrier(const XcdBarrier& b) {
;     asm volatile("s_waitcnt vmcnt(0)" ::: "memory");
;     __syncthreads();
;     int tid0 = threadIdx.x; asm volatile("" : "+v"(tid0));
;     if (tid0 == 0) {
;         unsigned* bar = b.bar;
;         __builtin_amdgcn_s_waitcnt(0);
;         unsigned nloc = b.st[0], nx = b.st[1];
;         if (nloc == 0u) { xcd_barrier_complete(bar, b.x, nloc, nx); b.st[0] = nloc; b.st[1] = nx; }
.Lxb_noinv_11:
	s_mov_b32 s100, 0
	s_cmp_lg_u32 s99, 0
	s_waitcnt vmcnt(0)
	v_mov_b32_e32 v2, v217
	s_waitcnt vmcnt(0) lgkmcnt(0)
	s_barrier
	s_nop 0
	v_cmp_eq_u32_e32 vcc, 0, v2
	s_and_saveexec_b64 s[2:3], vcc
	s_cbranch_execz .LBB0_1066
	v_readlane_b32 s7, v255, 23
	s_waitcnt vmcnt(0) expcnt(0) lgkmcnt(0)
	s_lshl_b64 s[4:5], s[4:5], 2
	v_mov_b32_e32 v2, s7
	ds_read_b32 v4, v2
	v_readlane_b32 s7, v255, 24
	s_add_u32 s4, s96, s4
	s_addc_u32 s5, s97, s5
	v_mov_b32_e32 v2, s7
	ds_read_b32 v2, v2
	s_waitcnt lgkmcnt(1)
	v_cmp_ne_u32_e32 vcc, 0, v4
	s_and_b32 s22, s6, 15
	s_cbranch_vccnz .LBB0_1030
	v_readlane_b32 s6, v255, 0
	v_readlane_b32 s7, v255, 1
	s_load_dwordx2 s[10:11], s[6:7], 0x4
	s_add_u32 s6, s4, 0x1000
	s_addc_u32 s7, s5, 0
	s_add_u32 s8, s4, 0x1100
	s_addc_u32 s9, s5, 0
	s_waitcnt lgkmcnt(0)
	s_mul_i32 s23, s10, s34
	s_add_u32 s10, s4, 0x1200
	s_mul_i32 s23, s23, s11
	s_addc_u32 s11, s5, 0
	s_add_u32 s12, s4, 0x1300
	s_addc_u32 s13, s5, 0
	s_mov_b32 s24, 1
	s_branch .LBB0_1018
